# MFMA order inside each 32-MFMA block changed to k-major across both column groups (g0.k0, g1.k0, g0.k1, g1.k1): same-accumulator distance 16, operand quads reused within 16-MFMA windows
# speedup vs baseline: 1.0022x; 1.0022x over previous
.LBB0_197:
	ds_read_b128 v[146:149], v161
	ds_read_b128 v[150:153], v161 offset:1024
	ds_read_b128 v[154:157], v161 offset:2048
	ds_read_b128 v[166:169], v161 offset:3072
	ds_read_b128 v[170:173], v162
	ds_read_b128 v[174:177], v162 offset:1024
	ds_read_b128 v[178:181], v162 offset:2048
	ds_read_b128 v[182:185], v162 offset:3072
	s_add_u32 s38, s36, 0xfffc0080
	s_addc_u32 s39, s37, -1
	s_cmp_eq_u32 s62, 12
	s_cselect_b32 s41, s17, s39
	s_cselect_b32 s40, s23, s38
	s_cselect_b32 s39, s15, s61
	s_cselect_b32 s38, s59, s60
	v_lshl_add_u64 v[218:219], s[36:37], 0, v[138:139]
	s_add_i32 m0, s45, 0xc000
	ds_read_b128 v[186:189], v163
	ds_read_b128 v[190:193], v163 offset:1024
	ds_read_b128 v[194:197], v163 offset:2048
	ds_read_b128 v[198:201], v163 offset:3072
	ds_read_b128 v[202:205], v163 offset:4096
	ds_read_b128 v[206:209], v163 offset:5120
	ds_read_b128 v[210:213], v163 offset:6144
	ds_read_b128 v[214:217], v163 offset:7168
	global_load_lds_dwordx4 v[218:219], off
	v_lshl_add_u64 v[218:219], s[36:37], 0, v[140:141]
	s_add_i32 m0, s45, 0xe000
	s_nop 0
	global_load_lds_dwordx4 v[218:219], off
	s_waitcnt vmcnt(8)
	s_waitcnt lgkmcnt(0)
	s_setprio 1
	s_barrier
	v_mfma_f32_16x16x32_bf16 v[124:127], v[146:149], v[186:189], v[124:127]
	v_mfma_f32_16x16x32_bf16 v[120:123], v[154:157], v[186:189], v[120:123]
	v_mfma_f32_16x16x32_bf16 v[116:119], v[146:149], v[194:197], v[116:119]
	v_mfma_f32_16x16x32_bf16 v[112:115], v[154:157], v[194:197], v[112:115]
	v_mfma_f32_16x16x32_bf16 v[92:95], v[146:149], v[202:205], v[92:95]
	v_mfma_f32_16x16x32_bf16 v[88:91], v[154:157], v[202:205], v[88:91]
	v_mfma_f32_16x16x32_bf16 v[76:79], v[146:149], v[210:213], v[76:79]
	v_mfma_f32_16x16x32_bf16 v[72:75], v[154:157], v[210:213], v[72:75]
	v_mfma_f32_16x16x32_bf16 v[108:111], v[170:173], v[186:189], v[108:111]
	v_mfma_f32_16x16x32_bf16 v[104:107], v[178:181], v[186:189], v[104:107]
	v_mfma_f32_16x16x32_bf16 v[100:103], v[170:173], v[194:197], v[100:103]
	v_mfma_f32_16x16x32_bf16 v[96:99], v[178:181], v[194:197], v[96:99]
	v_mfma_f32_16x16x32_bf16 v[84:87], v[170:173], v[202:205], v[84:87]
	v_mfma_f32_16x16x32_bf16 v[80:83], v[178:181], v[202:205], v[80:83]
	v_mfma_f32_16x16x32_bf16 v[68:71], v[170:173], v[210:213], v[68:71]
	v_mfma_f32_16x16x32_bf16 v[64:67], v[178:181], v[210:213], v[64:67]
	v_mfma_f32_16x16x32_bf16 v[124:127], v[150:153], v[190:193], v[124:127]
	v_mfma_f32_16x16x32_bf16 v[120:123], v[166:169], v[190:193], v[120:123]
	v_mfma_f32_16x16x32_bf16 v[116:119], v[150:153], v[198:201], v[116:119]
	v_mfma_f32_16x16x32_bf16 v[112:115], v[166:169], v[198:201], v[112:115]
	v_mfma_f32_16x16x32_bf16 v[92:95], v[150:153], v[206:209], v[92:95]
	v_mfma_f32_16x16x32_bf16 v[88:91], v[166:169], v[206:209], v[88:91]
	v_mfma_f32_16x16x32_bf16 v[76:79], v[150:153], v[214:217], v[76:79]
	v_mfma_f32_16x16x32_bf16 v[72:75], v[166:169], v[214:217], v[72:75]
	v_mfma_f32_16x16x32_bf16 v[108:111], v[174:177], v[190:193], v[108:111]
	v_mfma_f32_16x16x32_bf16 v[104:107], v[182:185], v[190:193], v[104:107]
	v_mfma_f32_16x16x32_bf16 v[100:103], v[174:177], v[198:201], v[100:103]
	v_mfma_f32_16x16x32_bf16 v[96:99], v[182:185], v[198:201], v[96:99]
	v_mfma_f32_16x16x32_bf16 v[84:87], v[174:177], v[206:209], v[84:87]
	v_mfma_f32_16x16x32_bf16 v[80:83], v[182:185], v[206:209], v[80:83]
	v_mfma_f32_16x16x32_bf16 v[68:71], v[174:177], v[214:217], v[68:71]
	v_mfma_f32_16x16x32_bf16 v[64:67], v[182:185], v[214:217], v[64:67]
	s_barrier
	s_setprio 0
	s_add_i32 s63, s56, s44
	v_lshl_add_u64 v[218:219], s[38:39], 0, v[130:131]
	s_mov_b32 m0, s63
	ds_read_b128 v[186:189], v163 offset:16384
	ds_read_b128 v[190:193], v163 offset:17408
	ds_read_b128 v[194:197], v163 offset:18432
	ds_read_b128 v[198:201], v163 offset:19456
	ds_read_b128 v[202:205], v163 offset:20480
	ds_read_b128 v[206:209], v163 offset:21504
	ds_read_b128 v[210:213], v163 offset:22528
	ds_read_b128 v[214:217], v163 offset:23552
	global_load_lds_dwordx4 v[218:219], off
	s_add_i32 m0, s63, 0x2000
	s_add_u32 s64, s38, 0x40000
	v_lshl_add_u64 v[220:221], s[38:39], 0, v[134:135]
	s_addc_u32 s65, s39, 0
	s_add_i32 s63, s57, s44
	global_load_lds_dwordx4 v[220:221], off
	v_lshl_add_u64 v[222:223], s[64:65], 0, v[130:131]
	s_mov_b32 m0, s63
	v_lshl_add_u64 v[224:225], s[40:41], 0, v[132:133]
	global_load_lds_dwordx4 v[222:223], off
	v_lshl_add_u64 v[222:223], s[64:65], 0, v[134:135]
	s_add_i32 m0, s63, 0x2000
	s_nop 0
	global_load_lds_dwordx4 v[222:223], off
	v_lshl_add_u64 v[222:223], s[40:41], 0, v[128:129]
	s_mov_b32 m0, s45
	s_nop 0
	global_load_lds_dwordx4 v[222:223], off
	s_mov_b32 m0, s46
	s_nop 0
	global_load_lds_dwordx4 v[224:225], off
	s_waitcnt vmcnt(8)
	s_waitcnt lgkmcnt(0)
	s_setprio 1
	s_barrier
	v_mfma_f32_16x16x32_bf16 v[60:63], v[146:149], v[186:189], v[60:63]
	v_mfma_f32_16x16x32_bf16 v[56:59], v[154:157], v[186:189], v[56:59]
	v_mfma_f32_16x16x32_bf16 v[44:47], v[146:149], v[194:197], v[44:47]
	v_mfma_f32_16x16x32_bf16 v[40:43], v[154:157], v[194:197], v[40:43]
	v_mfma_f32_16x16x32_bf16 v[28:31], v[146:149], v[202:205], v[28:31]
	v_mfma_f32_16x16x32_bf16 v[24:27], v[154:157], v[202:205], v[24:27]
	v_mfma_f32_16x16x32_bf16 v[12:15], v[146:149], v[210:213], v[12:15]
	v_mfma_f32_16x16x32_bf16 v[8:11], v[154:157], v[210:213], v[8:11]
	v_mfma_f32_16x16x32_bf16 v[52:55], v[170:173], v[186:189], v[52:55]
	v_mfma_f32_16x16x32_bf16 v[48:51], v[178:181], v[186:189], v[48:51]
	v_mfma_f32_16x16x32_bf16 v[36:39], v[170:173], v[194:197], v[36:39]
	v_mfma_f32_16x16x32_bf16 v[32:35], v[178:181], v[194:197], v[32:35]
	v_mfma_f32_16x16x32_bf16 v[20:23], v[170:173], v[202:205], v[20:23]
	v_mfma_f32_16x16x32_bf16 v[16:19], v[178:181], v[202:205], v[16:19]
	v_mfma_f32_16x16x32_bf16 v[4:7], v[170:173], v[210:213], v[4:7]
	v_mfma_f32_16x16x32_bf16 v[0:3], v[178:181], v[210:213], v[0:3]
	v_mfma_f32_16x16x32_bf16 v[60:63], v[150:153], v[190:193], v[60:63]
	v_mfma_f32_16x16x32_bf16 v[56:59], v[166:169], v[190:193], v[56:59]
	v_mfma_f32_16x16x32_bf16 v[44:47], v[150:153], v[198:201], v[44:47]
	v_mfma_f32_16x16x32_bf16 v[40:43], v[166:169], v[198:201], v[40:43]
	v_mfma_f32_16x16x32_bf16 v[28:31], v[150:153], v[206:209], v[28:31]
	v_mfma_f32_16x16x32_bf16 v[24:27], v[166:169], v[206:209], v[24:27]
	v_mfma_f32_16x16x32_bf16 v[12:15], v[150:153], v[214:217], v[12:15]
	v_mfma_f32_16x16x32_bf16 v[8:11], v[166:169], v[214:217], v[8:11]
	v_mfma_f32_16x16x32_bf16 v[52:55], v[174:177], v[190:193], v[52:55]
	v_mfma_f32_16x16x32_bf16 v[48:51], v[182:185], v[190:193], v[48:51]
	v_mfma_f32_16x16x32_bf16 v[36:39], v[174:177], v[198:201], v[36:39]
	v_mfma_f32_16x16x32_bf16 v[32:35], v[182:185], v[198:201], v[32:35]
	v_mfma_f32_16x16x32_bf16 v[20:23], v[174:177], v[206:209], v[20:23]
	v_mfma_f32_16x16x32_bf16 v[16:19], v[182:185], v[206:209], v[16:19]
	v_mfma_f32_16x16x32_bf16 v[4:7], v[174:177], v[214:217], v[4:7]
	v_mfma_f32_16x16x32_bf16 v[0:3], v[182:185], v[214:217], v[0:3]
	s_barrier
	s_setprio 0
	s_add_i32 s63, 0, 0x18000
	v_add_u32_e32 v136, s63, v160
	s_add_i32 s64, 0, 0x1c000
	ds_read_b128 v[146:149], v136
	ds_read_b128 v[150:153], v136 offset:1024
	ds_read_b128 v[154:157], v136 offset:2048
	ds_read_b128 v[166:169], v136 offset:3072
	v_add_u32_e32 v136, s64, v160
	ds_read_b128 v[170:173], v136
	ds_read_b128 v[174:177], v136 offset:1024
	ds_read_b128 v[178:181], v136 offset:2048
	ds_read_b128 v[182:185], v136 offset:3072
	s_add_u32 s40, s40, 0x40000
	s_addc_u32 s41, s41, 0
	s_mov_b32 m0, s47
	v_lshl_add_u64 v[226:227], s[40:41], 0, v[128:129]
	ds_read_b128 v[186:189], v163 offset:32768
	ds_read_b128 v[190:193], v163 offset:33792
	ds_read_b128 v[194:197], v163 offset:34816
	ds_read_b128 v[198:201], v163 offset:35840
	ds_read_b128 v[202:205], v163 offset:36864
	ds_read_b128 v[206:209], v163 offset:37888
	ds_read_b128 v[210:213], v163 offset:38912
	ds_read_b128 v[214:217], v163 offset:39936
	global_load_lds_dwordx4 v[226:227], off
	v_lshl_add_u64 v[226:227], s[40:41], 0, v[132:133]
	s_mov_b32 m0, s48
	s_nop 0
	global_load_lds_dwordx4 v[226:227], off
	s_waitcnt vmcnt(8)
	s_waitcnt lgkmcnt(0)
	s_setprio 1
	s_barrier
	v_mfma_f32_16x16x32_bf16 v[124:127], v[146:149], v[186:189], v[124:127]
	v_mfma_f32_16x16x32_bf16 v[120:123], v[154:157], v[186:189], v[120:123]
	v_mfma_f32_16x16x32_bf16 v[116:119], v[146:149], v[194:197], v[116:119]
	v_mfma_f32_16x16x32_bf16 v[112:115], v[154:157], v[194:197], v[112:115]
	v_mfma_f32_16x16x32_bf16 v[92:95], v[146:149], v[202:205], v[92:95]
	v_mfma_f32_16x16x32_bf16 v[88:91], v[154:157], v[202:205], v[88:91]
	v_mfma_f32_16x16x32_bf16 v[76:79], v[146:149], v[210:213], v[76:79]
	v_mfma_f32_16x16x32_bf16 v[72:75], v[154:157], v[210:213], v[72:75]
	v_mfma_f32_16x16x32_bf16 v[108:111], v[170:173], v[186:189], v[108:111]
	v_mfma_f32_16x16x32_bf16 v[104:107], v[178:181], v[186:189], v[104:107]
	v_mfma_f32_16x16x32_bf16 v[100:103], v[170:173], v[194:197], v[100:103]
	v_mfma_f32_16x16x32_bf16 v[96:99], v[178:181], v[194:197], v[96:99]
	v_mfma_f32_16x16x32_bf16 v[84:87], v[170:173], v[202:205], v[84:87]
	v_mfma_f32_16x16x32_bf16 v[80:83], v[178:181], v[202:205], v[80:83]
	v_mfma_f32_16x16x32_bf16 v[68:71], v[170:173], v[210:213], v[68:71]
	v_mfma_f32_16x16x32_bf16 v[64:67], v[178:181], v[210:213], v[64:67]
	v_mfma_f32_16x16x32_bf16 v[124:127], v[150:153], v[190:193], v[124:127]
	v_mfma_f32_16x16x32_bf16 v[120:123], v[166:169], v[190:193], v[120:123]
	v_mfma_f32_16x16x32_bf16 v[116:119], v[150:153], v[198:201], v[116:119]
	v_mfma_f32_16x16x32_bf16 v[112:115], v[166:169], v[198:201], v[112:115]
	v_mfma_f32_16x16x32_bf16 v[92:95], v[150:153], v[206:209], v[92:95]
	v_mfma_f32_16x16x32_bf16 v[88:91], v[166:169], v[206:209], v[88:91]
	v_mfma_f32_16x16x32_bf16 v[76:79], v[150:153], v[214:217], v[76:79]
	v_mfma_f32_16x16x32_bf16 v[72:75], v[166:169], v[214:217], v[72:75]
	v_mfma_f32_16x16x32_bf16 v[108:111], v[174:177], v[190:193], v[108:111]
	v_mfma_f32_16x16x32_bf16 v[104:107], v[182:185], v[190:193], v[104:107]
	v_mfma_f32_16x16x32_bf16 v[100:103], v[174:177], v[198:201], v[100:103]
	v_mfma_f32_16x16x32_bf16 v[96:99], v[182:185], v[198:201], v[96:99]
	v_mfma_f32_16x16x32_bf16 v[84:87], v[174:177], v[206:209], v[84:87]
	v_mfma_f32_16x16x32_bf16 v[80:83], v[182:185], v[206:209], v[80:83]
	v_mfma_f32_16x16x32_bf16 v[68:71], v[174:177], v[214:217], v[68:71]
	v_mfma_f32_16x16x32_bf16 v[64:67], v[182:185], v[214:217], v[64:67]
	s_barrier
	s_setprio 0
	s_add_i32 s40, s63, s44
	v_lshl_add_u64 v[218:219], v[218:219], 0, s[8:9]
	s_mov_b32 m0, s40
	ds_read_b128 v[186:189], v163 offset:49152
	ds_read_b128 v[190:193], v163 offset:50176
	ds_read_b128 v[194:197], v163 offset:51200
	ds_read_b128 v[198:201], v163 offset:52224
	ds_read_b128 v[202:205], v163 offset:53248
	ds_read_b128 v[206:209], v163 offset:54272
	ds_read_b128 v[210:213], v163 offset:55296
	ds_read_b128 v[214:217], v163 offset:56320
	global_load_lds_dwordx4 v[218:219], off
	s_add_i32 m0, s40, 0x2000
	s_add_u32 s38, s38, 0x40080
	v_lshl_add_u64 v[218:219], v[220:221], 0, s[8:9]
	s_addc_u32 s39, s39, 0
	s_add_i32 s40, s64, s44
	global_load_lds_dwordx4 v[218:219], off
	v_lshl_add_u64 v[218:219], s[38:39], 0, v[130:131]
	s_mov_b32 m0, s40
	s_nop 0
	global_load_lds_dwordx4 v[218:219], off
	v_lshl_add_u64 v[218:219], s[38:39], 0, v[134:135]
	s_add_i32 m0, s40, 0x2000
	s_nop 0
	global_load_lds_dwordx4 v[218:219], off
	v_lshl_add_u64 v[218:219], v[222:223], 0, s[8:9]
	s_mov_b32 m0, s54
	s_nop 0
	global_load_lds_dwordx4 v[218:219], off
	v_lshl_add_u64 v[218:219], v[224:225], 0, s[8:9]
	s_mov_b32 m0, s55
	s_nop 0
	global_load_lds_dwordx4 v[218:219], off
	s_waitcnt vmcnt(8)
	s_waitcnt lgkmcnt(0)
	s_setprio 1
	s_barrier
	v_mfma_f32_16x16x32_bf16 v[60:63], v[146:149], v[186:189], v[60:63]
	v_mfma_f32_16x16x32_bf16 v[56:59], v[154:157], v[186:189], v[56:59]
	v_mfma_f32_16x16x32_bf16 v[44:47], v[146:149], v[194:197], v[44:47]
	v_mfma_f32_16x16x32_bf16 v[40:43], v[154:157], v[194:197], v[40:43]
	v_mfma_f32_16x16x32_bf16 v[28:31], v[146:149], v[202:205], v[28:31]
	v_mfma_f32_16x16x32_bf16 v[24:27], v[154:157], v[202:205], v[24:27]
	v_mfma_f32_16x16x32_bf16 v[12:15], v[146:149], v[210:213], v[12:15]
	v_mfma_f32_16x16x32_bf16 v[8:11], v[154:157], v[210:213], v[8:11]
	v_mfma_f32_16x16x32_bf16 v[52:55], v[170:173], v[186:189], v[52:55]
	v_mfma_f32_16x16x32_bf16 v[48:51], v[178:181], v[186:189], v[48:51]
	v_mfma_f32_16x16x32_bf16 v[36:39], v[170:173], v[194:197], v[36:39]
	v_mfma_f32_16x16x32_bf16 v[32:35], v[178:181], v[194:197], v[32:35]
	v_mfma_f32_16x16x32_bf16 v[20:23], v[170:173], v[202:205], v[20:23]
	v_mfma_f32_16x16x32_bf16 v[16:19], v[178:181], v[202:205], v[16:19]
	v_mfma_f32_16x16x32_bf16 v[4:7], v[170:173], v[210:213], v[4:7]
	v_mfma_f32_16x16x32_bf16 v[0:3], v[178:181], v[210:213], v[0:3]
	v_mfma_f32_16x16x32_bf16 v[60:63], v[150:153], v[190:193], v[60:63]
	v_mfma_f32_16x16x32_bf16 v[56:59], v[166:169], v[190:193], v[56:59]
	v_mfma_f32_16x16x32_bf16 v[44:47], v[150:153], v[198:201], v[44:47]
	v_mfma_f32_16x16x32_bf16 v[40:43], v[166:169], v[198:201], v[40:43]
	v_mfma_f32_16x16x32_bf16 v[28:31], v[150:153], v[206:209], v[28:31]
	v_mfma_f32_16x16x32_bf16 v[24:27], v[166:169], v[206:209], v[24:27]
	v_mfma_f32_16x16x32_bf16 v[12:15], v[150:153], v[214:217], v[12:15]
	v_mfma_f32_16x16x32_bf16 v[8:11], v[166:169], v[214:217], v[8:11]
	v_mfma_f32_16x16x32_bf16 v[52:55], v[174:177], v[190:193], v[52:55]
	v_mfma_f32_16x16x32_bf16 v[48:51], v[182:185], v[190:193], v[48:51]
	v_mfma_f32_16x16x32_bf16 v[36:39], v[174:177], v[198:201], v[36:39]
	v_mfma_f32_16x16x32_bf16 v[32:35], v[182:185], v[198:201], v[32:35]
	v_mfma_f32_16x16x32_bf16 v[20:23], v[174:177], v[206:209], v[20:23]
	v_mfma_f32_16x16x32_bf16 v[16:19], v[182:185], v[206:209], v[16:19]
	v_mfma_f32_16x16x32_bf16 v[4:7], v[174:177], v[214:217], v[4:7]
	v_mfma_f32_16x16x32_bf16 v[0:3], v[182:185], v[214:217], v[0:3]
	s_barrier
	s_setprio 0
	s_add_i32 s62, s62, 2
	s_add_u32 s36, s36, 0x100
	s_addc_u32 s37, s37, 0
	s_add_u32 s60, s60, 0x100
	s_addc_u32 s61, s61, 0
	s_cmp_gt_u32 s62, 13
	s_cbranch_scc0 .LBB0_197
	s_and_b64 vcc, exec, s[12:13]
	s_cbranch_vccz .LBB0_200
	s_barrier

.Lrb0_skip:
	s_add_u32 s48, s46, 0xfffc0080
	s_addc_u32 s49, s47, -1
	s_add_i32 s63, 0, 0x10000
	s_cmp_eq_u32 s62, 12
	s_cselect_b32 s51, s39, s49
	s_cselect_b32 s50, s58, s48
	v_add_u32_e32 v0, s63, v144
	s_cselect_b32 s49, s23, s61
	s_cselect_b32 s48, s59, s60
	s_add_i32 s66, 0, 0x14000
	ds_read_b128 v[146:149], v0
	ds_read_b128 v[150:153], v0 offset:1024
	ds_read_b128 v[154:157], v0 offset:2048
	ds_read_b128 v[158:161], v0 offset:3072
	v_add_u32_e32 v0, s66, v144
	ds_read_b128 v[162:165], v0
	ds_read_b128 v[166:169], v0 offset:1024
	ds_read_b128 v[170:173], v0 offset:2048
	ds_read_b128 v[174:177], v0 offset:3072
	s_add_i32 m0, s5, 0xc000
	ds_read_b128 v[178:181], v145
	ds_read_b128 v[182:185], v145 offset:1024
	ds_read_b128 v[204:207], v145 offset:2048
	ds_read_b128 v[208:211], v145 offset:3072
	ds_read_b128 v[212:215], v145 offset:4096
	ds_read_b128 v[216:219], v145 offset:5120
	ds_read_b128 v[220:223], v145 offset:6144
	ds_read_b128 v[224:227], v145 offset:7168
	global_load_lds_dwordx4 v138, s[46:47]
	s_add_i32 m0, s5, 0xe000
	s_nop 0
	global_load_lds_dwordx4 v140, s[46:47]
	s_waitcnt vmcnt(8)
	s_waitcnt lgkmcnt(0)
	s_setprio 1
	s_barrier
	v_mfma_f32_16x16x32_bf16 v[118:121], v[146:149], v[178:181], 0
	v_mfma_f32_16x16x32_bf16 v[114:117], v[154:157], v[178:181], 0
	v_mfma_f32_16x16x32_bf16 v[110:113], v[146:149], v[204:207], 0
	v_mfma_f32_16x16x32_bf16 v[102:105], v[154:157], v[204:207], 0
	v_mfma_f32_16x16x32_bf16 v[94:97], v[146:149], v[212:215], 0
	v_mfma_f32_16x16x32_bf16 v[86:89], v[154:157], v[212:215], 0
	v_mfma_f32_16x16x32_bf16 v[78:81], v[146:149], v[220:223], 0
	v_mfma_f32_16x16x32_bf16 v[70:73], v[154:157], v[220:223], 0
	v_mfma_f32_16x16x32_bf16 v[126:129], v[162:165], v[178:181], 0
	v_mfma_f32_16x16x32_bf16 v[122:125], v[170:173], v[178:181], 0
	v_mfma_f32_16x16x32_bf16 v[106:109], v[162:165], v[204:207], 0
	v_mfma_f32_16x16x32_bf16 v[98:101], v[170:173], v[204:207], 0
	v_mfma_f32_16x16x32_bf16 v[90:93], v[162:165], v[212:215], 0
	v_mfma_f32_16x16x32_bf16 v[82:85], v[170:173], v[212:215], 0
	v_mfma_f32_16x16x32_bf16 v[74:77], v[162:165], v[220:223], 0
	v_mfma_f32_16x16x32_bf16 v[66:69], v[170:173], v[220:223], 0
	v_mfma_f32_16x16x32_bf16 v[118:121], v[150:153], v[182:185], v[118:121]
	v_mfma_f32_16x16x32_bf16 v[114:117], v[158:161], v[182:185], v[114:117]
	v_mfma_f32_16x16x32_bf16 v[110:113], v[150:153], v[208:211], v[110:113]
	v_mfma_f32_16x16x32_bf16 v[102:105], v[158:161], v[208:211], v[102:105]
	v_mfma_f32_16x16x32_bf16 v[94:97], v[150:153], v[216:219], v[94:97]
	v_mfma_f32_16x16x32_bf16 v[86:89], v[158:161], v[216:219], v[86:89]
	v_mfma_f32_16x16x32_bf16 v[78:81], v[150:153], v[224:227], v[78:81]
	v_mfma_f32_16x16x32_bf16 v[70:73], v[158:161], v[224:227], v[70:73]
	v_mfma_f32_16x16x32_bf16 v[126:129], v[166:169], v[182:185], v[126:129]
	v_mfma_f32_16x16x32_bf16 v[122:125], v[174:177], v[182:185], v[122:125]
	v_mfma_f32_16x16x32_bf16 v[106:109], v[166:169], v[208:211], v[106:109]
	v_mfma_f32_16x16x32_bf16 v[98:101], v[174:177], v[208:211], v[98:101]
	v_mfma_f32_16x16x32_bf16 v[90:93], v[166:169], v[216:219], v[90:93]
	v_mfma_f32_16x16x32_bf16 v[82:85], v[174:177], v[216:219], v[82:85]
	v_mfma_f32_16x16x32_bf16 v[74:77], v[166:169], v[224:227], v[74:77]
	v_mfma_f32_16x16x32_bf16 v[66:69], v[174:177], v[224:227], v[66:69]
	s_barrier
	s_setprio 0
	s_add_i32 s63, s63, s4
	s_mov_b32 m0, s63
	ds_read_b128 v[178:181], v145 offset:16384
	ds_read_b128 v[182:185], v145 offset:17408
	ds_read_b128 v[204:207], v145 offset:18432
	ds_read_b128 v[208:211], v145 offset:19456
	ds_read_b128 v[212:215], v145 offset:20480
	ds_read_b128 v[216:219], v145 offset:21504
	ds_read_b128 v[220:223], v145 offset:22528
	ds_read_b128 v[224:227], v145 offset:23552
	global_load_lds_dwordx4 v134, s[48:49]
	s_add_i32 m0, s63, 0x2000
	s_add_u32 s64, s48, 0x40000
	s_addc_u32 s65, s49, 0
	s_add_i32 s63, s66, s4
	global_load_lds_dwordx4 v130, s[48:49]
	s_mov_b32 m0, s63
	s_nop 0
	global_load_lds_dwordx4 v134, s[64:65]
	s_add_i32 m0, s63, 0x2000
	s_nop 0
	global_load_lds_dwordx4 v130, s[64:65]
	s_mov_b32 m0, s5
	s_nop 0
	global_load_lds_dwordx4 v136, s[50:51]
	s_mov_b32 m0, s6
	s_nop 0
	global_load_lds_dwordx4 v132, s[50:51]
	s_waitcnt vmcnt(8)
	s_waitcnt lgkmcnt(0)
	s_setprio 1
	s_barrier
	v_mfma_f32_16x16x32_bf16 v[62:65], v[146:149], v[178:181], 0
	v_mfma_f32_16x16x32_bf16 v[54:57], v[154:157], v[178:181], 0
	v_mfma_f32_16x16x32_bf16 v[46:49], v[146:149], v[204:207], 0
	v_mfma_f32_16x16x32_bf16 v[38:41], v[154:157], v[204:207], 0
	v_mfma_f32_16x16x32_bf16 v[30:33], v[146:149], v[212:215], 0
	v_mfma_f32_16x16x32_bf16 v[22:25], v[154:157], v[212:215], 0
	v_mfma_f32_16x16x32_bf16 v[14:17], v[146:149], v[220:223], 0
	v_mfma_f32_16x16x32_bf16 v[6:9], v[154:157], v[220:223], 0
	v_mfma_f32_16x16x32_bf16 v[58:61], v[162:165], v[178:181], 0
	v_mfma_f32_16x16x32_bf16 v[50:53], v[170:173], v[178:181], 0
	v_mfma_f32_16x16x32_bf16 v[42:45], v[162:165], v[204:207], 0
	v_mfma_f32_16x16x32_bf16 v[34:37], v[170:173], v[204:207], 0
	v_mfma_f32_16x16x32_bf16 v[26:29], v[162:165], v[212:215], 0
	v_mfma_f32_16x16x32_bf16 v[18:21], v[170:173], v[212:215], 0
	v_mfma_f32_16x16x32_bf16 v[10:13], v[162:165], v[220:223], 0
	v_mfma_f32_16x16x32_bf16 v[2:5], v[170:173], v[220:223], 0
	v_mfma_f32_16x16x32_bf16 v[62:65], v[150:153], v[182:185], v[62:65]
	v_mfma_f32_16x16x32_bf16 v[54:57], v[158:161], v[182:185], v[54:57]
	v_mfma_f32_16x16x32_bf16 v[46:49], v[150:153], v[208:211], v[46:49]
	v_mfma_f32_16x16x32_bf16 v[38:41], v[158:161], v[208:211], v[38:41]
	v_mfma_f32_16x16x32_bf16 v[30:33], v[150:153], v[216:219], v[30:33]
	v_mfma_f32_16x16x32_bf16 v[22:25], v[158:161], v[216:219], v[22:25]
	v_mfma_f32_16x16x32_bf16 v[14:17], v[150:153], v[224:227], v[14:17]
	v_mfma_f32_16x16x32_bf16 v[6:9], v[158:161], v[224:227], v[6:9]
	v_mfma_f32_16x16x32_bf16 v[58:61], v[166:169], v[182:185], v[58:61]
	v_mfma_f32_16x16x32_bf16 v[50:53], v[174:177], v[182:185], v[50:53]
	v_mfma_f32_16x16x32_bf16 v[42:45], v[166:169], v[208:211], v[42:45]
	v_mfma_f32_16x16x32_bf16 v[34:37], v[174:177], v[208:211], v[34:37]
	v_mfma_f32_16x16x32_bf16 v[26:29], v[166:169], v[216:219], v[26:29]
	v_mfma_f32_16x16x32_bf16 v[18:21], v[174:177], v[216:219], v[18:21]
	v_mfma_f32_16x16x32_bf16 v[10:13], v[166:169], v[224:227], v[10:13]
	v_mfma_f32_16x16x32_bf16 v[2:5], v[174:177], v[224:227], v[2:5]
	s_barrier
	s_setprio 0
	s_add_i32 s63, 0, 0x18000
	v_add_u32_e32 v0, s63, v144
	s_add_i32 s64, 0, 0x1c000
	ds_read_b128 v[146:149], v0
	ds_read_b128 v[150:153], v0 offset:1024
	ds_read_b128 v[154:157], v0 offset:2048
	ds_read_b128 v[158:161], v0 offset:3072
	v_add_u32_e32 v0, s64, v144
	ds_read_b128 v[162:165], v0
	ds_read_b128 v[166:169], v0 offset:1024
	ds_read_b128 v[170:173], v0 offset:2048
	ds_read_b128 v[174:177], v0 offset:3072
	s_add_u32 s50, s50, 0x40000
	s_addc_u32 s51, s51, 0
	s_mov_b32 m0, s7
	ds_read_b128 v[178:181], v145 offset:32768
	ds_read_b128 v[182:185], v145 offset:33792
	ds_read_b128 v[204:207], v145 offset:34816
	ds_read_b128 v[208:211], v145 offset:35840
	ds_read_b128 v[212:215], v145 offset:36864
	ds_read_b128 v[216:219], v145 offset:37888
	ds_read_b128 v[220:223], v145 offset:38912
	ds_read_b128 v[224:227], v145 offset:39936
	global_load_lds_dwordx4 v136, s[50:51]
	s_mov_b32 m0, s52
	s_nop 0
	global_load_lds_dwordx4 v132, s[50:51]
	s_waitcnt vmcnt(8)
	s_waitcnt lgkmcnt(0)
	s_setprio 1
	s_barrier
	v_mfma_f32_16x16x32_bf16 v[118:121], v[146:149], v[178:181], v[118:121]
	v_mfma_f32_16x16x32_bf16 v[114:117], v[154:157], v[178:181], v[114:117]
	v_mfma_f32_16x16x32_bf16 v[110:113], v[146:149], v[204:207], v[110:113]
	v_mfma_f32_16x16x32_bf16 v[102:105], v[154:157], v[204:207], v[102:105]
	v_mfma_f32_16x16x32_bf16 v[94:97], v[146:149], v[212:215], v[94:97]
	v_mfma_f32_16x16x32_bf16 v[86:89], v[154:157], v[212:215], v[86:89]
	v_mfma_f32_16x16x32_bf16 v[78:81], v[146:149], v[220:223], v[78:81]
	v_mfma_f32_16x16x32_bf16 v[70:73], v[154:157], v[220:223], v[70:73]
	v_mfma_f32_16x16x32_bf16 v[126:129], v[162:165], v[178:181], v[126:129]
	v_mfma_f32_16x16x32_bf16 v[122:125], v[170:173], v[178:181], v[122:125]
	v_mfma_f32_16x16x32_bf16 v[106:109], v[162:165], v[204:207], v[106:109]
	v_mfma_f32_16x16x32_bf16 v[98:101], v[170:173], v[204:207], v[98:101]
	v_mfma_f32_16x16x32_bf16 v[90:93], v[162:165], v[212:215], v[90:93]
	v_mfma_f32_16x16x32_bf16 v[82:85], v[170:173], v[212:215], v[82:85]
	v_mfma_f32_16x16x32_bf16 v[74:77], v[162:165], v[220:223], v[74:77]
	v_mfma_f32_16x16x32_bf16 v[66:69], v[170:173], v[220:223], v[66:69]
	v_mfma_f32_16x16x32_bf16 v[118:121], v[150:153], v[182:185], v[118:121]
	v_mfma_f32_16x16x32_bf16 v[114:117], v[158:161], v[182:185], v[114:117]
	v_mfma_f32_16x16x32_bf16 v[110:113], v[150:153], v[208:211], v[110:113]
	v_mfma_f32_16x16x32_bf16 v[102:105], v[158:161], v[208:211], v[102:105]
	v_mfma_f32_16x16x32_bf16 v[94:97], v[150:153], v[216:219], v[94:97]
	v_mfma_f32_16x16x32_bf16 v[86:89], v[158:161], v[216:219], v[86:89]
	v_mfma_f32_16x16x32_bf16 v[78:81], v[150:153], v[224:227], v[78:81]
	v_mfma_f32_16x16x32_bf16 v[70:73], v[158:161], v[224:227], v[70:73]
	v_mfma_f32_16x16x32_bf16 v[126:129], v[166:169], v[182:185], v[126:129]
	v_mfma_f32_16x16x32_bf16 v[122:125], v[174:177], v[182:185], v[122:125]
	v_mfma_f32_16x16x32_bf16 v[106:109], v[166:169], v[208:211], v[106:109]
	v_mfma_f32_16x16x32_bf16 v[98:101], v[174:177], v[208:211], v[98:101]
	v_mfma_f32_16x16x32_bf16 v[90:93], v[166:169], v[216:219], v[90:93]
	v_mfma_f32_16x16x32_bf16 v[82:85], v[174:177], v[216:219], v[82:85]
	v_mfma_f32_16x16x32_bf16 v[74:77], v[166:169], v[224:227], v[74:77]
	v_mfma_f32_16x16x32_bf16 v[66:69], v[174:177], v[224:227], v[66:69]
	s_barrier
	s_setprio 0
	s_add_i32 s65, s63, s4
	s_add_u32 s48, s48, 0x80
	s_addc_u32 s49, s49, 0
	s_mov_b32 m0, s65
	ds_read_b128 v[178:181], v145 offset:49152
	ds_read_b128 v[182:185], v145 offset:50176
	ds_read_b128 v[204:207], v145 offset:51200
	ds_read_b128 v[208:211], v145 offset:52224
	ds_read_b128 v[212:215], v145 offset:53248
	ds_read_b128 v[216:219], v145 offset:54272
	ds_read_b128 v[220:223], v145 offset:55296
	ds_read_b128 v[224:227], v145 offset:56320
	global_load_lds_dwordx4 v134, s[48:49]
	s_add_i32 m0, s65, 0x2000
	s_add_i32 s65, s64, s4
	global_load_lds_dwordx4 v130, s[48:49]
	s_add_u32 s48, s48, 0x40000
	s_addc_u32 s49, s49, 0
	s_mov_b32 m0, s65
	s_sub_u32 s50, s50, 0x3ff80
	global_load_lds_dwordx4 v134, s[48:49]
	s_subb_u32 s51, s51, 0
	s_add_i32 m0, s65, 0x2000
	s_nop 0
	global_load_lds_dwordx4 v130, s[48:49]
	s_mov_b32 m0, s55
	s_nop 0
	global_load_lds_dwordx4 v136, s[50:51]
	s_mov_b32 m0, s56
	s_nop 0
	global_load_lds_dwordx4 v132, s[50:51]
	s_waitcnt vmcnt(8)
	s_waitcnt lgkmcnt(0)
	s_setprio 1
	s_barrier
	v_mfma_f32_16x16x32_bf16 v[62:65], v[146:149], v[178:181], v[62:65]
	v_mfma_f32_16x16x32_bf16 v[54:57], v[154:157], v[178:181], v[54:57]
	v_mfma_f32_16x16x32_bf16 v[46:49], v[146:149], v[204:207], v[46:49]
	v_mfma_f32_16x16x32_bf16 v[38:41], v[154:157], v[204:207], v[38:41]
	v_mfma_f32_16x16x32_bf16 v[30:33], v[146:149], v[212:215], v[30:33]
	v_mfma_f32_16x16x32_bf16 v[22:25], v[154:157], v[212:215], v[22:25]
	v_mfma_f32_16x16x32_bf16 v[14:17], v[146:149], v[220:223], v[14:17]
	v_mfma_f32_16x16x32_bf16 v[6:9], v[154:157], v[220:223], v[6:9]
	v_mfma_f32_16x16x32_bf16 v[58:61], v[162:165], v[178:181], v[58:61]
	v_mfma_f32_16x16x32_bf16 v[50:53], v[170:173], v[178:181], v[50:53]
	v_mfma_f32_16x16x32_bf16 v[42:45], v[162:165], v[204:207], v[42:45]
	v_mfma_f32_16x16x32_bf16 v[34:37], v[170:173], v[204:207], v[34:37]
	v_mfma_f32_16x16x32_bf16 v[26:29], v[162:165], v[212:215], v[26:29]
	v_mfma_f32_16x16x32_bf16 v[18:21], v[170:173], v[212:215], v[18:21]
	v_mfma_f32_16x16x32_bf16 v[10:13], v[162:165], v[220:223], v[10:13]
	v_mfma_f32_16x16x32_bf16 v[2:5], v[170:173], v[220:223], v[2:5]
	v_mfma_f32_16x16x32_bf16 v[62:65], v[150:153], v[182:185], v[62:65]
	v_mfma_f32_16x16x32_bf16 v[54:57], v[158:161], v[182:185], v[54:57]
	v_mfma_f32_16x16x32_bf16 v[46:49], v[150:153], v[208:211], v[46:49]
	v_mfma_f32_16x16x32_bf16 v[38:41], v[158:161], v[208:211], v[38:41]
	v_mfma_f32_16x16x32_bf16 v[30:33], v[150:153], v[216:219], v[30:33]
	v_mfma_f32_16x16x32_bf16 v[22:25], v[158:161], v[216:219], v[22:25]
	v_mfma_f32_16x16x32_bf16 v[14:17], v[150:153], v[224:227], v[14:17]
	v_mfma_f32_16x16x32_bf16 v[6:9], v[158:161], v[224:227], v[6:9]
	v_mfma_f32_16x16x32_bf16 v[58:61], v[166:169], v[182:185], v[58:61]
	v_mfma_f32_16x16x32_bf16 v[50:53], v[174:177], v[182:185], v[50:53]
	v_mfma_f32_16x16x32_bf16 v[42:45], v[166:169], v[208:211], v[42:45]
	v_mfma_f32_16x16x32_bf16 v[34:37], v[174:177], v[208:211], v[34:37]
	v_mfma_f32_16x16x32_bf16 v[26:29], v[166:169], v[216:219], v[26:29]
	v_mfma_f32_16x16x32_bf16 v[18:21], v[174:177], v[216:219], v[18:21]
	v_mfma_f32_16x16x32_bf16 v[10:13], v[166:169], v[224:227], v[10:13]
	v_mfma_f32_16x16x32_bf16 v[2:5], v[174:177], v[224:227], v[2:5]
	s_barrier
	s_setprio 0
	s_add_i32 s62, s62, 2
	s_add_u32 s46, s46, 0x100
	s_addc_u32 s47, s47, 0
	s_add_u32 s60, s60, 0x100
	s_addc_u32 s61, s61, 0
	s_cmp_gt_u32 s62, 13
.LBB0_229:
	s_add_u32 s48, s46, 0xfffc0080
	s_addc_u32 s49, s47, -1
	s_add_i32 s63, 0, 0x10000
	s_cmp_eq_u32 s62, 12
	s_cselect_b32 s51, s39, s49
	s_cselect_b32 s50, s58, s48
	v_add_u32_e32 v0, s63, v144
	s_cselect_b32 s49, s23, s61
	s_cselect_b32 s48, s59, s60
	s_add_i32 s66, 0, 0x14000
	ds_read_b128 v[146:149], v0
	ds_read_b128 v[150:153], v0 offset:1024
	ds_read_b128 v[154:157], v0 offset:2048
	ds_read_b128 v[158:161], v0 offset:3072
	v_add_u32_e32 v0, s66, v144
	ds_read_b128 v[162:165], v0
	ds_read_b128 v[166:169], v0 offset:1024
	ds_read_b128 v[170:173], v0 offset:2048
	ds_read_b128 v[174:177], v0 offset:3072
	s_add_i32 m0, s5, 0xc000
	ds_read_b128 v[178:181], v145
	ds_read_b128 v[182:185], v145 offset:1024
	ds_read_b128 v[204:207], v145 offset:2048
	ds_read_b128 v[208:211], v145 offset:3072
	ds_read_b128 v[212:215], v145 offset:4096
	ds_read_b128 v[216:219], v145 offset:5120
	ds_read_b128 v[220:223], v145 offset:6144
	ds_read_b128 v[224:227], v145 offset:7168
	global_load_lds_dwordx4 v138, s[46:47]
	s_add_i32 m0, s5, 0xe000
	s_nop 0
	global_load_lds_dwordx4 v140, s[46:47]
	s_waitcnt vmcnt(8)
	s_waitcnt lgkmcnt(0)
	s_setprio 1
	s_barrier
	v_mfma_f32_16x16x32_bf16 v[118:121], v[146:149], v[178:181], v[118:121]
	v_mfma_f32_16x16x32_bf16 v[114:117], v[154:157], v[178:181], v[114:117]
	v_mfma_f32_16x16x32_bf16 v[110:113], v[146:149], v[204:207], v[110:113]
	v_mfma_f32_16x16x32_bf16 v[102:105], v[154:157], v[204:207], v[102:105]
	v_mfma_f32_16x16x32_bf16 v[94:97], v[146:149], v[212:215], v[94:97]
	v_mfma_f32_16x16x32_bf16 v[86:89], v[154:157], v[212:215], v[86:89]
	v_mfma_f32_16x16x32_bf16 v[78:81], v[146:149], v[220:223], v[78:81]
	v_mfma_f32_16x16x32_bf16 v[70:73], v[154:157], v[220:223], v[70:73]
	v_mfma_f32_16x16x32_bf16 v[126:129], v[162:165], v[178:181], v[126:129]
	v_mfma_f32_16x16x32_bf16 v[122:125], v[170:173], v[178:181], v[122:125]
	v_mfma_f32_16x16x32_bf16 v[106:109], v[162:165], v[204:207], v[106:109]
	v_mfma_f32_16x16x32_bf16 v[98:101], v[170:173], v[204:207], v[98:101]
	v_mfma_f32_16x16x32_bf16 v[90:93], v[162:165], v[212:215], v[90:93]
	v_mfma_f32_16x16x32_bf16 v[82:85], v[170:173], v[212:215], v[82:85]
	v_mfma_f32_16x16x32_bf16 v[74:77], v[162:165], v[220:223], v[74:77]
	v_mfma_f32_16x16x32_bf16 v[66:69], v[170:173], v[220:223], v[66:69]
	v_mfma_f32_16x16x32_bf16 v[118:121], v[150:153], v[182:185], v[118:121]
	v_mfma_f32_16x16x32_bf16 v[114:117], v[158:161], v[182:185], v[114:117]
	v_mfma_f32_16x16x32_bf16 v[110:113], v[150:153], v[208:211], v[110:113]
	v_mfma_f32_16x16x32_bf16 v[102:105], v[158:161], v[208:211], v[102:105]
	v_mfma_f32_16x16x32_bf16 v[94:97], v[150:153], v[216:219], v[94:97]
	v_mfma_f32_16x16x32_bf16 v[86:89], v[158:161], v[216:219], v[86:89]
	v_mfma_f32_16x16x32_bf16 v[78:81], v[150:153], v[224:227], v[78:81]
	v_mfma_f32_16x16x32_bf16 v[70:73], v[158:161], v[224:227], v[70:73]
	v_mfma_f32_16x16x32_bf16 v[126:129], v[166:169], v[182:185], v[126:129]
	v_mfma_f32_16x16x32_bf16 v[122:125], v[174:177], v[182:185], v[122:125]
	v_mfma_f32_16x16x32_bf16 v[106:109], v[166:169], v[208:211], v[106:109]
	v_mfma_f32_16x16x32_bf16 v[98:101], v[174:177], v[208:211], v[98:101]
	v_mfma_f32_16x16x32_bf16 v[90:93], v[166:169], v[216:219], v[90:93]
	v_mfma_f32_16x16x32_bf16 v[82:85], v[174:177], v[216:219], v[82:85]
	v_mfma_f32_16x16x32_bf16 v[74:77], v[166:169], v[224:227], v[74:77]
	v_mfma_f32_16x16x32_bf16 v[66:69], v[174:177], v[224:227], v[66:69]
	s_barrier
	s_setprio 0
	s_add_i32 s63, s63, s4
	s_mov_b32 m0, s63
	ds_read_b128 v[178:181], v145 offset:16384
	ds_read_b128 v[182:185], v145 offset:17408
	ds_read_b128 v[204:207], v145 offset:18432
	ds_read_b128 v[208:211], v145 offset:19456
	ds_read_b128 v[212:215], v145 offset:20480
	ds_read_b128 v[216:219], v145 offset:21504
	ds_read_b128 v[220:223], v145 offset:22528
	ds_read_b128 v[224:227], v145 offset:23552
	global_load_lds_dwordx4 v134, s[48:49]
	s_add_i32 m0, s63, 0x2000
	s_add_u32 s64, s48, 0x40000
	s_addc_u32 s65, s49, 0
	s_add_i32 s63, s66, s4
	global_load_lds_dwordx4 v130, s[48:49]
	s_mov_b32 m0, s63
	s_nop 0
	global_load_lds_dwordx4 v134, s[64:65]
	s_add_i32 m0, s63, 0x2000
	s_nop 0
	global_load_lds_dwordx4 v130, s[64:65]
	s_mov_b32 m0, s5
	s_nop 0
	global_load_lds_dwordx4 v136, s[50:51]
	s_mov_b32 m0, s6
	s_nop 0
	global_load_lds_dwordx4 v132, s[50:51]
	s_waitcnt vmcnt(8)
	s_waitcnt lgkmcnt(0)
	s_setprio 1
	s_barrier
	v_mfma_f32_16x16x32_bf16 v[62:65], v[146:149], v[178:181], v[62:65]
	v_mfma_f32_16x16x32_bf16 v[54:57], v[154:157], v[178:181], v[54:57]
	v_mfma_f32_16x16x32_bf16 v[46:49], v[146:149], v[204:207], v[46:49]
	v_mfma_f32_16x16x32_bf16 v[38:41], v[154:157], v[204:207], v[38:41]
	v_mfma_f32_16x16x32_bf16 v[30:33], v[146:149], v[212:215], v[30:33]
	v_mfma_f32_16x16x32_bf16 v[22:25], v[154:157], v[212:215], v[22:25]
	v_mfma_f32_16x16x32_bf16 v[14:17], v[146:149], v[220:223], v[14:17]
	v_mfma_f32_16x16x32_bf16 v[6:9], v[154:157], v[220:223], v[6:9]
	v_mfma_f32_16x16x32_bf16 v[58:61], v[162:165], v[178:181], v[58:61]
	v_mfma_f32_16x16x32_bf16 v[50:53], v[170:173], v[178:181], v[50:53]
	v_mfma_f32_16x16x32_bf16 v[42:45], v[162:165], v[204:207], v[42:45]
	v_mfma_f32_16x16x32_bf16 v[34:37], v[170:173], v[204:207], v[34:37]
	v_mfma_f32_16x16x32_bf16 v[26:29], v[162:165], v[212:215], v[26:29]
	v_mfma_f32_16x16x32_bf16 v[18:21], v[170:173], v[212:215], v[18:21]
	v_mfma_f32_16x16x32_bf16 v[10:13], v[162:165], v[220:223], v[10:13]
	v_mfma_f32_16x16x32_bf16 v[2:5], v[170:173], v[220:223], v[2:5]
	v_mfma_f32_16x16x32_bf16 v[62:65], v[150:153], v[182:185], v[62:65]
	v_mfma_f32_16x16x32_bf16 v[54:57], v[158:161], v[182:185], v[54:57]
	v_mfma_f32_16x16x32_bf16 v[46:49], v[150:153], v[208:211], v[46:49]
	v_mfma_f32_16x16x32_bf16 v[38:41], v[158:161], v[208:211], v[38:41]
	v_mfma_f32_16x16x32_bf16 v[30:33], v[150:153], v[216:219], v[30:33]
	v_mfma_f32_16x16x32_bf16 v[22:25], v[158:161], v[216:219], v[22:25]
	v_mfma_f32_16x16x32_bf16 v[14:17], v[150:153], v[224:227], v[14:17]
	v_mfma_f32_16x16x32_bf16 v[6:9], v[158:161], v[224:227], v[6:9]
	v_mfma_f32_16x16x32_bf16 v[58:61], v[166:169], v[182:185], v[58:61]
	v_mfma_f32_16x16x32_bf16 v[50:53], v[174:177], v[182:185], v[50:53]
	v_mfma_f32_16x16x32_bf16 v[42:45], v[166:169], v[208:211], v[42:45]
	v_mfma_f32_16x16x32_bf16 v[34:37], v[174:177], v[208:211], v[34:37]
	v_mfma_f32_16x16x32_bf16 v[26:29], v[166:169], v[216:219], v[26:29]
	v_mfma_f32_16x16x32_bf16 v[18:21], v[174:177], v[216:219], v[18:21]
	v_mfma_f32_16x16x32_bf16 v[10:13], v[166:169], v[224:227], v[10:13]
	v_mfma_f32_16x16x32_bf16 v[2:5], v[174:177], v[224:227], v[2:5]
	s_barrier
	s_setprio 0
	s_add_i32 s63, 0, 0x18000
	v_add_u32_e32 v0, s63, v144
	s_add_i32 s64, 0, 0x1c000
	ds_read_b128 v[146:149], v0
	ds_read_b128 v[150:153], v0 offset:1024
	ds_read_b128 v[154:157], v0 offset:2048
	ds_read_b128 v[158:161], v0 offset:3072
	v_add_u32_e32 v0, s64, v144
	ds_read_b128 v[162:165], v0
	ds_read_b128 v[166:169], v0 offset:1024
	ds_read_b128 v[170:173], v0 offset:2048
	ds_read_b128 v[174:177], v0 offset:3072
	s_add_u32 s50, s50, 0x40000
	s_addc_u32 s51, s51, 0
	s_mov_b32 m0, s7
	ds_read_b128 v[178:181], v145 offset:32768
	ds_read_b128 v[182:185], v145 offset:33792
	ds_read_b128 v[204:207], v145 offset:34816
	ds_read_b128 v[208:211], v145 offset:35840
	ds_read_b128 v[212:215], v145 offset:36864
	ds_read_b128 v[216:219], v145 offset:37888
	ds_read_b128 v[220:223], v145 offset:38912
	ds_read_b128 v[224:227], v145 offset:39936
	global_load_lds_dwordx4 v136, s[50:51]
	s_mov_b32 m0, s52
	s_nop 0
	global_load_lds_dwordx4 v132, s[50:51]
	s_waitcnt vmcnt(8)
	s_waitcnt lgkmcnt(0)
	s_setprio 1
	s_barrier
	v_mfma_f32_16x16x32_bf16 v[118:121], v[146:149], v[178:181], v[118:121]
	v_mfma_f32_16x16x32_bf16 v[114:117], v[154:157], v[178:181], v[114:117]
	v_mfma_f32_16x16x32_bf16 v[110:113], v[146:149], v[204:207], v[110:113]
	v_mfma_f32_16x16x32_bf16 v[102:105], v[154:157], v[204:207], v[102:105]
	v_mfma_f32_16x16x32_bf16 v[94:97], v[146:149], v[212:215], v[94:97]
	v_mfma_f32_16x16x32_bf16 v[86:89], v[154:157], v[212:215], v[86:89]
	v_mfma_f32_16x16x32_bf16 v[78:81], v[146:149], v[220:223], v[78:81]
	v_mfma_f32_16x16x32_bf16 v[70:73], v[154:157], v[220:223], v[70:73]
	v_mfma_f32_16x16x32_bf16 v[126:129], v[162:165], v[178:181], v[126:129]
	v_mfma_f32_16x16x32_bf16 v[122:125], v[170:173], v[178:181], v[122:125]
	v_mfma_f32_16x16x32_bf16 v[106:109], v[162:165], v[204:207], v[106:109]
	v_mfma_f32_16x16x32_bf16 v[98:101], v[170:173], v[204:207], v[98:101]
	v_mfma_f32_16x16x32_bf16 v[90:93], v[162:165], v[212:215], v[90:93]
	v_mfma_f32_16x16x32_bf16 v[82:85], v[170:173], v[212:215], v[82:85]
	v_mfma_f32_16x16x32_bf16 v[74:77], v[162:165], v[220:223], v[74:77]
	v_mfma_f32_16x16x32_bf16 v[66:69], v[170:173], v[220:223], v[66:69]
	v_mfma_f32_16x16x32_bf16 v[118:121], v[150:153], v[182:185], v[118:121]
	v_mfma_f32_16x16x32_bf16 v[114:117], v[158:161], v[182:185], v[114:117]
	v_mfma_f32_16x16x32_bf16 v[110:113], v[150:153], v[208:211], v[110:113]
	v_mfma_f32_16x16x32_bf16 v[102:105], v[158:161], v[208:211], v[102:105]
	v_mfma_f32_16x16x32_bf16 v[94:97], v[150:153], v[216:219], v[94:97]
	v_mfma_f32_16x16x32_bf16 v[86:89], v[158:161], v[216:219], v[86:89]
	v_mfma_f32_16x16x32_bf16 v[78:81], v[150:153], v[224:227], v[78:81]
	v_mfma_f32_16x16x32_bf16 v[70:73], v[158:161], v[224:227], v[70:73]
	v_mfma_f32_16x16x32_bf16 v[126:129], v[166:169], v[182:185], v[126:129]
	v_mfma_f32_16x16x32_bf16 v[122:125], v[174:177], v[182:185], v[122:125]
	v_mfma_f32_16x16x32_bf16 v[106:109], v[166:169], v[208:211], v[106:109]
	v_mfma_f32_16x16x32_bf16 v[98:101], v[174:177], v[208:211], v[98:101]
	v_mfma_f32_16x16x32_bf16 v[90:93], v[166:169], v[216:219], v[90:93]
	v_mfma_f32_16x16x32_bf16 v[82:85], v[174:177], v[216:219], v[82:85]
	v_mfma_f32_16x16x32_bf16 v[74:77], v[166:169], v[224:227], v[74:77]
	v_mfma_f32_16x16x32_bf16 v[66:69], v[174:177], v[224:227], v[66:69]
	s_barrier
	s_setprio 0
	s_add_i32 s65, s63, s4
	s_add_u32 s48, s48, 0x80
	s_addc_u32 s49, s49, 0
	s_mov_b32 m0, s65
	ds_read_b128 v[178:181], v145 offset:49152
	ds_read_b128 v[182:185], v145 offset:50176
	ds_read_b128 v[204:207], v145 offset:51200
	ds_read_b128 v[208:211], v145 offset:52224
	ds_read_b128 v[212:215], v145 offset:53248
	ds_read_b128 v[216:219], v145 offset:54272
	ds_read_b128 v[220:223], v145 offset:55296
	ds_read_b128 v[224:227], v145 offset:56320
	global_load_lds_dwordx4 v134, s[48:49]
	s_add_i32 m0, s65, 0x2000
	s_add_i32 s65, s64, s4
	global_load_lds_dwordx4 v130, s[48:49]
	s_add_u32 s48, s48, 0x40000
	s_addc_u32 s49, s49, 0
	s_mov_b32 m0, s65
	s_sub_u32 s50, s50, 0x3ff80
	global_load_lds_dwordx4 v134, s[48:49]
	s_subb_u32 s51, s51, 0
	s_add_i32 m0, s65, 0x2000
	s_nop 0
	global_load_lds_dwordx4 v130, s[48:49]
	s_mov_b32 m0, s55
	s_nop 0
	global_load_lds_dwordx4 v136, s[50:51]
	s_mov_b32 m0, s56
	s_nop 0
	global_load_lds_dwordx4 v132, s[50:51]
	s_waitcnt vmcnt(8)
	s_waitcnt lgkmcnt(0)
	s_setprio 1
	s_barrier
	v_mfma_f32_16x16x32_bf16 v[62:65], v[146:149], v[178:181], v[62:65]
	v_mfma_f32_16x16x32_bf16 v[54:57], v[154:157], v[178:181], v[54:57]
	v_mfma_f32_16x16x32_bf16 v[46:49], v[146:149], v[204:207], v[46:49]
	v_mfma_f32_16x16x32_bf16 v[38:41], v[154:157], v[204:207], v[38:41]
	v_mfma_f32_16x16x32_bf16 v[30:33], v[146:149], v[212:215], v[30:33]
	v_mfma_f32_16x16x32_bf16 v[22:25], v[154:157], v[212:215], v[22:25]
	v_mfma_f32_16x16x32_bf16 v[14:17], v[146:149], v[220:223], v[14:17]
	v_mfma_f32_16x16x32_bf16 v[6:9], v[154:157], v[220:223], v[6:9]
	v_mfma_f32_16x16x32_bf16 v[58:61], v[162:165], v[178:181], v[58:61]
	v_mfma_f32_16x16x32_bf16 v[50:53], v[170:173], v[178:181], v[50:53]
	v_mfma_f32_16x16x32_bf16 v[42:45], v[162:165], v[204:207], v[42:45]
	v_mfma_f32_16x16x32_bf16 v[34:37], v[170:173], v[204:207], v[34:37]
	v_mfma_f32_16x16x32_bf16 v[26:29], v[162:165], v[212:215], v[26:29]
	v_mfma_f32_16x16x32_bf16 v[18:21], v[170:173], v[212:215], v[18:21]
	v_mfma_f32_16x16x32_bf16 v[10:13], v[162:165], v[220:223], v[10:13]
	v_mfma_f32_16x16x32_bf16 v[2:5], v[170:173], v[220:223], v[2:5]
	v_mfma_f32_16x16x32_bf16 v[62:65], v[150:153], v[182:185], v[62:65]
	v_mfma_f32_16x16x32_bf16 v[54:57], v[158:161], v[182:185], v[54:57]
	v_mfma_f32_16x16x32_bf16 v[46:49], v[150:153], v[208:211], v[46:49]
	v_mfma_f32_16x16x32_bf16 v[38:41], v[158:161], v[208:211], v[38:41]
	v_mfma_f32_16x16x32_bf16 v[30:33], v[150:153], v[216:219], v[30:33]
	v_mfma_f32_16x16x32_bf16 v[22:25], v[158:161], v[216:219], v[22:25]
	v_mfma_f32_16x16x32_bf16 v[14:17], v[150:153], v[224:227], v[14:17]
	v_mfma_f32_16x16x32_bf16 v[6:9], v[158:161], v[224:227], v[6:9]
	v_mfma_f32_16x16x32_bf16 v[58:61], v[166:169], v[182:185], v[58:61]
	v_mfma_f32_16x16x32_bf16 v[50:53], v[174:177], v[182:185], v[50:53]
	v_mfma_f32_16x16x32_bf16 v[42:45], v[166:169], v[208:211], v[42:45]
	v_mfma_f32_16x16x32_bf16 v[34:37], v[174:177], v[208:211], v[34:37]
	v_mfma_f32_16x16x32_bf16 v[26:29], v[166:169], v[216:219], v[26:29]
	v_mfma_f32_16x16x32_bf16 v[18:21], v[174:177], v[216:219], v[18:21]
	v_mfma_f32_16x16x32_bf16 v[10:13], v[166:169], v[224:227], v[10:13]
	v_mfma_f32_16x16x32_bf16 v[2:5], v[174:177], v[224:227], v[2:5]
	s_barrier
	s_setprio 0
	s_add_i32 s62, s62, 2
	s_add_u32 s46, s46, 0x100
	s_addc_u32 s47, s47, 0
	s_add_u32 s60, s60, 0x100
	s_addc_u32 s61, s61, 0
	s_cmp_gt_u32 s62, 13
	s_cbranch_scc0 .LBB0_229
	s_and_b64 vcc, exec, s[20:21]
	s_cbranch_vccz .LBB0_232
	s_barrier

.Lrb1_skip:
	s_add_u32 s0, s48, 0x100
	s_addc_u32 s1, s49, 0
	s_add_i32 s51, 0, 0x10000
	s_cmp_eq_u32 s19, 40
	s_cselect_b32 s55, s45, s1
	s_cselect_b32 s54, s44, s0
	v_add_u32_e32 v0, s51, v219
	s_cselect_b32 s53, s47, s18
	s_cselect_b32 s52, s46, s7
	s_add_i32 s66, 0, 0x14000
	ds_read_b128 v[106:109], v0
	ds_read_b128 v[110:113], v0 offset:1024
	ds_read_b128 v[126:129], v0 offset:2048
	ds_read_b128 v[134:137], v0 offset:3072
	v_add_u32_e32 v0, s66, v219
	ds_read_b128 v[146:149], v0
	ds_read_b128 v[150:153], v0 offset:1024
	ds_read_b128 v[154:157], v0 offset:2048
	ds_read_b128 v[158:161], v0 offset:3072
	v_lshl_add_u64 v[216:217], s[48:49], 0, v[212:213]
	s_add_i32 m0, s57, 0xc000
	ds_read_b128 v[162:165], v220
	ds_read_b128 v[166:169], v220 offset:1024
	ds_read_b128 v[170:173], v220 offset:2048
	ds_read_b128 v[174:177], v220 offset:3072
	ds_read_b128 v[178:181], v220 offset:4096
	ds_read_b128 v[182:185], v220 offset:5120
	ds_read_b128 v[222:225], v220 offset:6144
	ds_read_b128 v[226:229], v220 offset:7168
	global_load_lds_dwordx4 v[216:217], off
	v_lshl_add_u64 v[216:217], s[48:49], 0, v[214:215]
	s_add_i32 m0, s57, 0xe000
	s_nop 0
	global_load_lds_dwordx4 v[216:217], off
	s_waitcnt vmcnt(8)
	s_waitcnt lgkmcnt(0)
	s_setprio 1
	s_barrier
	v_mfma_f32_16x16x32_bf16 v[142:145], v[106:109], v[162:165], 0
	v_mfma_f32_16x16x32_bf16 v[138:141], v[126:129], v[162:165], 0
	v_mfma_f32_16x16x32_bf16 v[118:121], v[106:109], v[170:173], 0
	v_mfma_f32_16x16x32_bf16 v[114:117], v[126:129], v[170:173], 0
	v_mfma_f32_16x16x32_bf16 v[94:97], v[106:109], v[178:181], 0
	v_mfma_f32_16x16x32_bf16 v[90:93], v[126:129], v[178:181], 0
	v_mfma_f32_16x16x32_bf16 v[78:81], v[106:109], v[222:225], 0
	v_mfma_f32_16x16x32_bf16 v[74:77], v[126:129], v[222:225], 0
	v_mfma_f32_16x16x32_bf16 v[130:133], v[146:149], v[162:165], 0
	v_mfma_f32_16x16x32_bf16 v[122:125], v[154:157], v[162:165], 0
	v_mfma_f32_16x16x32_bf16 v[102:105], v[146:149], v[170:173], 0
	v_mfma_f32_16x16x32_bf16 v[98:101], v[154:157], v[170:173], 0
	v_mfma_f32_16x16x32_bf16 v[86:89], v[146:149], v[178:181], 0
	v_mfma_f32_16x16x32_bf16 v[82:85], v[154:157], v[178:181], 0
	v_mfma_f32_16x16x32_bf16 v[70:73], v[146:149], v[222:225], 0
	v_mfma_f32_16x16x32_bf16 v[66:69], v[154:157], v[222:225], 0
	v_mfma_f32_16x16x32_bf16 v[142:145], v[110:113], v[166:169], v[142:145]
	v_mfma_f32_16x16x32_bf16 v[138:141], v[134:137], v[166:169], v[138:141]
	v_mfma_f32_16x16x32_bf16 v[118:121], v[110:113], v[174:177], v[118:121]
	v_mfma_f32_16x16x32_bf16 v[114:117], v[134:137], v[174:177], v[114:117]
	v_mfma_f32_16x16x32_bf16 v[94:97], v[110:113], v[182:185], v[94:97]
	v_mfma_f32_16x16x32_bf16 v[90:93], v[134:137], v[182:185], v[90:93]
	v_mfma_f32_16x16x32_bf16 v[78:81], v[110:113], v[226:229], v[78:81]
	v_mfma_f32_16x16x32_bf16 v[74:77], v[134:137], v[226:229], v[74:77]
	v_mfma_f32_16x16x32_bf16 v[130:133], v[150:153], v[166:169], v[130:133]
	v_mfma_f32_16x16x32_bf16 v[122:125], v[158:161], v[166:169], v[122:125]
	v_mfma_f32_16x16x32_bf16 v[102:105], v[150:153], v[174:177], v[102:105]
	v_mfma_f32_16x16x32_bf16 v[98:101], v[158:161], v[174:177], v[98:101]
	v_mfma_f32_16x16x32_bf16 v[86:89], v[150:153], v[182:185], v[86:89]
	v_mfma_f32_16x16x32_bf16 v[82:85], v[158:161], v[182:185], v[82:85]
	v_mfma_f32_16x16x32_bf16 v[70:73], v[150:153], v[226:229], v[70:73]
	v_mfma_f32_16x16x32_bf16 v[66:69], v[158:161], v[226:229], v[66:69]
	s_barrier
	s_setprio 0
	s_add_i32 s48, s51, s56
	v_lshl_add_u64 v[216:217], s[52:53], 0, v[208:209]
	s_mov_b32 m0, s48
	ds_read_b128 v[162:165], v220 offset:16384
	ds_read_b128 v[166:169], v220 offset:17408
	ds_read_b128 v[170:173], v220 offset:18432
	ds_read_b128 v[174:177], v220 offset:19456
	ds_read_b128 v[178:181], v220 offset:20480
	ds_read_b128 v[182:185], v220 offset:21504
	ds_read_b128 v[222:225], v220 offset:22528
	ds_read_b128 v[226:229], v220 offset:23552
	global_load_lds_dwordx4 v[216:217], off
	s_add_i32 m0, s48, 0x2000
	s_add_u32 s48, s52, 0xb0000
	v_lshl_add_u64 v[230:231], s[52:53], 0, v[204:205]
	s_addc_u32 s49, s53, 0
	s_add_i32 s51, s66, s56
	global_load_lds_dwordx4 v[230:231], off
	v_lshl_add_u64 v[240:241], s[48:49], 0, v[208:209]
	s_mov_b32 m0, s51
	v_lshl_add_u64 v[242:243], s[54:55], 0, v[206:207]
	global_load_lds_dwordx4 v[240:241], off
	v_lshl_add_u64 v[240:241], s[48:49], 0, v[204:205]
	s_add_i32 m0, s51, 0x2000
	s_nop 0
	global_load_lds_dwordx4 v[240:241], off
	v_lshl_add_u64 v[240:241], s[54:55], 0, v[210:211]
	s_mov_b32 m0, s57
	s_nop 0
	global_load_lds_dwordx4 v[240:241], off
	s_mov_b32 m0, s58
	s_nop 0
	global_load_lds_dwordx4 v[242:243], off
	s_waitcnt vmcnt(8)
	s_waitcnt lgkmcnt(0)
	s_setprio 1
	s_barrier
	v_mfma_f32_16x16x32_bf16 v[62:65], v[106:109], v[162:165], 0
	v_mfma_f32_16x16x32_bf16 v[58:61], v[126:129], v[162:165], 0
	v_mfma_f32_16x16x32_bf16 v[46:49], v[106:109], v[170:173], 0
	v_mfma_f32_16x16x32_bf16 v[42:45], v[126:129], v[170:173], 0
	v_mfma_f32_16x16x32_bf16 v[30:33], v[106:109], v[178:181], 0
	v_mfma_f32_16x16x32_bf16 v[26:29], v[126:129], v[178:181], 0
	v_mfma_f32_16x16x32_bf16 v[14:17], v[106:109], v[222:225], 0
	v_mfma_f32_16x16x32_bf16 v[10:13], v[126:129], v[222:225], 0
	v_mfma_f32_16x16x32_bf16 v[54:57], v[146:149], v[162:165], 0
	v_mfma_f32_16x16x32_bf16 v[50:53], v[154:157], v[162:165], 0
	v_mfma_f32_16x16x32_bf16 v[38:41], v[146:149], v[170:173], 0
	v_mfma_f32_16x16x32_bf16 v[34:37], v[154:157], v[170:173], 0
	v_mfma_f32_16x16x32_bf16 v[22:25], v[146:149], v[178:181], 0
	v_mfma_f32_16x16x32_bf16 v[18:21], v[154:157], v[178:181], 0
	v_mfma_f32_16x16x32_bf16 v[6:9], v[146:149], v[222:225], 0
	v_mfma_f32_16x16x32_bf16 v[2:5], v[154:157], v[222:225], 0
	v_mfma_f32_16x16x32_bf16 v[62:65], v[110:113], v[166:169], v[62:65]
	v_mfma_f32_16x16x32_bf16 v[58:61], v[134:137], v[166:169], v[58:61]
	v_mfma_f32_16x16x32_bf16 v[46:49], v[110:113], v[174:177], v[46:49]
	v_mfma_f32_16x16x32_bf16 v[42:45], v[134:137], v[174:177], v[42:45]
	v_mfma_f32_16x16x32_bf16 v[30:33], v[110:113], v[182:185], v[30:33]
	v_mfma_f32_16x16x32_bf16 v[26:29], v[134:137], v[182:185], v[26:29]
	v_mfma_f32_16x16x32_bf16 v[14:17], v[110:113], v[226:229], v[14:17]
	v_mfma_f32_16x16x32_bf16 v[10:13], v[134:137], v[226:229], v[10:13]
	v_mfma_f32_16x16x32_bf16 v[54:57], v[150:153], v[166:169], v[54:57]
	v_mfma_f32_16x16x32_bf16 v[50:53], v[158:161], v[166:169], v[50:53]
	v_mfma_f32_16x16x32_bf16 v[38:41], v[150:153], v[174:177], v[38:41]
	v_mfma_f32_16x16x32_bf16 v[34:37], v[158:161], v[174:177], v[34:37]
	v_mfma_f32_16x16x32_bf16 v[22:25], v[150:153], v[182:185], v[22:25]
	v_mfma_f32_16x16x32_bf16 v[18:21], v[158:161], v[182:185], v[18:21]
	v_mfma_f32_16x16x32_bf16 v[6:9], v[150:153], v[226:229], v[6:9]
	v_mfma_f32_16x16x32_bf16 v[2:5], v[158:161], v[226:229], v[2:5]
	s_barrier
	s_setprio 0
	s_add_i32 s51, 0, 0x18000
	v_add_u32_e32 v0, s51, v219
	s_add_i32 s66, 0, 0x1c000
	ds_read_b128 v[106:109], v0
	ds_read_b128 v[110:113], v0 offset:1024
	ds_read_b128 v[126:129], v0 offset:2048
	ds_read_b128 v[134:137], v0 offset:3072
	v_add_u32_e32 v0, s66, v219
	ds_read_b128 v[146:149], v0
	ds_read_b128 v[150:153], v0 offset:1024
	ds_read_b128 v[154:157], v0 offset:2048
	ds_read_b128 v[158:161], v0 offset:3072
	s_add_u32 s48, s54, 0xb0000
	s_addc_u32 s49, s55, 0
	s_mov_b32 m0, s59
	v_lshl_add_u64 v[244:245], s[48:49], 0, v[210:211]
	ds_read_b128 v[162:165], v220 offset:32768
	ds_read_b128 v[166:169], v220 offset:33792
	ds_read_b128 v[170:173], v220 offset:34816
	ds_read_b128 v[174:177], v220 offset:35840
	ds_read_b128 v[178:181], v220 offset:36864
	ds_read_b128 v[182:185], v220 offset:37888
	ds_read_b128 v[222:225], v220 offset:38912
	ds_read_b128 v[226:229], v220 offset:39936
	global_load_lds_dwordx4 v[244:245], off
	v_lshl_add_u64 v[244:245], s[48:49], 0, v[206:207]
	s_mov_b32 m0, s60
	s_nop 0
	global_load_lds_dwordx4 v[244:245], off
	s_waitcnt vmcnt(8)
	s_waitcnt lgkmcnt(0)
	s_setprio 1
	s_barrier
	v_mfma_f32_16x16x32_bf16 v[142:145], v[106:109], v[162:165], v[142:145]
	v_mfma_f32_16x16x32_bf16 v[138:141], v[126:129], v[162:165], v[138:141]
	v_mfma_f32_16x16x32_bf16 v[118:121], v[106:109], v[170:173], v[118:121]
	v_mfma_f32_16x16x32_bf16 v[114:117], v[126:129], v[170:173], v[114:117]
	v_mfma_f32_16x16x32_bf16 v[94:97], v[106:109], v[178:181], v[94:97]
	v_mfma_f32_16x16x32_bf16 v[90:93], v[126:129], v[178:181], v[90:93]
	v_mfma_f32_16x16x32_bf16 v[78:81], v[106:109], v[222:225], v[78:81]
	v_mfma_f32_16x16x32_bf16 v[74:77], v[126:129], v[222:225], v[74:77]
	v_mfma_f32_16x16x32_bf16 v[130:133], v[146:149], v[162:165], v[130:133]
	v_mfma_f32_16x16x32_bf16 v[122:125], v[154:157], v[162:165], v[122:125]
	v_mfma_f32_16x16x32_bf16 v[102:105], v[146:149], v[170:173], v[102:105]
	v_mfma_f32_16x16x32_bf16 v[98:101], v[154:157], v[170:173], v[98:101]
	v_mfma_f32_16x16x32_bf16 v[86:89], v[146:149], v[178:181], v[86:89]
	v_mfma_f32_16x16x32_bf16 v[82:85], v[154:157], v[178:181], v[82:85]
	v_mfma_f32_16x16x32_bf16 v[70:73], v[146:149], v[222:225], v[70:73]
	v_mfma_f32_16x16x32_bf16 v[66:69], v[154:157], v[222:225], v[66:69]
	v_mfma_f32_16x16x32_bf16 v[142:145], v[110:113], v[166:169], v[142:145]
	v_mfma_f32_16x16x32_bf16 v[138:141], v[134:137], v[166:169], v[138:141]
	v_mfma_f32_16x16x32_bf16 v[118:121], v[110:113], v[174:177], v[118:121]
	v_mfma_f32_16x16x32_bf16 v[114:117], v[134:137], v[174:177], v[114:117]
	v_mfma_f32_16x16x32_bf16 v[94:97], v[110:113], v[182:185], v[94:97]
	v_mfma_f32_16x16x32_bf16 v[90:93], v[134:137], v[182:185], v[90:93]
	v_mfma_f32_16x16x32_bf16 v[78:81], v[110:113], v[226:229], v[78:81]
	v_mfma_f32_16x16x32_bf16 v[74:77], v[134:137], v[226:229], v[74:77]
	v_mfma_f32_16x16x32_bf16 v[130:133], v[150:153], v[166:169], v[130:133]
	v_mfma_f32_16x16x32_bf16 v[122:125], v[158:161], v[166:169], v[122:125]
	v_mfma_f32_16x16x32_bf16 v[102:105], v[150:153], v[174:177], v[102:105]
	v_mfma_f32_16x16x32_bf16 v[98:101], v[158:161], v[174:177], v[98:101]
	v_mfma_f32_16x16x32_bf16 v[86:89], v[150:153], v[182:185], v[86:89]
	v_mfma_f32_16x16x32_bf16 v[82:85], v[158:161], v[182:185], v[82:85]
	v_mfma_f32_16x16x32_bf16 v[70:73], v[150:153], v[226:229], v[70:73]
	v_mfma_f32_16x16x32_bf16 v[66:69], v[158:161], v[226:229], v[66:69]
	s_barrier
	s_setprio 0
	s_add_i32 s48, s51, s56
	v_lshl_add_u64 v[216:217], v[216:217], 0, s[16:17]
	s_mov_b32 m0, s48
	ds_read_b128 v[162:165], v220 offset:49152
	ds_read_b128 v[166:169], v220 offset:50176
	ds_read_b128 v[170:173], v220 offset:51200
	ds_read_b128 v[174:177], v220 offset:52224
	ds_read_b128 v[178:181], v220 offset:53248
	ds_read_b128 v[182:185], v220 offset:54272
	ds_read_b128 v[222:225], v220 offset:55296
	ds_read_b128 v[226:229], v220 offset:56320
	global_load_lds_dwordx4 v[216:217], off
	s_add_i32 m0, s48, 0x2000
	s_add_u32 s48, s52, 0xb0080
	v_lshl_add_u64 v[216:217], v[230:231], 0, s[16:17]
	s_addc_u32 s49, s53, 0
	s_add_i32 s51, s66, s56
	global_load_lds_dwordx4 v[216:217], off
	v_lshl_add_u64 v[216:217], s[48:49], 0, v[208:209]
	s_mov_b32 m0, s51
	s_nop 0
	global_load_lds_dwordx4 v[216:217], off
	v_lshl_add_u64 v[216:217], s[48:49], 0, v[204:205]
	s_add_i32 m0, s51, 0x2000
	s_nop 0
	global_load_lds_dwordx4 v[216:217], off
	v_lshl_add_u64 v[216:217], v[240:241], 0, s[16:17]
	s_mov_b32 m0, s63
	s_nop 0
	global_load_lds_dwordx4 v[216:217], off
	v_lshl_add_u64 v[216:217], v[242:243], 0, s[16:17]
	s_mov_b32 m0, s64
	s_nop 0
	global_load_lds_dwordx4 v[216:217], off
	s_waitcnt vmcnt(8)
	s_waitcnt lgkmcnt(0)
	s_setprio 1
	s_barrier
	v_mfma_f32_16x16x32_bf16 v[62:65], v[106:109], v[162:165], v[62:65]
	v_mfma_f32_16x16x32_bf16 v[58:61], v[126:129], v[162:165], v[58:61]
	v_mfma_f32_16x16x32_bf16 v[46:49], v[106:109], v[170:173], v[46:49]
	v_mfma_f32_16x16x32_bf16 v[42:45], v[126:129], v[170:173], v[42:45]
	v_mfma_f32_16x16x32_bf16 v[30:33], v[106:109], v[178:181], v[30:33]
	v_mfma_f32_16x16x32_bf16 v[26:29], v[126:129], v[178:181], v[26:29]
	v_mfma_f32_16x16x32_bf16 v[14:17], v[106:109], v[222:225], v[14:17]
	v_mfma_f32_16x16x32_bf16 v[10:13], v[126:129], v[222:225], v[10:13]
	v_mfma_f32_16x16x32_bf16 v[54:57], v[146:149], v[162:165], v[54:57]
	v_mfma_f32_16x16x32_bf16 v[50:53], v[154:157], v[162:165], v[50:53]
	v_mfma_f32_16x16x32_bf16 v[38:41], v[146:149], v[170:173], v[38:41]
	v_mfma_f32_16x16x32_bf16 v[34:37], v[154:157], v[170:173], v[34:37]
	v_mfma_f32_16x16x32_bf16 v[22:25], v[146:149], v[178:181], v[22:25]
	v_mfma_f32_16x16x32_bf16 v[18:21], v[154:157], v[178:181], v[18:21]
	v_mfma_f32_16x16x32_bf16 v[6:9], v[146:149], v[222:225], v[6:9]
	v_mfma_f32_16x16x32_bf16 v[2:5], v[154:157], v[222:225], v[2:5]
	v_mfma_f32_16x16x32_bf16 v[62:65], v[110:113], v[166:169], v[62:65]
	v_mfma_f32_16x16x32_bf16 v[58:61], v[134:137], v[166:169], v[58:61]
	v_mfma_f32_16x16x32_bf16 v[46:49], v[110:113], v[174:177], v[46:49]
	v_mfma_f32_16x16x32_bf16 v[42:45], v[134:137], v[174:177], v[42:45]
	v_mfma_f32_16x16x32_bf16 v[30:33], v[110:113], v[182:185], v[30:33]
	v_mfma_f32_16x16x32_bf16 v[26:29], v[134:137], v[182:185], v[26:29]
	v_mfma_f32_16x16x32_bf16 v[14:17], v[110:113], v[226:229], v[14:17]
	v_mfma_f32_16x16x32_bf16 v[10:13], v[134:137], v[226:229], v[10:13]
	v_mfma_f32_16x16x32_bf16 v[54:57], v[150:153], v[166:169], v[54:57]
	v_mfma_f32_16x16x32_bf16 v[50:53], v[158:161], v[166:169], v[50:53]
	v_mfma_f32_16x16x32_bf16 v[38:41], v[150:153], v[174:177], v[38:41]
	v_mfma_f32_16x16x32_bf16 v[34:37], v[158:161], v[174:177], v[34:37]
	v_mfma_f32_16x16x32_bf16 v[22:25], v[150:153], v[182:185], v[22:25]
	v_mfma_f32_16x16x32_bf16 v[18:21], v[158:161], v[182:185], v[18:21]
	v_mfma_f32_16x16x32_bf16 v[6:9], v[150:153], v[226:229], v[6:9]
	v_mfma_f32_16x16x32_bf16 v[2:5], v[158:161], v[226:229], v[2:5]
	s_barrier
	s_setprio 0
	s_add_i32 s19, s19, 2
	s_add_u32 s7, s7, 0x100
	s_addc_u32 s18, s18, 0
	s_cmp_gt_u32 s19, 41
	s_mov_b64 s[48:49], s[0:1]
.LBB0_320:
	s_add_u32 s0, s48, 0x100
	s_addc_u32 s1, s49, 0
	s_add_i32 s51, 0, 0x10000
	s_cmp_eq_u32 s19, 40
	s_cselect_b32 s55, s45, s1
	s_cselect_b32 s54, s44, s0
	v_add_u32_e32 v0, s51, v219
	s_cselect_b32 s53, s47, s18
	s_cselect_b32 s52, s46, s7
	s_add_i32 s66, 0, 0x14000
	ds_read_b128 v[106:109], v0
	ds_read_b128 v[110:113], v0 offset:1024
	ds_read_b128 v[126:129], v0 offset:2048
	ds_read_b128 v[134:137], v0 offset:3072
	v_add_u32_e32 v0, s66, v219
	ds_read_b128 v[146:149], v0
	ds_read_b128 v[150:153], v0 offset:1024
	ds_read_b128 v[154:157], v0 offset:2048
	ds_read_b128 v[158:161], v0 offset:3072
	v_lshl_add_u64 v[216:217], s[48:49], 0, v[212:213]
	s_add_i32 m0, s57, 0xc000
	ds_read_b128 v[162:165], v220
	ds_read_b128 v[166:169], v220 offset:1024
	ds_read_b128 v[170:173], v220 offset:2048
	ds_read_b128 v[174:177], v220 offset:3072
	ds_read_b128 v[178:181], v220 offset:4096
	ds_read_b128 v[182:185], v220 offset:5120
	ds_read_b128 v[222:225], v220 offset:6144
	ds_read_b128 v[226:229], v220 offset:7168
	global_load_lds_dwordx4 v[216:217], off
	v_lshl_add_u64 v[216:217], s[48:49], 0, v[214:215]
	s_add_i32 m0, s57, 0xe000
	s_nop 0
	global_load_lds_dwordx4 v[216:217], off
	s_waitcnt vmcnt(8)
	s_waitcnt lgkmcnt(0)
	s_setprio 1
	s_barrier
	v_mfma_f32_16x16x32_bf16 v[142:145], v[106:109], v[162:165], v[142:145]
	v_mfma_f32_16x16x32_bf16 v[138:141], v[126:129], v[162:165], v[138:141]
	v_mfma_f32_16x16x32_bf16 v[118:121], v[106:109], v[170:173], v[118:121]
	v_mfma_f32_16x16x32_bf16 v[114:117], v[126:129], v[170:173], v[114:117]
	v_mfma_f32_16x16x32_bf16 v[94:97], v[106:109], v[178:181], v[94:97]
	v_mfma_f32_16x16x32_bf16 v[90:93], v[126:129], v[178:181], v[90:93]
	v_mfma_f32_16x16x32_bf16 v[78:81], v[106:109], v[222:225], v[78:81]
	v_mfma_f32_16x16x32_bf16 v[74:77], v[126:129], v[222:225], v[74:77]
	v_mfma_f32_16x16x32_bf16 v[130:133], v[146:149], v[162:165], v[130:133]
	v_mfma_f32_16x16x32_bf16 v[122:125], v[154:157], v[162:165], v[122:125]
	v_mfma_f32_16x16x32_bf16 v[102:105], v[146:149], v[170:173], v[102:105]
	v_mfma_f32_16x16x32_bf16 v[98:101], v[154:157], v[170:173], v[98:101]
	v_mfma_f32_16x16x32_bf16 v[86:89], v[146:149], v[178:181], v[86:89]
	v_mfma_f32_16x16x32_bf16 v[82:85], v[154:157], v[178:181], v[82:85]
	v_mfma_f32_16x16x32_bf16 v[70:73], v[146:149], v[222:225], v[70:73]
	v_mfma_f32_16x16x32_bf16 v[66:69], v[154:157], v[222:225], v[66:69]
	v_mfma_f32_16x16x32_bf16 v[142:145], v[110:113], v[166:169], v[142:145]
	v_mfma_f32_16x16x32_bf16 v[138:141], v[134:137], v[166:169], v[138:141]
	v_mfma_f32_16x16x32_bf16 v[118:121], v[110:113], v[174:177], v[118:121]
	v_mfma_f32_16x16x32_bf16 v[114:117], v[134:137], v[174:177], v[114:117]
	v_mfma_f32_16x16x32_bf16 v[94:97], v[110:113], v[182:185], v[94:97]
	v_mfma_f32_16x16x32_bf16 v[90:93], v[134:137], v[182:185], v[90:93]
	v_mfma_f32_16x16x32_bf16 v[78:81], v[110:113], v[226:229], v[78:81]
	v_mfma_f32_16x16x32_bf16 v[74:77], v[134:137], v[226:229], v[74:77]
	v_mfma_f32_16x16x32_bf16 v[130:133], v[150:153], v[166:169], v[130:133]
	v_mfma_f32_16x16x32_bf16 v[122:125], v[158:161], v[166:169], v[122:125]
	v_mfma_f32_16x16x32_bf16 v[102:105], v[150:153], v[174:177], v[102:105]
	v_mfma_f32_16x16x32_bf16 v[98:101], v[158:161], v[174:177], v[98:101]
	v_mfma_f32_16x16x32_bf16 v[86:89], v[150:153], v[182:185], v[86:89]
	v_mfma_f32_16x16x32_bf16 v[82:85], v[158:161], v[182:185], v[82:85]
	v_mfma_f32_16x16x32_bf16 v[70:73], v[150:153], v[226:229], v[70:73]
	v_mfma_f32_16x16x32_bf16 v[66:69], v[158:161], v[226:229], v[66:69]
	s_barrier
	s_setprio 0
	s_add_i32 s48, s51, s56
	v_lshl_add_u64 v[216:217], s[52:53], 0, v[208:209]
	s_mov_b32 m0, s48
	ds_read_b128 v[162:165], v220 offset:16384
	ds_read_b128 v[166:169], v220 offset:17408
	ds_read_b128 v[170:173], v220 offset:18432
	ds_read_b128 v[174:177], v220 offset:19456
	ds_read_b128 v[178:181], v220 offset:20480
	ds_read_b128 v[182:185], v220 offset:21504
	ds_read_b128 v[222:225], v220 offset:22528
	ds_read_b128 v[226:229], v220 offset:23552
	global_load_lds_dwordx4 v[216:217], off
	s_add_i32 m0, s48, 0x2000
	s_add_u32 s48, s52, 0xb0000
	v_lshl_add_u64 v[230:231], s[52:53], 0, v[204:205]
	s_addc_u32 s49, s53, 0
	s_add_i32 s51, s66, s56
	global_load_lds_dwordx4 v[230:231], off
	v_lshl_add_u64 v[240:241], s[48:49], 0, v[208:209]
	s_mov_b32 m0, s51
	v_lshl_add_u64 v[242:243], s[54:55], 0, v[206:207]
	global_load_lds_dwordx4 v[240:241], off
	v_lshl_add_u64 v[240:241], s[48:49], 0, v[204:205]
	s_add_i32 m0, s51, 0x2000
	s_nop 0
	global_load_lds_dwordx4 v[240:241], off
	v_lshl_add_u64 v[240:241], s[54:55], 0, v[210:211]
	s_mov_b32 m0, s57
	s_nop 0
	global_load_lds_dwordx4 v[240:241], off
	s_mov_b32 m0, s58
	s_nop 0
	global_load_lds_dwordx4 v[242:243], off
	s_waitcnt vmcnt(8)
	s_waitcnt lgkmcnt(0)
	s_setprio 1
	s_barrier
	v_mfma_f32_16x16x32_bf16 v[62:65], v[106:109], v[162:165], v[62:65]
	v_mfma_f32_16x16x32_bf16 v[58:61], v[126:129], v[162:165], v[58:61]
	v_mfma_f32_16x16x32_bf16 v[46:49], v[106:109], v[170:173], v[46:49]
	v_mfma_f32_16x16x32_bf16 v[42:45], v[126:129], v[170:173], v[42:45]
	v_mfma_f32_16x16x32_bf16 v[30:33], v[106:109], v[178:181], v[30:33]
	v_mfma_f32_16x16x32_bf16 v[26:29], v[126:129], v[178:181], v[26:29]
	v_mfma_f32_16x16x32_bf16 v[14:17], v[106:109], v[222:225], v[14:17]
	v_mfma_f32_16x16x32_bf16 v[10:13], v[126:129], v[222:225], v[10:13]
	v_mfma_f32_16x16x32_bf16 v[54:57], v[146:149], v[162:165], v[54:57]
	v_mfma_f32_16x16x32_bf16 v[50:53], v[154:157], v[162:165], v[50:53]
	v_mfma_f32_16x16x32_bf16 v[38:41], v[146:149], v[170:173], v[38:41]
	v_mfma_f32_16x16x32_bf16 v[34:37], v[154:157], v[170:173], v[34:37]
	v_mfma_f32_16x16x32_bf16 v[22:25], v[146:149], v[178:181], v[22:25]
	v_mfma_f32_16x16x32_bf16 v[18:21], v[154:157], v[178:181], v[18:21]
	v_mfma_f32_16x16x32_bf16 v[6:9], v[146:149], v[222:225], v[6:9]
	v_mfma_f32_16x16x32_bf16 v[2:5], v[154:157], v[222:225], v[2:5]
	v_mfma_f32_16x16x32_bf16 v[62:65], v[110:113], v[166:169], v[62:65]
	v_mfma_f32_16x16x32_bf16 v[58:61], v[134:137], v[166:169], v[58:61]
	v_mfma_f32_16x16x32_bf16 v[46:49], v[110:113], v[174:177], v[46:49]
	v_mfma_f32_16x16x32_bf16 v[42:45], v[134:137], v[174:177], v[42:45]
	v_mfma_f32_16x16x32_bf16 v[30:33], v[110:113], v[182:185], v[30:33]
	v_mfma_f32_16x16x32_bf16 v[26:29], v[134:137], v[182:185], v[26:29]
	v_mfma_f32_16x16x32_bf16 v[14:17], v[110:113], v[226:229], v[14:17]
	v_mfma_f32_16x16x32_bf16 v[10:13], v[134:137], v[226:229], v[10:13]
	v_mfma_f32_16x16x32_bf16 v[54:57], v[150:153], v[166:169], v[54:57]
	v_mfma_f32_16x16x32_bf16 v[50:53], v[158:161], v[166:169], v[50:53]
	v_mfma_f32_16x16x32_bf16 v[38:41], v[150:153], v[174:177], v[38:41]
	v_mfma_f32_16x16x32_bf16 v[34:37], v[158:161], v[174:177], v[34:37]
	v_mfma_f32_16x16x32_bf16 v[22:25], v[150:153], v[182:185], v[22:25]
	v_mfma_f32_16x16x32_bf16 v[18:21], v[158:161], v[182:185], v[18:21]
	v_mfma_f32_16x16x32_bf16 v[6:9], v[150:153], v[226:229], v[6:9]
	v_mfma_f32_16x16x32_bf16 v[2:5], v[158:161], v[226:229], v[2:5]
	s_barrier
	s_setprio 0
	s_add_i32 s51, 0, 0x18000
	v_add_u32_e32 v0, s51, v219
	s_add_i32 s66, 0, 0x1c000
	ds_read_b128 v[106:109], v0
	ds_read_b128 v[110:113], v0 offset:1024
	ds_read_b128 v[126:129], v0 offset:2048
	ds_read_b128 v[134:137], v0 offset:3072
	v_add_u32_e32 v0, s66, v219
	ds_read_b128 v[146:149], v0
	ds_read_b128 v[150:153], v0 offset:1024
	ds_read_b128 v[154:157], v0 offset:2048
	ds_read_b128 v[158:161], v0 offset:3072
	s_add_u32 s48, s54, 0xb0000
	s_addc_u32 s49, s55, 0
	s_mov_b32 m0, s59
	v_lshl_add_u64 v[244:245], s[48:49], 0, v[210:211]
	ds_read_b128 v[162:165], v220 offset:32768
	ds_read_b128 v[166:169], v220 offset:33792
	ds_read_b128 v[170:173], v220 offset:34816
	ds_read_b128 v[174:177], v220 offset:35840
	ds_read_b128 v[178:181], v220 offset:36864
	ds_read_b128 v[182:185], v220 offset:37888
	ds_read_b128 v[222:225], v220 offset:38912
	ds_read_b128 v[226:229], v220 offset:39936
	global_load_lds_dwordx4 v[244:245], off
	v_lshl_add_u64 v[244:245], s[48:49], 0, v[206:207]
	s_mov_b32 m0, s60
	s_nop 0
	global_load_lds_dwordx4 v[244:245], off
	s_waitcnt vmcnt(8)
	s_waitcnt lgkmcnt(0)
	s_setprio 1
	s_barrier
	v_mfma_f32_16x16x32_bf16 v[142:145], v[106:109], v[162:165], v[142:145]
	v_mfma_f32_16x16x32_bf16 v[138:141], v[126:129], v[162:165], v[138:141]
	v_mfma_f32_16x16x32_bf16 v[118:121], v[106:109], v[170:173], v[118:121]
	v_mfma_f32_16x16x32_bf16 v[114:117], v[126:129], v[170:173], v[114:117]
	v_mfma_f32_16x16x32_bf16 v[94:97], v[106:109], v[178:181], v[94:97]
	v_mfma_f32_16x16x32_bf16 v[90:93], v[126:129], v[178:181], v[90:93]
	v_mfma_f32_16x16x32_bf16 v[78:81], v[106:109], v[222:225], v[78:81]
	v_mfma_f32_16x16x32_bf16 v[74:77], v[126:129], v[222:225], v[74:77]
	v_mfma_f32_16x16x32_bf16 v[130:133], v[146:149], v[162:165], v[130:133]
	v_mfma_f32_16x16x32_bf16 v[122:125], v[154:157], v[162:165], v[122:125]
	v_mfma_f32_16x16x32_bf16 v[102:105], v[146:149], v[170:173], v[102:105]
	v_mfma_f32_16x16x32_bf16 v[98:101], v[154:157], v[170:173], v[98:101]
	v_mfma_f32_16x16x32_bf16 v[86:89], v[146:149], v[178:181], v[86:89]
	v_mfma_f32_16x16x32_bf16 v[82:85], v[154:157], v[178:181], v[82:85]
	v_mfma_f32_16x16x32_bf16 v[70:73], v[146:149], v[222:225], v[70:73]
	v_mfma_f32_16x16x32_bf16 v[66:69], v[154:157], v[222:225], v[66:69]
	v_mfma_f32_16x16x32_bf16 v[142:145], v[110:113], v[166:169], v[142:145]
	v_mfma_f32_16x16x32_bf16 v[138:141], v[134:137], v[166:169], v[138:141]
	v_mfma_f32_16x16x32_bf16 v[118:121], v[110:113], v[174:177], v[118:121]
	v_mfma_f32_16x16x32_bf16 v[114:117], v[134:137], v[174:177], v[114:117]
	v_mfma_f32_16x16x32_bf16 v[94:97], v[110:113], v[182:185], v[94:97]
	v_mfma_f32_16x16x32_bf16 v[90:93], v[134:137], v[182:185], v[90:93]
	v_mfma_f32_16x16x32_bf16 v[78:81], v[110:113], v[226:229], v[78:81]
	v_mfma_f32_16x16x32_bf16 v[74:77], v[134:137], v[226:229], v[74:77]
	v_mfma_f32_16x16x32_bf16 v[130:133], v[150:153], v[166:169], v[130:133]
	v_mfma_f32_16x16x32_bf16 v[122:125], v[158:161], v[166:169], v[122:125]
	v_mfma_f32_16x16x32_bf16 v[102:105], v[150:153], v[174:177], v[102:105]
	v_mfma_f32_16x16x32_bf16 v[98:101], v[158:161], v[174:177], v[98:101]
	v_mfma_f32_16x16x32_bf16 v[86:89], v[150:153], v[182:185], v[86:89]
	v_mfma_f32_16x16x32_bf16 v[82:85], v[158:161], v[182:185], v[82:85]
	v_mfma_f32_16x16x32_bf16 v[70:73], v[150:153], v[226:229], v[70:73]
	v_mfma_f32_16x16x32_bf16 v[66:69], v[158:161], v[226:229], v[66:69]
	s_barrier
	s_setprio 0
	s_add_i32 s48, s51, s56
	v_lshl_add_u64 v[216:217], v[216:217], 0, s[16:17]
	s_mov_b32 m0, s48
	ds_read_b128 v[162:165], v220 offset:49152
	ds_read_b128 v[166:169], v220 offset:50176
	ds_read_b128 v[170:173], v220 offset:51200
	ds_read_b128 v[174:177], v220 offset:52224
	ds_read_b128 v[178:181], v220 offset:53248
	ds_read_b128 v[182:185], v220 offset:54272
	ds_read_b128 v[222:225], v220 offset:55296
	ds_read_b128 v[226:229], v220 offset:56320
	global_load_lds_dwordx4 v[216:217], off
	s_add_i32 m0, s48, 0x2000
	s_add_u32 s48, s52, 0xb0080
	v_lshl_add_u64 v[216:217], v[230:231], 0, s[16:17]
	s_addc_u32 s49, s53, 0
	s_add_i32 s51, s66, s56
	global_load_lds_dwordx4 v[216:217], off
	v_lshl_add_u64 v[216:217], s[48:49], 0, v[208:209]
	s_mov_b32 m0, s51
	s_nop 0
	global_load_lds_dwordx4 v[216:217], off
	v_lshl_add_u64 v[216:217], s[48:49], 0, v[204:205]
	s_add_i32 m0, s51, 0x2000
	s_nop 0
	global_load_lds_dwordx4 v[216:217], off
	v_lshl_add_u64 v[216:217], v[240:241], 0, s[16:17]
	s_mov_b32 m0, s63
	s_nop 0
	global_load_lds_dwordx4 v[216:217], off
	v_lshl_add_u64 v[216:217], v[242:243], 0, s[16:17]
	s_mov_b32 m0, s64
	s_nop 0
	global_load_lds_dwordx4 v[216:217], off
	s_waitcnt vmcnt(8)
	s_waitcnt lgkmcnt(0)
	s_setprio 1
	s_barrier
	v_mfma_f32_16x16x32_bf16 v[62:65], v[106:109], v[162:165], v[62:65]
	v_mfma_f32_16x16x32_bf16 v[58:61], v[126:129], v[162:165], v[58:61]
	v_mfma_f32_16x16x32_bf16 v[46:49], v[106:109], v[170:173], v[46:49]
	v_mfma_f32_16x16x32_bf16 v[42:45], v[126:129], v[170:173], v[42:45]
	v_mfma_f32_16x16x32_bf16 v[30:33], v[106:109], v[178:181], v[30:33]
	v_mfma_f32_16x16x32_bf16 v[26:29], v[126:129], v[178:181], v[26:29]
	v_mfma_f32_16x16x32_bf16 v[14:17], v[106:109], v[222:225], v[14:17]
	v_mfma_f32_16x16x32_bf16 v[10:13], v[126:129], v[222:225], v[10:13]
	v_mfma_f32_16x16x32_bf16 v[54:57], v[146:149], v[162:165], v[54:57]
	v_mfma_f32_16x16x32_bf16 v[50:53], v[154:157], v[162:165], v[50:53]
	v_mfma_f32_16x16x32_bf16 v[38:41], v[146:149], v[170:173], v[38:41]
	v_mfma_f32_16x16x32_bf16 v[34:37], v[154:157], v[170:173], v[34:37]
	v_mfma_f32_16x16x32_bf16 v[22:25], v[146:149], v[178:181], v[22:25]
	v_mfma_f32_16x16x32_bf16 v[18:21], v[154:157], v[178:181], v[18:21]
	v_mfma_f32_16x16x32_bf16 v[6:9], v[146:149], v[222:225], v[6:9]
	v_mfma_f32_16x16x32_bf16 v[2:5], v[154:157], v[222:225], v[2:5]
	v_mfma_f32_16x16x32_bf16 v[62:65], v[110:113], v[166:169], v[62:65]
	v_mfma_f32_16x16x32_bf16 v[58:61], v[134:137], v[166:169], v[58:61]
	v_mfma_f32_16x16x32_bf16 v[46:49], v[110:113], v[174:177], v[46:49]
	v_mfma_f32_16x16x32_bf16 v[42:45], v[134:137], v[174:177], v[42:45]
	v_mfma_f32_16x16x32_bf16 v[30:33], v[110:113], v[182:185], v[30:33]
	v_mfma_f32_16x16x32_bf16 v[26:29], v[134:137], v[182:185], v[26:29]
	v_mfma_f32_16x16x32_bf16 v[14:17], v[110:113], v[226:229], v[14:17]
	v_mfma_f32_16x16x32_bf16 v[10:13], v[134:137], v[226:229], v[10:13]
	v_mfma_f32_16x16x32_bf16 v[54:57], v[150:153], v[166:169], v[54:57]
	v_mfma_f32_16x16x32_bf16 v[50:53], v[158:161], v[166:169], v[50:53]
	v_mfma_f32_16x16x32_bf16 v[38:41], v[150:153], v[174:177], v[38:41]
	v_mfma_f32_16x16x32_bf16 v[34:37], v[158:161], v[174:177], v[34:37]
	v_mfma_f32_16x16x32_bf16 v[22:25], v[150:153], v[182:185], v[22:25]
	v_mfma_f32_16x16x32_bf16 v[18:21], v[158:161], v[182:185], v[18:21]
	v_mfma_f32_16x16x32_bf16 v[6:9], v[150:153], v[226:229], v[6:9]
	v_mfma_f32_16x16x32_bf16 v[2:5], v[158:161], v[226:229], v[2:5]
	s_barrier
	s_setprio 0
	s_add_i32 s19, s19, 2
	s_add_u32 s7, s7, 0x100
	s_addc_u32 s18, s18, 0
	s_cmp_gt_u32 s19, 41
	s_mov_b64 s[48:49], s[0:1]
	s_cbranch_scc0 .LBB0_320
	s_and_b64 vcc, exec, s[40:41]
	s_cbranch_vccz .LBB0_323
	s_barrier

.Lrb2_skip:
	s_add_u32 s54, s52, 0xfffc0080
	s_addc_u32 s55, s53, -1
	s_add_i32 s67, 0, 0x10000
	s_cmp_eq_u32 s66, 12
	s_cselect_b32 s57, s19, s55
	s_cselect_b32 s56, s45, s54
	v_add_u32_e32 v0, s67, v158
	s_cselect_b32 s55, s41, s65
	s_cselect_b32 s54, s51, s64
	s_add_i32 s70, 0, 0x14000
	ds_read_b128 v[142:145], v0
	ds_read_b128 v[146:149], v0 offset:1024
	ds_read_b128 v[150:153], v0 offset:2048
	ds_read_b128 v[160:163], v0 offset:3072
	v_add_u32_e32 v0, s70, v158
	ds_read_b128 v[164:167], v0
	ds_read_b128 v[168:171], v0 offset:1024
	ds_read_b128 v[172:175], v0 offset:2048
	ds_read_b128 v[176:179], v0 offset:3072
	s_add_i32 m0, s59, 0xc000
	ds_read_b128 v[180:183], v159
	ds_read_b128 v[204:207], v159 offset:1024
	ds_read_b128 v[208:211], v159 offset:2048
	ds_read_b128 v[212:215], v159 offset:3072
	ds_read_b128 v[216:219], v159 offset:4096
	ds_read_b128 v[220:223], v159 offset:5120
	ds_read_b128 v[224:227], v159 offset:6144
	ds_read_b128 v[228:231], v159 offset:7168
	global_load_lds_dwordx4 v138, s[52:53]
	s_add_i32 m0, s59, 0xe000
	s_nop 0
	global_load_lds_dwordx4 v140, s[52:53]
	s_waitcnt vmcnt(8)
	s_waitcnt lgkmcnt(0)
	s_setprio 1
	s_barrier
	v_mfma_f32_16x16x32_bf16 v[126:129], v[142:145], v[180:183], 0
	v_mfma_f32_16x16x32_bf16 v[122:125], v[150:153], v[180:183], 0
	v_mfma_f32_16x16x32_bf16 v[110:113], v[142:145], v[208:211], 0
	v_mfma_f32_16x16x32_bf16 v[106:109], v[150:153], v[208:211], 0
	v_mfma_f32_16x16x32_bf16 v[94:97], v[142:145], v[216:219], 0
	v_mfma_f32_16x16x32_bf16 v[90:93], v[150:153], v[216:219], 0
	v_mfma_f32_16x16x32_bf16 v[78:81], v[142:145], v[224:227], 0
	v_mfma_f32_16x16x32_bf16 v[74:77], v[150:153], v[224:227], 0
	v_mfma_f32_16x16x32_bf16 v[118:121], v[164:167], v[180:183], 0
	v_mfma_f32_16x16x32_bf16 v[114:117], v[172:175], v[180:183], 0
	v_mfma_f32_16x16x32_bf16 v[102:105], v[164:167], v[208:211], 0
	v_mfma_f32_16x16x32_bf16 v[98:101], v[172:175], v[208:211], 0
	v_mfma_f32_16x16x32_bf16 v[86:89], v[164:167], v[216:219], 0
	v_mfma_f32_16x16x32_bf16 v[82:85], v[172:175], v[216:219], 0
	v_mfma_f32_16x16x32_bf16 v[70:73], v[164:167], v[224:227], 0
	v_mfma_f32_16x16x32_bf16 v[66:69], v[172:175], v[224:227], 0
	v_mfma_f32_16x16x32_bf16 v[126:129], v[146:149], v[204:207], v[126:129]
	v_mfma_f32_16x16x32_bf16 v[122:125], v[160:163], v[204:207], v[122:125]
	v_mfma_f32_16x16x32_bf16 v[110:113], v[146:149], v[212:215], v[110:113]
	v_mfma_f32_16x16x32_bf16 v[106:109], v[160:163], v[212:215], v[106:109]
	v_mfma_f32_16x16x32_bf16 v[94:97], v[146:149], v[220:223], v[94:97]
	v_mfma_f32_16x16x32_bf16 v[90:93], v[160:163], v[220:223], v[90:93]
	v_mfma_f32_16x16x32_bf16 v[78:81], v[146:149], v[228:231], v[78:81]
	v_mfma_f32_16x16x32_bf16 v[74:77], v[160:163], v[228:231], v[74:77]
	v_mfma_f32_16x16x32_bf16 v[118:121], v[168:171], v[204:207], v[118:121]
	v_mfma_f32_16x16x32_bf16 v[114:117], v[176:179], v[204:207], v[114:117]
	v_mfma_f32_16x16x32_bf16 v[102:105], v[168:171], v[212:215], v[102:105]
	v_mfma_f32_16x16x32_bf16 v[98:101], v[176:179], v[212:215], v[98:101]
	v_mfma_f32_16x16x32_bf16 v[86:89], v[168:171], v[220:223], v[86:89]
	v_mfma_f32_16x16x32_bf16 v[82:85], v[176:179], v[220:223], v[82:85]
	v_mfma_f32_16x16x32_bf16 v[70:73], v[168:171], v[228:231], v[70:73]
	v_mfma_f32_16x16x32_bf16 v[66:69], v[176:179], v[228:231], v[66:69]
	s_barrier
	s_setprio 0
	s_add_i32 s67, s67, s58
	s_mov_b32 m0, s67
	ds_read_b128 v[180:183], v159 offset:16384
	ds_read_b128 v[204:207], v159 offset:17408
	ds_read_b128 v[208:211], v159 offset:18432
	ds_read_b128 v[212:215], v159 offset:19456
	ds_read_b128 v[216:219], v159 offset:20480
	ds_read_b128 v[220:223], v159 offset:21504
	ds_read_b128 v[224:227], v159 offset:22528
	ds_read_b128 v[228:231], v159 offset:23552
	global_load_lds_dwordx4 v134, s[54:55]
	s_add_i32 m0, s67, 0x2000
	s_add_u32 s68, s54, 0x40000
	s_addc_u32 s69, s55, 0
	s_add_i32 s67, s70, s58
	global_load_lds_dwordx4 v130, s[54:55]
	s_mov_b32 m0, s67
	s_nop 0
	global_load_lds_dwordx4 v134, s[68:69]
	s_add_i32 m0, s67, 0x2000
	s_nop 0
	global_load_lds_dwordx4 v130, s[68:69]
	s_mov_b32 m0, s59
	s_nop 0
	global_load_lds_dwordx4 v136, s[56:57]
	s_mov_b32 m0, s60
	s_nop 0
	global_load_lds_dwordx4 v132, s[56:57]
	s_waitcnt vmcnt(8)
	s_waitcnt lgkmcnt(0)
	s_setprio 1
	s_barrier
	v_mfma_f32_16x16x32_bf16 v[62:65], v[142:145], v[180:183], 0
	v_mfma_f32_16x16x32_bf16 v[58:61], v[150:153], v[180:183], 0
	v_mfma_f32_16x16x32_bf16 v[46:49], v[142:145], v[208:211], 0
	v_mfma_f32_16x16x32_bf16 v[42:45], v[150:153], v[208:211], 0
	v_mfma_f32_16x16x32_bf16 v[30:33], v[142:145], v[216:219], 0
	v_mfma_f32_16x16x32_bf16 v[26:29], v[150:153], v[216:219], 0
	v_mfma_f32_16x16x32_bf16 v[14:17], v[142:145], v[224:227], 0
	v_mfma_f32_16x16x32_bf16 v[10:13], v[150:153], v[224:227], 0
	v_mfma_f32_16x16x32_bf16 v[54:57], v[164:167], v[180:183], 0
	v_mfma_f32_16x16x32_bf16 v[50:53], v[172:175], v[180:183], 0
	v_mfma_f32_16x16x32_bf16 v[38:41], v[164:167], v[208:211], 0
	v_mfma_f32_16x16x32_bf16 v[34:37], v[172:175], v[208:211], 0
	v_mfma_f32_16x16x32_bf16 v[22:25], v[164:167], v[216:219], 0
	v_mfma_f32_16x16x32_bf16 v[18:21], v[172:175], v[216:219], 0
	v_mfma_f32_16x16x32_bf16 v[6:9], v[164:167], v[224:227], 0
	v_mfma_f32_16x16x32_bf16 v[2:5], v[172:175], v[224:227], 0
	v_mfma_f32_16x16x32_bf16 v[62:65], v[146:149], v[204:207], v[62:65]
	v_mfma_f32_16x16x32_bf16 v[58:61], v[160:163], v[204:207], v[58:61]
	v_mfma_f32_16x16x32_bf16 v[46:49], v[146:149], v[212:215], v[46:49]
	v_mfma_f32_16x16x32_bf16 v[42:45], v[160:163], v[212:215], v[42:45]
	v_mfma_f32_16x16x32_bf16 v[30:33], v[146:149], v[220:223], v[30:33]
	v_mfma_f32_16x16x32_bf16 v[26:29], v[160:163], v[220:223], v[26:29]
	v_mfma_f32_16x16x32_bf16 v[14:17], v[146:149], v[228:231], v[14:17]
	v_mfma_f32_16x16x32_bf16 v[10:13], v[160:163], v[228:231], v[10:13]
	v_mfma_f32_16x16x32_bf16 v[54:57], v[168:171], v[204:207], v[54:57]
	v_mfma_f32_16x16x32_bf16 v[50:53], v[176:179], v[204:207], v[50:53]
	v_mfma_f32_16x16x32_bf16 v[38:41], v[168:171], v[212:215], v[38:41]
	v_mfma_f32_16x16x32_bf16 v[34:37], v[176:179], v[212:215], v[34:37]
	v_mfma_f32_16x16x32_bf16 v[22:25], v[168:171], v[220:223], v[22:25]
	v_mfma_f32_16x16x32_bf16 v[18:21], v[176:179], v[220:223], v[18:21]
	v_mfma_f32_16x16x32_bf16 v[6:9], v[168:171], v[228:231], v[6:9]
	v_mfma_f32_16x16x32_bf16 v[2:5], v[176:179], v[228:231], v[2:5]
	s_barrier
	s_setprio 0
	s_add_i32 s67, 0, 0x18000
	v_add_u32_e32 v0, s67, v158
	s_add_i32 s68, 0, 0x1c000
	ds_read_b128 v[142:145], v0
	ds_read_b128 v[146:149], v0 offset:1024
	ds_read_b128 v[150:153], v0 offset:2048
	ds_read_b128 v[160:163], v0 offset:3072
	v_add_u32_e32 v0, s68, v158
	ds_read_b128 v[164:167], v0
	ds_read_b128 v[168:171], v0 offset:1024
	ds_read_b128 v[172:175], v0 offset:2048
	ds_read_b128 v[176:179], v0 offset:3072
	s_add_u32 s56, s56, 0x40000
	s_addc_u32 s57, s57, 0
	s_mov_b32 m0, s61
	ds_read_b128 v[180:183], v159 offset:32768
	ds_read_b128 v[204:207], v159 offset:33792
	ds_read_b128 v[208:211], v159 offset:34816
	ds_read_b128 v[212:215], v159 offset:35840
	ds_read_b128 v[216:219], v159 offset:36864
	ds_read_b128 v[220:223], v159 offset:37888
	ds_read_b128 v[224:227], v159 offset:38912
	ds_read_b128 v[228:231], v159 offset:39936
	global_load_lds_dwordx4 v136, s[56:57]
	s_mov_b32 m0, s62
	s_nop 0
	global_load_lds_dwordx4 v132, s[56:57]
	s_waitcnt vmcnt(8)
	s_waitcnt lgkmcnt(0)
	s_setprio 1
	s_barrier
	v_mfma_f32_16x16x32_bf16 v[126:129], v[142:145], v[180:183], v[126:129]
	v_mfma_f32_16x16x32_bf16 v[122:125], v[150:153], v[180:183], v[122:125]
	v_mfma_f32_16x16x32_bf16 v[110:113], v[142:145], v[208:211], v[110:113]
	v_mfma_f32_16x16x32_bf16 v[106:109], v[150:153], v[208:211], v[106:109]
	v_mfma_f32_16x16x32_bf16 v[94:97], v[142:145], v[216:219], v[94:97]
	v_mfma_f32_16x16x32_bf16 v[90:93], v[150:153], v[216:219], v[90:93]
	v_mfma_f32_16x16x32_bf16 v[78:81], v[142:145], v[224:227], v[78:81]
	v_mfma_f32_16x16x32_bf16 v[74:77], v[150:153], v[224:227], v[74:77]
	v_mfma_f32_16x16x32_bf16 v[118:121], v[164:167], v[180:183], v[118:121]
	v_mfma_f32_16x16x32_bf16 v[114:117], v[172:175], v[180:183], v[114:117]
	v_mfma_f32_16x16x32_bf16 v[102:105], v[164:167], v[208:211], v[102:105]
	v_mfma_f32_16x16x32_bf16 v[98:101], v[172:175], v[208:211], v[98:101]
	v_mfma_f32_16x16x32_bf16 v[86:89], v[164:167], v[216:219], v[86:89]
	v_mfma_f32_16x16x32_bf16 v[82:85], v[172:175], v[216:219], v[82:85]
	v_mfma_f32_16x16x32_bf16 v[70:73], v[164:167], v[224:227], v[70:73]
	v_mfma_f32_16x16x32_bf16 v[66:69], v[172:175], v[224:227], v[66:69]
	v_mfma_f32_16x16x32_bf16 v[126:129], v[146:149], v[204:207], v[126:129]
	v_mfma_f32_16x16x32_bf16 v[122:125], v[160:163], v[204:207], v[122:125]
	v_mfma_f32_16x16x32_bf16 v[110:113], v[146:149], v[212:215], v[110:113]
	v_mfma_f32_16x16x32_bf16 v[106:109], v[160:163], v[212:215], v[106:109]
	v_mfma_f32_16x16x32_bf16 v[94:97], v[146:149], v[220:223], v[94:97]
	v_mfma_f32_16x16x32_bf16 v[90:93], v[160:163], v[220:223], v[90:93]
	v_mfma_f32_16x16x32_bf16 v[78:81], v[146:149], v[228:231], v[78:81]
	v_mfma_f32_16x16x32_bf16 v[74:77], v[160:163], v[228:231], v[74:77]
	v_mfma_f32_16x16x32_bf16 v[118:121], v[168:171], v[204:207], v[118:121]
	v_mfma_f32_16x16x32_bf16 v[114:117], v[176:179], v[204:207], v[114:117]
	v_mfma_f32_16x16x32_bf16 v[102:105], v[168:171], v[212:215], v[102:105]
	v_mfma_f32_16x16x32_bf16 v[98:101], v[176:179], v[212:215], v[98:101]
	v_mfma_f32_16x16x32_bf16 v[86:89], v[168:171], v[220:223], v[86:89]
	v_mfma_f32_16x16x32_bf16 v[82:85], v[176:179], v[220:223], v[82:85]
	v_mfma_f32_16x16x32_bf16 v[70:73], v[168:171], v[228:231], v[70:73]
	v_mfma_f32_16x16x32_bf16 v[66:69], v[176:179], v[228:231], v[66:69]
	s_barrier
	s_setprio 0
	s_add_i32 s69, s67, s58
	s_add_u32 s54, s54, 0x80
	s_addc_u32 s55, s55, 0
	s_mov_b32 m0, s69
	ds_read_b128 v[180:183], v159 offset:49152
	ds_read_b128 v[204:207], v159 offset:50176
	ds_read_b128 v[208:211], v159 offset:51200
	ds_read_b128 v[212:215], v159 offset:52224
	ds_read_b128 v[216:219], v159 offset:53248
	ds_read_b128 v[220:223], v159 offset:54272
	ds_read_b128 v[224:227], v159 offset:55296
	ds_read_b128 v[228:231], v159 offset:56320
	global_load_lds_dwordx4 v134, s[54:55]
	s_add_i32 m0, s69, 0x2000
	s_add_i32 s69, s68, s58
	global_load_lds_dwordx4 v130, s[54:55]
	s_add_u32 s54, s54, 0x40000
	s_addc_u32 s55, s55, 0
	s_mov_b32 m0, s69
	s_sub_u32 s56, s56, 0x3ff80
	global_load_lds_dwordx4 v134, s[54:55]
	s_subb_u32 s57, s57, 0
	s_add_i32 m0, s69, 0x2000
	s_nop 0
	global_load_lds_dwordx4 v130, s[54:55]
	s_mov_b32 m0, s5
	s_nop 0
	global_load_lds_dwordx4 v136, s[56:57]
	s_mov_b32 m0, s6
	s_nop 0
	global_load_lds_dwordx4 v132, s[56:57]
	s_waitcnt vmcnt(8)
	s_waitcnt lgkmcnt(0)
	s_setprio 1
	s_barrier
	v_mfma_f32_16x16x32_bf16 v[62:65], v[142:145], v[180:183], v[62:65]
	v_mfma_f32_16x16x32_bf16 v[58:61], v[150:153], v[180:183], v[58:61]
	v_mfma_f32_16x16x32_bf16 v[46:49], v[142:145], v[208:211], v[46:49]
	v_mfma_f32_16x16x32_bf16 v[42:45], v[150:153], v[208:211], v[42:45]
	v_mfma_f32_16x16x32_bf16 v[30:33], v[142:145], v[216:219], v[30:33]
	v_mfma_f32_16x16x32_bf16 v[26:29], v[150:153], v[216:219], v[26:29]
	v_mfma_f32_16x16x32_bf16 v[14:17], v[142:145], v[224:227], v[14:17]
	v_mfma_f32_16x16x32_bf16 v[10:13], v[150:153], v[224:227], v[10:13]
	v_mfma_f32_16x16x32_bf16 v[54:57], v[164:167], v[180:183], v[54:57]
	v_mfma_f32_16x16x32_bf16 v[50:53], v[172:175], v[180:183], v[50:53]
	v_mfma_f32_16x16x32_bf16 v[38:41], v[164:167], v[208:211], v[38:41]
	v_mfma_f32_16x16x32_bf16 v[34:37], v[172:175], v[208:211], v[34:37]
	v_mfma_f32_16x16x32_bf16 v[22:25], v[164:167], v[216:219], v[22:25]
	v_mfma_f32_16x16x32_bf16 v[18:21], v[172:175], v[216:219], v[18:21]
	v_mfma_f32_16x16x32_bf16 v[6:9], v[164:167], v[224:227], v[6:9]
	v_mfma_f32_16x16x32_bf16 v[2:5], v[172:175], v[224:227], v[2:5]
	v_mfma_f32_16x16x32_bf16 v[62:65], v[146:149], v[204:207], v[62:65]
	v_mfma_f32_16x16x32_bf16 v[58:61], v[160:163], v[204:207], v[58:61]
	v_mfma_f32_16x16x32_bf16 v[46:49], v[146:149], v[212:215], v[46:49]
	v_mfma_f32_16x16x32_bf16 v[42:45], v[160:163], v[212:215], v[42:45]
	v_mfma_f32_16x16x32_bf16 v[30:33], v[146:149], v[220:223], v[30:33]
	v_mfma_f32_16x16x32_bf16 v[26:29], v[160:163], v[220:223], v[26:29]
	v_mfma_f32_16x16x32_bf16 v[14:17], v[146:149], v[228:231], v[14:17]
	v_mfma_f32_16x16x32_bf16 v[10:13], v[160:163], v[228:231], v[10:13]
	v_mfma_f32_16x16x32_bf16 v[54:57], v[168:171], v[204:207], v[54:57]
	v_mfma_f32_16x16x32_bf16 v[50:53], v[176:179], v[204:207], v[50:53]
	v_mfma_f32_16x16x32_bf16 v[38:41], v[168:171], v[212:215], v[38:41]
	v_mfma_f32_16x16x32_bf16 v[34:37], v[176:179], v[212:215], v[34:37]
	v_mfma_f32_16x16x32_bf16 v[22:25], v[168:171], v[220:223], v[22:25]
	v_mfma_f32_16x16x32_bf16 v[18:21], v[176:179], v[220:223], v[18:21]
	v_mfma_f32_16x16x32_bf16 v[6:9], v[168:171], v[228:231], v[6:9]
	v_mfma_f32_16x16x32_bf16 v[2:5], v[176:179], v[228:231], v[2:5]
	s_barrier
	s_setprio 0
	s_add_i32 s66, s66, 2
	s_add_u32 s52, s52, 0x100
	s_addc_u32 s53, s53, 0
	s_add_u32 s64, s64, 0x100
	s_addc_u32 s65, s65, 0
	s_cmp_gt_u32 s66, 13
.LBB0_422:
	s_add_u32 s54, s52, 0xfffc0080
	s_addc_u32 s55, s53, -1
	s_add_i32 s67, 0, 0x10000
	s_cmp_eq_u32 s66, 12
	s_cselect_b32 s57, s19, s55
	s_cselect_b32 s56, s45, s54
	v_add_u32_e32 v0, s67, v158
	s_cselect_b32 s55, s41, s65
	s_cselect_b32 s54, s51, s64
	s_add_i32 s70, 0, 0x14000
	ds_read_b128 v[142:145], v0
	ds_read_b128 v[146:149], v0 offset:1024
	ds_read_b128 v[150:153], v0 offset:2048
	ds_read_b128 v[160:163], v0 offset:3072
	v_add_u32_e32 v0, s70, v158
	ds_read_b128 v[164:167], v0
	ds_read_b128 v[168:171], v0 offset:1024
	ds_read_b128 v[172:175], v0 offset:2048
	ds_read_b128 v[176:179], v0 offset:3072
	s_add_i32 m0, s59, 0xc000
	ds_read_b128 v[180:183], v159
	ds_read_b128 v[204:207], v159 offset:1024
	ds_read_b128 v[208:211], v159 offset:2048
	ds_read_b128 v[212:215], v159 offset:3072
	ds_read_b128 v[216:219], v159 offset:4096
	ds_read_b128 v[220:223], v159 offset:5120
	ds_read_b128 v[224:227], v159 offset:6144
	ds_read_b128 v[228:231], v159 offset:7168
	global_load_lds_dwordx4 v138, s[52:53]
	s_add_i32 m0, s59, 0xe000
	s_nop 0
	global_load_lds_dwordx4 v140, s[52:53]
	s_waitcnt vmcnt(8)
	s_waitcnt lgkmcnt(0)
	s_setprio 1
	s_barrier
	v_mfma_f32_16x16x32_bf16 v[126:129], v[142:145], v[180:183], v[126:129]
	v_mfma_f32_16x16x32_bf16 v[122:125], v[150:153], v[180:183], v[122:125]
	v_mfma_f32_16x16x32_bf16 v[110:113], v[142:145], v[208:211], v[110:113]
	v_mfma_f32_16x16x32_bf16 v[106:109], v[150:153], v[208:211], v[106:109]
	v_mfma_f32_16x16x32_bf16 v[94:97], v[142:145], v[216:219], v[94:97]
	v_mfma_f32_16x16x32_bf16 v[90:93], v[150:153], v[216:219], v[90:93]
	v_mfma_f32_16x16x32_bf16 v[78:81], v[142:145], v[224:227], v[78:81]
	v_mfma_f32_16x16x32_bf16 v[74:77], v[150:153], v[224:227], v[74:77]
	v_mfma_f32_16x16x32_bf16 v[118:121], v[164:167], v[180:183], v[118:121]
	v_mfma_f32_16x16x32_bf16 v[114:117], v[172:175], v[180:183], v[114:117]
	v_mfma_f32_16x16x32_bf16 v[102:105], v[164:167], v[208:211], v[102:105]
	v_mfma_f32_16x16x32_bf16 v[98:101], v[172:175], v[208:211], v[98:101]
	v_mfma_f32_16x16x32_bf16 v[86:89], v[164:167], v[216:219], v[86:89]
	v_mfma_f32_16x16x32_bf16 v[82:85], v[172:175], v[216:219], v[82:85]
	v_mfma_f32_16x16x32_bf16 v[70:73], v[164:167], v[224:227], v[70:73]
	v_mfma_f32_16x16x32_bf16 v[66:69], v[172:175], v[224:227], v[66:69]
	v_mfma_f32_16x16x32_bf16 v[126:129], v[146:149], v[204:207], v[126:129]
	v_mfma_f32_16x16x32_bf16 v[122:125], v[160:163], v[204:207], v[122:125]
	v_mfma_f32_16x16x32_bf16 v[110:113], v[146:149], v[212:215], v[110:113]
	v_mfma_f32_16x16x32_bf16 v[106:109], v[160:163], v[212:215], v[106:109]
	v_mfma_f32_16x16x32_bf16 v[94:97], v[146:149], v[220:223], v[94:97]
	v_mfma_f32_16x16x32_bf16 v[90:93], v[160:163], v[220:223], v[90:93]
	v_mfma_f32_16x16x32_bf16 v[78:81], v[146:149], v[228:231], v[78:81]
	v_mfma_f32_16x16x32_bf16 v[74:77], v[160:163], v[228:231], v[74:77]
	v_mfma_f32_16x16x32_bf16 v[118:121], v[168:171], v[204:207], v[118:121]
	v_mfma_f32_16x16x32_bf16 v[114:117], v[176:179], v[204:207], v[114:117]
	v_mfma_f32_16x16x32_bf16 v[102:105], v[168:171], v[212:215], v[102:105]
	v_mfma_f32_16x16x32_bf16 v[98:101], v[176:179], v[212:215], v[98:101]
	v_mfma_f32_16x16x32_bf16 v[86:89], v[168:171], v[220:223], v[86:89]
	v_mfma_f32_16x16x32_bf16 v[82:85], v[176:179], v[220:223], v[82:85]
	v_mfma_f32_16x16x32_bf16 v[70:73], v[168:171], v[228:231], v[70:73]
	v_mfma_f32_16x16x32_bf16 v[66:69], v[176:179], v[228:231], v[66:69]
	s_barrier
	s_setprio 0
	s_add_i32 s67, s67, s58
	s_mov_b32 m0, s67
	ds_read_b128 v[180:183], v159 offset:16384
	ds_read_b128 v[204:207], v159 offset:17408
	ds_read_b128 v[208:211], v159 offset:18432
	ds_read_b128 v[212:215], v159 offset:19456
	ds_read_b128 v[216:219], v159 offset:20480
	ds_read_b128 v[220:223], v159 offset:21504
	ds_read_b128 v[224:227], v159 offset:22528
	ds_read_b128 v[228:231], v159 offset:23552
	global_load_lds_dwordx4 v134, s[54:55]
	s_add_i32 m0, s67, 0x2000
	s_add_u32 s68, s54, 0x40000
	s_addc_u32 s69, s55, 0
	s_add_i32 s67, s70, s58
	global_load_lds_dwordx4 v130, s[54:55]
	s_mov_b32 m0, s67
	s_nop 0
	global_load_lds_dwordx4 v134, s[68:69]
	s_add_i32 m0, s67, 0x2000
	s_nop 0
	global_load_lds_dwordx4 v130, s[68:69]
	s_mov_b32 m0, s59
	s_nop 0
	global_load_lds_dwordx4 v136, s[56:57]
	s_mov_b32 m0, s60
	s_nop 0
	global_load_lds_dwordx4 v132, s[56:57]
	s_waitcnt vmcnt(8)
	s_waitcnt lgkmcnt(0)
	s_setprio 1
	s_barrier
	v_mfma_f32_16x16x32_bf16 v[62:65], v[142:145], v[180:183], v[62:65]
	v_mfma_f32_16x16x32_bf16 v[58:61], v[150:153], v[180:183], v[58:61]
	v_mfma_f32_16x16x32_bf16 v[46:49], v[142:145], v[208:211], v[46:49]
	v_mfma_f32_16x16x32_bf16 v[42:45], v[150:153], v[208:211], v[42:45]
	v_mfma_f32_16x16x32_bf16 v[30:33], v[142:145], v[216:219], v[30:33]
	v_mfma_f32_16x16x32_bf16 v[26:29], v[150:153], v[216:219], v[26:29]
	v_mfma_f32_16x16x32_bf16 v[14:17], v[142:145], v[224:227], v[14:17]
	v_mfma_f32_16x16x32_bf16 v[10:13], v[150:153], v[224:227], v[10:13]
	v_mfma_f32_16x16x32_bf16 v[54:57], v[164:167], v[180:183], v[54:57]
	v_mfma_f32_16x16x32_bf16 v[50:53], v[172:175], v[180:183], v[50:53]
	v_mfma_f32_16x16x32_bf16 v[38:41], v[164:167], v[208:211], v[38:41]
	v_mfma_f32_16x16x32_bf16 v[34:37], v[172:175], v[208:211], v[34:37]
	v_mfma_f32_16x16x32_bf16 v[22:25], v[164:167], v[216:219], v[22:25]
	v_mfma_f32_16x16x32_bf16 v[18:21], v[172:175], v[216:219], v[18:21]
	v_mfma_f32_16x16x32_bf16 v[6:9], v[164:167], v[224:227], v[6:9]
	v_mfma_f32_16x16x32_bf16 v[2:5], v[172:175], v[224:227], v[2:5]
	v_mfma_f32_16x16x32_bf16 v[62:65], v[146:149], v[204:207], v[62:65]
	v_mfma_f32_16x16x32_bf16 v[58:61], v[160:163], v[204:207], v[58:61]
	v_mfma_f32_16x16x32_bf16 v[46:49], v[146:149], v[212:215], v[46:49]
	v_mfma_f32_16x16x32_bf16 v[42:45], v[160:163], v[212:215], v[42:45]
	v_mfma_f32_16x16x32_bf16 v[30:33], v[146:149], v[220:223], v[30:33]
	v_mfma_f32_16x16x32_bf16 v[26:29], v[160:163], v[220:223], v[26:29]
	v_mfma_f32_16x16x32_bf16 v[14:17], v[146:149], v[228:231], v[14:17]
	v_mfma_f32_16x16x32_bf16 v[10:13], v[160:163], v[228:231], v[10:13]
	v_mfma_f32_16x16x32_bf16 v[54:57], v[168:171], v[204:207], v[54:57]
	v_mfma_f32_16x16x32_bf16 v[50:53], v[176:179], v[204:207], v[50:53]
	v_mfma_f32_16x16x32_bf16 v[38:41], v[168:171], v[212:215], v[38:41]
	v_mfma_f32_16x16x32_bf16 v[34:37], v[176:179], v[212:215], v[34:37]
	v_mfma_f32_16x16x32_bf16 v[22:25], v[168:171], v[220:223], v[22:25]
	v_mfma_f32_16x16x32_bf16 v[18:21], v[176:179], v[220:223], v[18:21]
	v_mfma_f32_16x16x32_bf16 v[6:9], v[168:171], v[228:231], v[6:9]
	v_mfma_f32_16x16x32_bf16 v[2:5], v[176:179], v[228:231], v[2:5]
	s_barrier
	s_setprio 0
	s_add_i32 s67, 0, 0x18000
	v_add_u32_e32 v0, s67, v158
	s_add_i32 s68, 0, 0x1c000
	ds_read_b128 v[142:145], v0
	ds_read_b128 v[146:149], v0 offset:1024
	ds_read_b128 v[150:153], v0 offset:2048
	ds_read_b128 v[160:163], v0 offset:3072
	v_add_u32_e32 v0, s68, v158
	ds_read_b128 v[164:167], v0
	ds_read_b128 v[168:171], v0 offset:1024
	ds_read_b128 v[172:175], v0 offset:2048
	ds_read_b128 v[176:179], v0 offset:3072
	s_add_u32 s56, s56, 0x40000
	s_addc_u32 s57, s57, 0
	s_mov_b32 m0, s61
	ds_read_b128 v[180:183], v159 offset:32768
	ds_read_b128 v[204:207], v159 offset:33792
	ds_read_b128 v[208:211], v159 offset:34816
	ds_read_b128 v[212:215], v159 offset:35840
	ds_read_b128 v[216:219], v159 offset:36864
	ds_read_b128 v[220:223], v159 offset:37888
	ds_read_b128 v[224:227], v159 offset:38912
	ds_read_b128 v[228:231], v159 offset:39936
	global_load_lds_dwordx4 v136, s[56:57]
	s_mov_b32 m0, s62
	s_nop 0
	global_load_lds_dwordx4 v132, s[56:57]
	s_waitcnt vmcnt(8)
	s_waitcnt lgkmcnt(0)
	s_setprio 1
	s_barrier
	v_mfma_f32_16x16x32_bf16 v[126:129], v[142:145], v[180:183], v[126:129]
	v_mfma_f32_16x16x32_bf16 v[122:125], v[150:153], v[180:183], v[122:125]
	v_mfma_f32_16x16x32_bf16 v[110:113], v[142:145], v[208:211], v[110:113]
	v_mfma_f32_16x16x32_bf16 v[106:109], v[150:153], v[208:211], v[106:109]
	v_mfma_f32_16x16x32_bf16 v[94:97], v[142:145], v[216:219], v[94:97]
	v_mfma_f32_16x16x32_bf16 v[90:93], v[150:153], v[216:219], v[90:93]
	v_mfma_f32_16x16x32_bf16 v[78:81], v[142:145], v[224:227], v[78:81]
	v_mfma_f32_16x16x32_bf16 v[74:77], v[150:153], v[224:227], v[74:77]
	v_mfma_f32_16x16x32_bf16 v[118:121], v[164:167], v[180:183], v[118:121]
	v_mfma_f32_16x16x32_bf16 v[114:117], v[172:175], v[180:183], v[114:117]
	v_mfma_f32_16x16x32_bf16 v[102:105], v[164:167], v[208:211], v[102:105]
	v_mfma_f32_16x16x32_bf16 v[98:101], v[172:175], v[208:211], v[98:101]
	v_mfma_f32_16x16x32_bf16 v[86:89], v[164:167], v[216:219], v[86:89]
	v_mfma_f32_16x16x32_bf16 v[82:85], v[172:175], v[216:219], v[82:85]
	v_mfma_f32_16x16x32_bf16 v[70:73], v[164:167], v[224:227], v[70:73]
	v_mfma_f32_16x16x32_bf16 v[66:69], v[172:175], v[224:227], v[66:69]
	v_mfma_f32_16x16x32_bf16 v[126:129], v[146:149], v[204:207], v[126:129]
	v_mfma_f32_16x16x32_bf16 v[122:125], v[160:163], v[204:207], v[122:125]
	v_mfma_f32_16x16x32_bf16 v[110:113], v[146:149], v[212:215], v[110:113]
	v_mfma_f32_16x16x32_bf16 v[106:109], v[160:163], v[212:215], v[106:109]
	v_mfma_f32_16x16x32_bf16 v[94:97], v[146:149], v[220:223], v[94:97]
	v_mfma_f32_16x16x32_bf16 v[90:93], v[160:163], v[220:223], v[90:93]
	v_mfma_f32_16x16x32_bf16 v[78:81], v[146:149], v[228:231], v[78:81]
	v_mfma_f32_16x16x32_bf16 v[74:77], v[160:163], v[228:231], v[74:77]
	v_mfma_f32_16x16x32_bf16 v[118:121], v[168:171], v[204:207], v[118:121]
	v_mfma_f32_16x16x32_bf16 v[114:117], v[176:179], v[204:207], v[114:117]
	v_mfma_f32_16x16x32_bf16 v[102:105], v[168:171], v[212:215], v[102:105]
	v_mfma_f32_16x16x32_bf16 v[98:101], v[176:179], v[212:215], v[98:101]
	v_mfma_f32_16x16x32_bf16 v[86:89], v[168:171], v[220:223], v[86:89]
	v_mfma_f32_16x16x32_bf16 v[82:85], v[176:179], v[220:223], v[82:85]
	v_mfma_f32_16x16x32_bf16 v[70:73], v[168:171], v[228:231], v[70:73]
	v_mfma_f32_16x16x32_bf16 v[66:69], v[176:179], v[228:231], v[66:69]
	s_barrier
	s_setprio 0
	s_add_i32 s69, s67, s58
	s_add_u32 s54, s54, 0x80
	s_addc_u32 s55, s55, 0
	s_mov_b32 m0, s69
	ds_read_b128 v[180:183], v159 offset:49152
	ds_read_b128 v[204:207], v159 offset:50176
	ds_read_b128 v[208:211], v159 offset:51200
	ds_read_b128 v[212:215], v159 offset:52224
	ds_read_b128 v[216:219], v159 offset:53248
	ds_read_b128 v[220:223], v159 offset:54272
	ds_read_b128 v[224:227], v159 offset:55296
	ds_read_b128 v[228:231], v159 offset:56320
	global_load_lds_dwordx4 v134, s[54:55]
	s_add_i32 m0, s69, 0x2000
	s_add_i32 s69, s68, s58
	global_load_lds_dwordx4 v130, s[54:55]
	s_add_u32 s54, s54, 0x40000
	s_addc_u32 s55, s55, 0
	s_mov_b32 m0, s69
	s_sub_u32 s56, s56, 0x3ff80
	global_load_lds_dwordx4 v134, s[54:55]
	s_subb_u32 s57, s57, 0
	s_add_i32 m0, s69, 0x2000
	s_nop 0
	global_load_lds_dwordx4 v130, s[54:55]
	s_mov_b32 m0, s5
	s_nop 0
	global_load_lds_dwordx4 v136, s[56:57]
	s_mov_b32 m0, s6
	s_nop 0
	global_load_lds_dwordx4 v132, s[56:57]
	s_waitcnt vmcnt(8)
	s_waitcnt lgkmcnt(0)
	s_setprio 1
	s_barrier
	v_mfma_f32_16x16x32_bf16 v[62:65], v[142:145], v[180:183], v[62:65]
	v_mfma_f32_16x16x32_bf16 v[58:61], v[150:153], v[180:183], v[58:61]
	v_mfma_f32_16x16x32_bf16 v[46:49], v[142:145], v[208:211], v[46:49]
	v_mfma_f32_16x16x32_bf16 v[42:45], v[150:153], v[208:211], v[42:45]
	v_mfma_f32_16x16x32_bf16 v[30:33], v[142:145], v[216:219], v[30:33]
	v_mfma_f32_16x16x32_bf16 v[26:29], v[150:153], v[216:219], v[26:29]
	v_mfma_f32_16x16x32_bf16 v[14:17], v[142:145], v[224:227], v[14:17]
	v_mfma_f32_16x16x32_bf16 v[10:13], v[150:153], v[224:227], v[10:13]
	v_mfma_f32_16x16x32_bf16 v[54:57], v[164:167], v[180:183], v[54:57]
	v_mfma_f32_16x16x32_bf16 v[50:53], v[172:175], v[180:183], v[50:53]
	v_mfma_f32_16x16x32_bf16 v[38:41], v[164:167], v[208:211], v[38:41]
	v_mfma_f32_16x16x32_bf16 v[34:37], v[172:175], v[208:211], v[34:37]
	v_mfma_f32_16x16x32_bf16 v[22:25], v[164:167], v[216:219], v[22:25]
	v_mfma_f32_16x16x32_bf16 v[18:21], v[172:175], v[216:219], v[18:21]
	v_mfma_f32_16x16x32_bf16 v[6:9], v[164:167], v[224:227], v[6:9]
	v_mfma_f32_16x16x32_bf16 v[2:5], v[172:175], v[224:227], v[2:5]
	v_mfma_f32_16x16x32_bf16 v[62:65], v[146:149], v[204:207], v[62:65]
	v_mfma_f32_16x16x32_bf16 v[58:61], v[160:163], v[204:207], v[58:61]
	v_mfma_f32_16x16x32_bf16 v[46:49], v[146:149], v[212:215], v[46:49]
	v_mfma_f32_16x16x32_bf16 v[42:45], v[160:163], v[212:215], v[42:45]
	v_mfma_f32_16x16x32_bf16 v[30:33], v[146:149], v[220:223], v[30:33]
	v_mfma_f32_16x16x32_bf16 v[26:29], v[160:163], v[220:223], v[26:29]
	v_mfma_f32_16x16x32_bf16 v[14:17], v[146:149], v[228:231], v[14:17]
	v_mfma_f32_16x16x32_bf16 v[10:13], v[160:163], v[228:231], v[10:13]
	v_mfma_f32_16x16x32_bf16 v[54:57], v[168:171], v[204:207], v[54:57]
	v_mfma_f32_16x16x32_bf16 v[50:53], v[176:179], v[204:207], v[50:53]
	v_mfma_f32_16x16x32_bf16 v[38:41], v[168:171], v[212:215], v[38:41]
	v_mfma_f32_16x16x32_bf16 v[34:37], v[176:179], v[212:215], v[34:37]
	v_mfma_f32_16x16x32_bf16 v[22:25], v[168:171], v[220:223], v[22:25]
	v_mfma_f32_16x16x32_bf16 v[18:21], v[176:179], v[220:223], v[18:21]
	v_mfma_f32_16x16x32_bf16 v[6:9], v[168:171], v[228:231], v[6:9]
	v_mfma_f32_16x16x32_bf16 v[2:5], v[176:179], v[228:231], v[2:5]
	s_barrier
	s_setprio 0
	s_add_i32 s66, s66, 2
	s_add_u32 s52, s52, 0x100
	s_addc_u32 s53, s53, 0
	s_add_u32 s64, s64, 0x100
	s_addc_u32 s65, s65, 0
	s_cmp_gt_u32 s66, 13
	s_cbranch_scc0 .LBB0_422
	s_and_b64 vcc, exec, s[38:39]
	s_cbranch_vccz .LBB0_425
	s_barrier

.Lrb3_skip:
	s_add_u32 s54, s52, 0xfffc0080
	s_addc_u32 s55, s53, -1
	s_add_i32 s61, 0, 0x10000
	s_cmp_eq_u32 s60, 12
	s_cselect_b32 s57, s19, s55
	s_cselect_b32 s56, s45, s54
	v_add_u32_e32 v0, s61, v160
	s_cselect_b32 s55, s41, s59
	s_cselect_b32 s54, s47, s58
	s_add_i32 s64, 0, 0x14000
	ds_read_b128 v[142:145], v0
	ds_read_b128 v[146:149], v0 offset:1024
	ds_read_b128 v[150:153], v0 offset:2048
	ds_read_b128 v[154:157], v0 offset:3072
	v_add_u32_e32 v0, s64, v160
	ds_read_b128 v[162:165], v0
	ds_read_b128 v[166:169], v0 offset:1024
	ds_read_b128 v[170:173], v0 offset:2048
	ds_read_b128 v[174:177], v0 offset:3072
	s_add_i32 m0, s71, 0xc000
	ds_read_b128 v[178:181], v161
	ds_read_b128 v[182:185], v161 offset:1024
	ds_read_b128 v[204:207], v161 offset:2048
	ds_read_b128 v[208:211], v161 offset:3072
	ds_read_b128 v[212:215], v161 offset:4096
	ds_read_b128 v[216:219], v161 offset:5120
	ds_read_b128 v[220:223], v161 offset:6144
	ds_read_b128 v[224:227], v161 offset:7168
	global_load_lds_dwordx4 v138, s[52:53]
	s_add_i32 m0, s71, 0xe000
	s_nop 0
	global_load_lds_dwordx4 v140, s[52:53]
	s_waitcnt vmcnt(8)
	s_waitcnt lgkmcnt(0)
	s_setprio 1
	s_barrier
	v_mfma_f32_16x16x32_bf16 v[126:129], v[142:145], v[178:181], 0
	v_mfma_f32_16x16x32_bf16 v[122:125], v[150:153], v[178:181], 0
	v_mfma_f32_16x16x32_bf16 v[110:113], v[142:145], v[204:207], 0
	v_mfma_f32_16x16x32_bf16 v[106:109], v[150:153], v[204:207], 0
	v_mfma_f32_16x16x32_bf16 v[94:97], v[142:145], v[212:215], 0
	v_mfma_f32_16x16x32_bf16 v[90:93], v[150:153], v[212:215], 0
	v_mfma_f32_16x16x32_bf16 v[78:81], v[142:145], v[220:223], 0
	v_mfma_f32_16x16x32_bf16 v[74:77], v[150:153], v[220:223], 0
	v_mfma_f32_16x16x32_bf16 v[118:121], v[162:165], v[178:181], 0
	v_mfma_f32_16x16x32_bf16 v[114:117], v[170:173], v[178:181], 0
	v_mfma_f32_16x16x32_bf16 v[102:105], v[162:165], v[204:207], 0
	v_mfma_f32_16x16x32_bf16 v[98:101], v[170:173], v[204:207], 0
	v_mfma_f32_16x16x32_bf16 v[86:89], v[162:165], v[212:215], 0
	v_mfma_f32_16x16x32_bf16 v[82:85], v[170:173], v[212:215], 0
	v_mfma_f32_16x16x32_bf16 v[70:73], v[162:165], v[220:223], 0
	v_mfma_f32_16x16x32_bf16 v[66:69], v[170:173], v[220:223], 0
	v_mfma_f32_16x16x32_bf16 v[126:129], v[146:149], v[182:185], v[126:129]
	v_mfma_f32_16x16x32_bf16 v[122:125], v[154:157], v[182:185], v[122:125]
	v_mfma_f32_16x16x32_bf16 v[110:113], v[146:149], v[208:211], v[110:113]
	v_mfma_f32_16x16x32_bf16 v[106:109], v[154:157], v[208:211], v[106:109]
	v_mfma_f32_16x16x32_bf16 v[94:97], v[146:149], v[216:219], v[94:97]
	v_mfma_f32_16x16x32_bf16 v[90:93], v[154:157], v[216:219], v[90:93]
	v_mfma_f32_16x16x32_bf16 v[78:81], v[146:149], v[224:227], v[78:81]
	v_mfma_f32_16x16x32_bf16 v[74:77], v[154:157], v[224:227], v[74:77]
	v_mfma_f32_16x16x32_bf16 v[118:121], v[166:169], v[182:185], v[118:121]
	v_mfma_f32_16x16x32_bf16 v[114:117], v[174:177], v[182:185], v[114:117]
	v_mfma_f32_16x16x32_bf16 v[102:105], v[166:169], v[208:211], v[102:105]
	v_mfma_f32_16x16x32_bf16 v[98:101], v[174:177], v[208:211], v[98:101]
	v_mfma_f32_16x16x32_bf16 v[86:89], v[166:169], v[216:219], v[86:89]
	v_mfma_f32_16x16x32_bf16 v[82:85], v[174:177], v[216:219], v[82:85]
	v_mfma_f32_16x16x32_bf16 v[70:73], v[166:169], v[224:227], v[70:73]
	v_mfma_f32_16x16x32_bf16 v[66:69], v[174:177], v[224:227], v[66:69]
	s_barrier
	s_setprio 0
	s_add_i32 s61, s61, s70
	s_mov_b32 m0, s61
	ds_read_b128 v[178:181], v161 offset:16384
	ds_read_b128 v[182:185], v161 offset:17408
	ds_read_b128 v[204:207], v161 offset:18432
	ds_read_b128 v[208:211], v161 offset:19456
	ds_read_b128 v[212:215], v161 offset:20480
	ds_read_b128 v[216:219], v161 offset:21504
	ds_read_b128 v[220:223], v161 offset:22528
	ds_read_b128 v[224:227], v161 offset:23552
	global_load_lds_dwordx4 v134, s[54:55]
	s_add_i32 m0, s61, 0x2000
	s_add_u32 s62, s54, 0x40000
	s_addc_u32 s63, s55, 0
	s_add_i32 s61, s64, s70
	global_load_lds_dwordx4 v130, s[54:55]
	s_mov_b32 m0, s61
	s_nop 0
	global_load_lds_dwordx4 v134, s[62:63]
	s_add_i32 m0, s61, 0x2000
	s_nop 0
	global_load_lds_dwordx4 v130, s[62:63]
	s_mov_b32 m0, s71
	s_nop 0
	global_load_lds_dwordx4 v136, s[56:57]
	s_mov_b32 m0, s72
	s_nop 0
	global_load_lds_dwordx4 v132, s[56:57]
	s_waitcnt vmcnt(8)
	s_waitcnt lgkmcnt(0)
	s_setprio 1
	s_barrier
	v_mfma_f32_16x16x32_bf16 v[62:65], v[142:145], v[178:181], 0
	v_mfma_f32_16x16x32_bf16 v[58:61], v[150:153], v[178:181], 0
	v_mfma_f32_16x16x32_bf16 v[46:49], v[142:145], v[204:207], 0
	v_mfma_f32_16x16x32_bf16 v[42:45], v[150:153], v[204:207], 0
	v_mfma_f32_16x16x32_bf16 v[30:33], v[142:145], v[212:215], 0
	v_mfma_f32_16x16x32_bf16 v[26:29], v[150:153], v[212:215], 0
	v_mfma_f32_16x16x32_bf16 v[14:17], v[142:145], v[220:223], 0
	v_mfma_f32_16x16x32_bf16 v[10:13], v[150:153], v[220:223], 0
	v_mfma_f32_16x16x32_bf16 v[54:57], v[162:165], v[178:181], 0
	v_mfma_f32_16x16x32_bf16 v[50:53], v[170:173], v[178:181], 0
	v_mfma_f32_16x16x32_bf16 v[38:41], v[162:165], v[204:207], 0
	v_mfma_f32_16x16x32_bf16 v[34:37], v[170:173], v[204:207], 0
	v_mfma_f32_16x16x32_bf16 v[22:25], v[162:165], v[212:215], 0
	v_mfma_f32_16x16x32_bf16 v[18:21], v[170:173], v[212:215], 0
	v_mfma_f32_16x16x32_bf16 v[6:9], v[162:165], v[220:223], 0
	v_mfma_f32_16x16x32_bf16 v[2:5], v[170:173], v[220:223], 0
	v_mfma_f32_16x16x32_bf16 v[62:65], v[146:149], v[182:185], v[62:65]
	v_mfma_f32_16x16x32_bf16 v[58:61], v[154:157], v[182:185], v[58:61]
	v_mfma_f32_16x16x32_bf16 v[46:49], v[146:149], v[208:211], v[46:49]
	v_mfma_f32_16x16x32_bf16 v[42:45], v[154:157], v[208:211], v[42:45]
	v_mfma_f32_16x16x32_bf16 v[30:33], v[146:149], v[216:219], v[30:33]
	v_mfma_f32_16x16x32_bf16 v[26:29], v[154:157], v[216:219], v[26:29]
	v_mfma_f32_16x16x32_bf16 v[14:17], v[146:149], v[224:227], v[14:17]
	v_mfma_f32_16x16x32_bf16 v[10:13], v[154:157], v[224:227], v[10:13]
	v_mfma_f32_16x16x32_bf16 v[54:57], v[166:169], v[182:185], v[54:57]
	v_mfma_f32_16x16x32_bf16 v[50:53], v[174:177], v[182:185], v[50:53]
	v_mfma_f32_16x16x32_bf16 v[38:41], v[166:169], v[208:211], v[38:41]
	v_mfma_f32_16x16x32_bf16 v[34:37], v[174:177], v[208:211], v[34:37]
	v_mfma_f32_16x16x32_bf16 v[22:25], v[166:169], v[216:219], v[22:25]
	v_mfma_f32_16x16x32_bf16 v[18:21], v[174:177], v[216:219], v[18:21]
	v_mfma_f32_16x16x32_bf16 v[6:9], v[166:169], v[224:227], v[6:9]
	v_mfma_f32_16x16x32_bf16 v[2:5], v[174:177], v[224:227], v[2:5]
	s_barrier
	s_setprio 0
	s_add_i32 s61, 0, 0x18000
	v_add_u32_e32 v0, s61, v160
	s_add_i32 s62, 0, 0x1c000
	ds_read_b128 v[142:145], v0
	ds_read_b128 v[146:149], v0 offset:1024
	ds_read_b128 v[150:153], v0 offset:2048
	ds_read_b128 v[154:157], v0 offset:3072
	v_add_u32_e32 v0, s62, v160
	ds_read_b128 v[162:165], v0
	ds_read_b128 v[166:169], v0 offset:1024
	ds_read_b128 v[170:173], v0 offset:2048
	ds_read_b128 v[174:177], v0 offset:3072
	s_add_u32 s56, s56, 0x40000
	s_addc_u32 s57, s57, 0
	s_mov_b32 m0, s73
	ds_read_b128 v[178:181], v161 offset:32768
	ds_read_b128 v[182:185], v161 offset:33792
	ds_read_b128 v[204:207], v161 offset:34816
	ds_read_b128 v[208:211], v161 offset:35840
	ds_read_b128 v[212:215], v161 offset:36864
	ds_read_b128 v[216:219], v161 offset:37888
	ds_read_b128 v[220:223], v161 offset:38912
	ds_read_b128 v[224:227], v161 offset:39936
	global_load_lds_dwordx4 v136, s[56:57]
	s_mov_b32 m0, s74
	s_nop 0
	global_load_lds_dwordx4 v132, s[56:57]
	s_waitcnt vmcnt(8)
	s_waitcnt lgkmcnt(0)
	s_setprio 1
	s_barrier
	v_mfma_f32_16x16x32_bf16 v[126:129], v[142:145], v[178:181], v[126:129]
	v_mfma_f32_16x16x32_bf16 v[122:125], v[150:153], v[178:181], v[122:125]
	v_mfma_f32_16x16x32_bf16 v[110:113], v[142:145], v[204:207], v[110:113]
	v_mfma_f32_16x16x32_bf16 v[106:109], v[150:153], v[204:207], v[106:109]
	v_mfma_f32_16x16x32_bf16 v[94:97], v[142:145], v[212:215], v[94:97]
	v_mfma_f32_16x16x32_bf16 v[90:93], v[150:153], v[212:215], v[90:93]
	v_mfma_f32_16x16x32_bf16 v[78:81], v[142:145], v[220:223], v[78:81]
	v_mfma_f32_16x16x32_bf16 v[74:77], v[150:153], v[220:223], v[74:77]
	v_mfma_f32_16x16x32_bf16 v[118:121], v[162:165], v[178:181], v[118:121]
	v_mfma_f32_16x16x32_bf16 v[114:117], v[170:173], v[178:181], v[114:117]
	v_mfma_f32_16x16x32_bf16 v[102:105], v[162:165], v[204:207], v[102:105]
	v_mfma_f32_16x16x32_bf16 v[98:101], v[170:173], v[204:207], v[98:101]
	v_mfma_f32_16x16x32_bf16 v[86:89], v[162:165], v[212:215], v[86:89]
	v_mfma_f32_16x16x32_bf16 v[82:85], v[170:173], v[212:215], v[82:85]
	v_mfma_f32_16x16x32_bf16 v[70:73], v[162:165], v[220:223], v[70:73]
	v_mfma_f32_16x16x32_bf16 v[66:69], v[170:173], v[220:223], v[66:69]
	v_mfma_f32_16x16x32_bf16 v[126:129], v[146:149], v[182:185], v[126:129]
	v_mfma_f32_16x16x32_bf16 v[122:125], v[154:157], v[182:185], v[122:125]
	v_mfma_f32_16x16x32_bf16 v[110:113], v[146:149], v[208:211], v[110:113]
	v_mfma_f32_16x16x32_bf16 v[106:109], v[154:157], v[208:211], v[106:109]
	v_mfma_f32_16x16x32_bf16 v[94:97], v[146:149], v[216:219], v[94:97]
	v_mfma_f32_16x16x32_bf16 v[90:93], v[154:157], v[216:219], v[90:93]
	v_mfma_f32_16x16x32_bf16 v[78:81], v[146:149], v[224:227], v[78:81]
	v_mfma_f32_16x16x32_bf16 v[74:77], v[154:157], v[224:227], v[74:77]
	v_mfma_f32_16x16x32_bf16 v[118:121], v[166:169], v[182:185], v[118:121]
	v_mfma_f32_16x16x32_bf16 v[114:117], v[174:177], v[182:185], v[114:117]
	v_mfma_f32_16x16x32_bf16 v[102:105], v[166:169], v[208:211], v[102:105]
	v_mfma_f32_16x16x32_bf16 v[98:101], v[174:177], v[208:211], v[98:101]
	v_mfma_f32_16x16x32_bf16 v[86:89], v[166:169], v[216:219], v[86:89]
	v_mfma_f32_16x16x32_bf16 v[82:85], v[174:177], v[216:219], v[82:85]
	v_mfma_f32_16x16x32_bf16 v[70:73], v[166:169], v[224:227], v[70:73]
	v_mfma_f32_16x16x32_bf16 v[66:69], v[174:177], v[224:227], v[66:69]
	s_barrier
	s_setprio 0
	s_add_i32 s63, s61, s70
	s_add_u32 s54, s54, 0x80
	s_addc_u32 s55, s55, 0
	s_mov_b32 m0, s63
	ds_read_b128 v[178:181], v161 offset:49152
	ds_read_b128 v[182:185], v161 offset:50176
	ds_read_b128 v[204:207], v161 offset:51200
	ds_read_b128 v[208:211], v161 offset:52224
	ds_read_b128 v[212:215], v161 offset:53248
	ds_read_b128 v[216:219], v161 offset:54272
	ds_read_b128 v[220:223], v161 offset:55296
	ds_read_b128 v[224:227], v161 offset:56320
	global_load_lds_dwordx4 v134, s[54:55]
	s_add_i32 m0, s63, 0x2000
	s_add_i32 s63, s62, s70
	global_load_lds_dwordx4 v130, s[54:55]
	s_add_u32 s54, s54, 0x40000
	s_addc_u32 s55, s55, 0
	s_mov_b32 m0, s63
	s_sub_u32 s56, s56, 0x3ff80
	global_load_lds_dwordx4 v134, s[54:55]
	s_subb_u32 s57, s57, 0
	s_add_i32 m0, s63, 0x2000
	s_nop 0
	global_load_lds_dwordx4 v130, s[54:55]
	s_mov_b32 m0, s86
	s_nop 0
	global_load_lds_dwordx4 v136, s[56:57]
	s_mov_b32 m0, s87
	s_nop 0
	global_load_lds_dwordx4 v132, s[56:57]
	s_waitcnt vmcnt(8)
	s_waitcnt lgkmcnt(0)
	s_setprio 1
	s_barrier
	v_mfma_f32_16x16x32_bf16 v[62:65], v[142:145], v[178:181], v[62:65]
	v_mfma_f32_16x16x32_bf16 v[58:61], v[150:153], v[178:181], v[58:61]
	v_mfma_f32_16x16x32_bf16 v[46:49], v[142:145], v[204:207], v[46:49]
	v_mfma_f32_16x16x32_bf16 v[42:45], v[150:153], v[204:207], v[42:45]
	v_mfma_f32_16x16x32_bf16 v[30:33], v[142:145], v[212:215], v[30:33]
	v_mfma_f32_16x16x32_bf16 v[26:29], v[150:153], v[212:215], v[26:29]
	v_mfma_f32_16x16x32_bf16 v[14:17], v[142:145], v[220:223], v[14:17]
	v_mfma_f32_16x16x32_bf16 v[10:13], v[150:153], v[220:223], v[10:13]
	v_mfma_f32_16x16x32_bf16 v[54:57], v[162:165], v[178:181], v[54:57]
	v_mfma_f32_16x16x32_bf16 v[50:53], v[170:173], v[178:181], v[50:53]
	v_mfma_f32_16x16x32_bf16 v[38:41], v[162:165], v[204:207], v[38:41]
	v_mfma_f32_16x16x32_bf16 v[34:37], v[170:173], v[204:207], v[34:37]
	v_mfma_f32_16x16x32_bf16 v[22:25], v[162:165], v[212:215], v[22:25]
	v_mfma_f32_16x16x32_bf16 v[18:21], v[170:173], v[212:215], v[18:21]
	v_mfma_f32_16x16x32_bf16 v[6:9], v[162:165], v[220:223], v[6:9]
	v_mfma_f32_16x16x32_bf16 v[2:5], v[170:173], v[220:223], v[2:5]
	v_mfma_f32_16x16x32_bf16 v[62:65], v[146:149], v[182:185], v[62:65]
	v_mfma_f32_16x16x32_bf16 v[58:61], v[154:157], v[182:185], v[58:61]
	v_mfma_f32_16x16x32_bf16 v[46:49], v[146:149], v[208:211], v[46:49]
	v_mfma_f32_16x16x32_bf16 v[42:45], v[154:157], v[208:211], v[42:45]
	v_mfma_f32_16x16x32_bf16 v[30:33], v[146:149], v[216:219], v[30:33]
	v_mfma_f32_16x16x32_bf16 v[26:29], v[154:157], v[216:219], v[26:29]
	v_mfma_f32_16x16x32_bf16 v[14:17], v[146:149], v[224:227], v[14:17]
	v_mfma_f32_16x16x32_bf16 v[10:13], v[154:157], v[224:227], v[10:13]
	v_mfma_f32_16x16x32_bf16 v[54:57], v[166:169], v[182:185], v[54:57]
	v_mfma_f32_16x16x32_bf16 v[50:53], v[174:177], v[182:185], v[50:53]
	v_mfma_f32_16x16x32_bf16 v[38:41], v[166:169], v[208:211], v[38:41]
	v_mfma_f32_16x16x32_bf16 v[34:37], v[174:177], v[208:211], v[34:37]
	v_mfma_f32_16x16x32_bf16 v[22:25], v[166:169], v[216:219], v[22:25]
	v_mfma_f32_16x16x32_bf16 v[18:21], v[174:177], v[216:219], v[18:21]
	v_mfma_f32_16x16x32_bf16 v[6:9], v[166:169], v[224:227], v[6:9]
	v_mfma_f32_16x16x32_bf16 v[2:5], v[174:177], v[224:227], v[2:5]
	s_barrier
	s_setprio 0
	s_add_i32 s60, s60, 2
	s_add_u32 s52, s52, 0x100
	s_addc_u32 s53, s53, 0
	s_add_u32 s58, s58, 0x100
	s_addc_u32 s59, s59, 0
	s_cmp_gt_u32 s60, 13
.LBB0_479:
	s_add_u32 s54, s52, 0xfffc0080
	s_addc_u32 s55, s53, -1
	s_add_i32 s61, 0, 0x10000
	s_cmp_eq_u32 s60, 12
	s_cselect_b32 s57, s19, s55
	s_cselect_b32 s56, s45, s54
	v_add_u32_e32 v0, s61, v160
	s_cselect_b32 s55, s41, s59
	s_cselect_b32 s54, s47, s58
	s_add_i32 s64, 0, 0x14000
	ds_read_b128 v[142:145], v0
	ds_read_b128 v[146:149], v0 offset:1024
	ds_read_b128 v[150:153], v0 offset:2048
	ds_read_b128 v[154:157], v0 offset:3072
	v_add_u32_e32 v0, s64, v160
	ds_read_b128 v[162:165], v0
	ds_read_b128 v[166:169], v0 offset:1024
	ds_read_b128 v[170:173], v0 offset:2048
	ds_read_b128 v[174:177], v0 offset:3072
	s_add_i32 m0, s71, 0xc000
	ds_read_b128 v[178:181], v161
	ds_read_b128 v[182:185], v161 offset:1024
	ds_read_b128 v[204:207], v161 offset:2048
	ds_read_b128 v[208:211], v161 offset:3072
	ds_read_b128 v[212:215], v161 offset:4096
	ds_read_b128 v[216:219], v161 offset:5120
	ds_read_b128 v[220:223], v161 offset:6144
	ds_read_b128 v[224:227], v161 offset:7168
	global_load_lds_dwordx4 v138, s[52:53]
	s_add_i32 m0, s71, 0xe000
	s_nop 0
	global_load_lds_dwordx4 v140, s[52:53]
	s_waitcnt vmcnt(8)
	s_waitcnt lgkmcnt(0)
	s_setprio 1
	s_barrier
	v_mfma_f32_16x16x32_bf16 v[126:129], v[142:145], v[178:181], v[126:129]
	v_mfma_f32_16x16x32_bf16 v[122:125], v[150:153], v[178:181], v[122:125]
	v_mfma_f32_16x16x32_bf16 v[110:113], v[142:145], v[204:207], v[110:113]
	v_mfma_f32_16x16x32_bf16 v[106:109], v[150:153], v[204:207], v[106:109]
	v_mfma_f32_16x16x32_bf16 v[94:97], v[142:145], v[212:215], v[94:97]
	v_mfma_f32_16x16x32_bf16 v[90:93], v[150:153], v[212:215], v[90:93]
	v_mfma_f32_16x16x32_bf16 v[78:81], v[142:145], v[220:223], v[78:81]
	v_mfma_f32_16x16x32_bf16 v[74:77], v[150:153], v[220:223], v[74:77]
	v_mfma_f32_16x16x32_bf16 v[118:121], v[162:165], v[178:181], v[118:121]
	v_mfma_f32_16x16x32_bf16 v[114:117], v[170:173], v[178:181], v[114:117]
	v_mfma_f32_16x16x32_bf16 v[102:105], v[162:165], v[204:207], v[102:105]
	v_mfma_f32_16x16x32_bf16 v[98:101], v[170:173], v[204:207], v[98:101]
	v_mfma_f32_16x16x32_bf16 v[86:89], v[162:165], v[212:215], v[86:89]
	v_mfma_f32_16x16x32_bf16 v[82:85], v[170:173], v[212:215], v[82:85]
	v_mfma_f32_16x16x32_bf16 v[70:73], v[162:165], v[220:223], v[70:73]
	v_mfma_f32_16x16x32_bf16 v[66:69], v[170:173], v[220:223], v[66:69]
	v_mfma_f32_16x16x32_bf16 v[126:129], v[146:149], v[182:185], v[126:129]
	v_mfma_f32_16x16x32_bf16 v[122:125], v[154:157], v[182:185], v[122:125]
	v_mfma_f32_16x16x32_bf16 v[110:113], v[146:149], v[208:211], v[110:113]
	v_mfma_f32_16x16x32_bf16 v[106:109], v[154:157], v[208:211], v[106:109]
	v_mfma_f32_16x16x32_bf16 v[94:97], v[146:149], v[216:219], v[94:97]
	v_mfma_f32_16x16x32_bf16 v[90:93], v[154:157], v[216:219], v[90:93]
	v_mfma_f32_16x16x32_bf16 v[78:81], v[146:149], v[224:227], v[78:81]
	v_mfma_f32_16x16x32_bf16 v[74:77], v[154:157], v[224:227], v[74:77]
	v_mfma_f32_16x16x32_bf16 v[118:121], v[166:169], v[182:185], v[118:121]
	v_mfma_f32_16x16x32_bf16 v[114:117], v[174:177], v[182:185], v[114:117]
	v_mfma_f32_16x16x32_bf16 v[102:105], v[166:169], v[208:211], v[102:105]
	v_mfma_f32_16x16x32_bf16 v[98:101], v[174:177], v[208:211], v[98:101]
	v_mfma_f32_16x16x32_bf16 v[86:89], v[166:169], v[216:219], v[86:89]
	v_mfma_f32_16x16x32_bf16 v[82:85], v[174:177], v[216:219], v[82:85]
	v_mfma_f32_16x16x32_bf16 v[70:73], v[166:169], v[224:227], v[70:73]
	v_mfma_f32_16x16x32_bf16 v[66:69], v[174:177], v[224:227], v[66:69]
	s_barrier
	s_setprio 0
	s_add_i32 s61, s61, s70
	s_mov_b32 m0, s61
	ds_read_b128 v[178:181], v161 offset:16384
	ds_read_b128 v[182:185], v161 offset:17408
	ds_read_b128 v[204:207], v161 offset:18432
	ds_read_b128 v[208:211], v161 offset:19456
	ds_read_b128 v[212:215], v161 offset:20480
	ds_read_b128 v[216:219], v161 offset:21504
	ds_read_b128 v[220:223], v161 offset:22528
	ds_read_b128 v[224:227], v161 offset:23552
	global_load_lds_dwordx4 v134, s[54:55]
	s_add_i32 m0, s61, 0x2000
	s_add_u32 s62, s54, 0x40000
	s_addc_u32 s63, s55, 0
	s_add_i32 s61, s64, s70
	global_load_lds_dwordx4 v130, s[54:55]
	s_mov_b32 m0, s61
	s_nop 0
	global_load_lds_dwordx4 v134, s[62:63]
	s_add_i32 m0, s61, 0x2000
	s_nop 0
	global_load_lds_dwordx4 v130, s[62:63]
	s_mov_b32 m0, s71
	s_nop 0
	global_load_lds_dwordx4 v136, s[56:57]
	s_mov_b32 m0, s72
	s_nop 0
	global_load_lds_dwordx4 v132, s[56:57]
	s_waitcnt vmcnt(8)
	s_waitcnt lgkmcnt(0)
	s_setprio 1
	s_barrier
	v_mfma_f32_16x16x32_bf16 v[62:65], v[142:145], v[178:181], v[62:65]
	v_mfma_f32_16x16x32_bf16 v[58:61], v[150:153], v[178:181], v[58:61]
	v_mfma_f32_16x16x32_bf16 v[46:49], v[142:145], v[204:207], v[46:49]
	v_mfma_f32_16x16x32_bf16 v[42:45], v[150:153], v[204:207], v[42:45]
	v_mfma_f32_16x16x32_bf16 v[30:33], v[142:145], v[212:215], v[30:33]
	v_mfma_f32_16x16x32_bf16 v[26:29], v[150:153], v[212:215], v[26:29]
	v_mfma_f32_16x16x32_bf16 v[14:17], v[142:145], v[220:223], v[14:17]
	v_mfma_f32_16x16x32_bf16 v[10:13], v[150:153], v[220:223], v[10:13]
	v_mfma_f32_16x16x32_bf16 v[54:57], v[162:165], v[178:181], v[54:57]
	v_mfma_f32_16x16x32_bf16 v[50:53], v[170:173], v[178:181], v[50:53]
	v_mfma_f32_16x16x32_bf16 v[38:41], v[162:165], v[204:207], v[38:41]
	v_mfma_f32_16x16x32_bf16 v[34:37], v[170:173], v[204:207], v[34:37]
	v_mfma_f32_16x16x32_bf16 v[22:25], v[162:165], v[212:215], v[22:25]
	v_mfma_f32_16x16x32_bf16 v[18:21], v[170:173], v[212:215], v[18:21]
	v_mfma_f32_16x16x32_bf16 v[6:9], v[162:165], v[220:223], v[6:9]
	v_mfma_f32_16x16x32_bf16 v[2:5], v[170:173], v[220:223], v[2:5]
	v_mfma_f32_16x16x32_bf16 v[62:65], v[146:149], v[182:185], v[62:65]
	v_mfma_f32_16x16x32_bf16 v[58:61], v[154:157], v[182:185], v[58:61]
	v_mfma_f32_16x16x32_bf16 v[46:49], v[146:149], v[208:211], v[46:49]
	v_mfma_f32_16x16x32_bf16 v[42:45], v[154:157], v[208:211], v[42:45]
	v_mfma_f32_16x16x32_bf16 v[30:33], v[146:149], v[216:219], v[30:33]
	v_mfma_f32_16x16x32_bf16 v[26:29], v[154:157], v[216:219], v[26:29]
	v_mfma_f32_16x16x32_bf16 v[14:17], v[146:149], v[224:227], v[14:17]
	v_mfma_f32_16x16x32_bf16 v[10:13], v[154:157], v[224:227], v[10:13]
	v_mfma_f32_16x16x32_bf16 v[54:57], v[166:169], v[182:185], v[54:57]
	v_mfma_f32_16x16x32_bf16 v[50:53], v[174:177], v[182:185], v[50:53]
	v_mfma_f32_16x16x32_bf16 v[38:41], v[166:169], v[208:211], v[38:41]
	v_mfma_f32_16x16x32_bf16 v[34:37], v[174:177], v[208:211], v[34:37]
	v_mfma_f32_16x16x32_bf16 v[22:25], v[166:169], v[216:219], v[22:25]
	v_mfma_f32_16x16x32_bf16 v[18:21], v[174:177], v[216:219], v[18:21]
	v_mfma_f32_16x16x32_bf16 v[6:9], v[166:169], v[224:227], v[6:9]
	v_mfma_f32_16x16x32_bf16 v[2:5], v[174:177], v[224:227], v[2:5]
	s_barrier
	s_setprio 0
	s_add_i32 s61, 0, 0x18000
	v_add_u32_e32 v0, s61, v160
	s_add_i32 s62, 0, 0x1c000
	ds_read_b128 v[142:145], v0
	ds_read_b128 v[146:149], v0 offset:1024
	ds_read_b128 v[150:153], v0 offset:2048
	ds_read_b128 v[154:157], v0 offset:3072
	v_add_u32_e32 v0, s62, v160
	ds_read_b128 v[162:165], v0
	ds_read_b128 v[166:169], v0 offset:1024
	ds_read_b128 v[170:173], v0 offset:2048
	ds_read_b128 v[174:177], v0 offset:3072
	s_add_u32 s56, s56, 0x40000
	s_addc_u32 s57, s57, 0
	s_mov_b32 m0, s73
	ds_read_b128 v[178:181], v161 offset:32768
	ds_read_b128 v[182:185], v161 offset:33792
	ds_read_b128 v[204:207], v161 offset:34816
	ds_read_b128 v[208:211], v161 offset:35840
	ds_read_b128 v[212:215], v161 offset:36864
	ds_read_b128 v[216:219], v161 offset:37888
	ds_read_b128 v[220:223], v161 offset:38912
	ds_read_b128 v[224:227], v161 offset:39936
	global_load_lds_dwordx4 v136, s[56:57]
	s_mov_b32 m0, s74
	s_nop 0
	global_load_lds_dwordx4 v132, s[56:57]
	s_waitcnt vmcnt(8)
	s_waitcnt lgkmcnt(0)
	s_setprio 1
	s_barrier
	v_mfma_f32_16x16x32_bf16 v[126:129], v[142:145], v[178:181], v[126:129]
	v_mfma_f32_16x16x32_bf16 v[122:125], v[150:153], v[178:181], v[122:125]
	v_mfma_f32_16x16x32_bf16 v[110:113], v[142:145], v[204:207], v[110:113]
	v_mfma_f32_16x16x32_bf16 v[106:109], v[150:153], v[204:207], v[106:109]
	v_mfma_f32_16x16x32_bf16 v[94:97], v[142:145], v[212:215], v[94:97]
	v_mfma_f32_16x16x32_bf16 v[90:93], v[150:153], v[212:215], v[90:93]
	v_mfma_f32_16x16x32_bf16 v[78:81], v[142:145], v[220:223], v[78:81]
	v_mfma_f32_16x16x32_bf16 v[74:77], v[150:153], v[220:223], v[74:77]
	v_mfma_f32_16x16x32_bf16 v[118:121], v[162:165], v[178:181], v[118:121]
	v_mfma_f32_16x16x32_bf16 v[114:117], v[170:173], v[178:181], v[114:117]
	v_mfma_f32_16x16x32_bf16 v[102:105], v[162:165], v[204:207], v[102:105]
	v_mfma_f32_16x16x32_bf16 v[98:101], v[170:173], v[204:207], v[98:101]
	v_mfma_f32_16x16x32_bf16 v[86:89], v[162:165], v[212:215], v[86:89]
	v_mfma_f32_16x16x32_bf16 v[82:85], v[170:173], v[212:215], v[82:85]
	v_mfma_f32_16x16x32_bf16 v[70:73], v[162:165], v[220:223], v[70:73]
	v_mfma_f32_16x16x32_bf16 v[66:69], v[170:173], v[220:223], v[66:69]
	v_mfma_f32_16x16x32_bf16 v[126:129], v[146:149], v[182:185], v[126:129]
	v_mfma_f32_16x16x32_bf16 v[122:125], v[154:157], v[182:185], v[122:125]
	v_mfma_f32_16x16x32_bf16 v[110:113], v[146:149], v[208:211], v[110:113]
	v_mfma_f32_16x16x32_bf16 v[106:109], v[154:157], v[208:211], v[106:109]
	v_mfma_f32_16x16x32_bf16 v[94:97], v[146:149], v[216:219], v[94:97]
	v_mfma_f32_16x16x32_bf16 v[90:93], v[154:157], v[216:219], v[90:93]
	v_mfma_f32_16x16x32_bf16 v[78:81], v[146:149], v[224:227], v[78:81]
	v_mfma_f32_16x16x32_bf16 v[74:77], v[154:157], v[224:227], v[74:77]
	v_mfma_f32_16x16x32_bf16 v[118:121], v[166:169], v[182:185], v[118:121]
	v_mfma_f32_16x16x32_bf16 v[114:117], v[174:177], v[182:185], v[114:117]
	v_mfma_f32_16x16x32_bf16 v[102:105], v[166:169], v[208:211], v[102:105]
	v_mfma_f32_16x16x32_bf16 v[98:101], v[174:177], v[208:211], v[98:101]
	v_mfma_f32_16x16x32_bf16 v[86:89], v[166:169], v[216:219], v[86:89]
	v_mfma_f32_16x16x32_bf16 v[82:85], v[174:177], v[216:219], v[82:85]
	v_mfma_f32_16x16x32_bf16 v[70:73], v[166:169], v[224:227], v[70:73]
	v_mfma_f32_16x16x32_bf16 v[66:69], v[174:177], v[224:227], v[66:69]
	s_barrier
	s_setprio 0
	s_add_i32 s63, s61, s70
	s_add_u32 s54, s54, 0x80
	s_addc_u32 s55, s55, 0
	s_mov_b32 m0, s63
	ds_read_b128 v[178:181], v161 offset:49152
	ds_read_b128 v[182:185], v161 offset:50176
	ds_read_b128 v[204:207], v161 offset:51200
	ds_read_b128 v[208:211], v161 offset:52224
	ds_read_b128 v[212:215], v161 offset:53248
	ds_read_b128 v[216:219], v161 offset:54272
	ds_read_b128 v[220:223], v161 offset:55296
	ds_read_b128 v[224:227], v161 offset:56320
	global_load_lds_dwordx4 v134, s[54:55]
	s_add_i32 m0, s63, 0x2000
	s_add_i32 s63, s62, s70
	global_load_lds_dwordx4 v130, s[54:55]
	s_add_u32 s54, s54, 0x40000
	s_addc_u32 s55, s55, 0
	s_mov_b32 m0, s63
	s_sub_u32 s56, s56, 0x3ff80
	global_load_lds_dwordx4 v134, s[54:55]
	s_subb_u32 s57, s57, 0
	s_add_i32 m0, s63, 0x2000
	s_nop 0
	global_load_lds_dwordx4 v130, s[54:55]
	s_mov_b32 m0, s86
	s_nop 0
	global_load_lds_dwordx4 v136, s[56:57]
	s_mov_b32 m0, s87
	s_nop 0
	global_load_lds_dwordx4 v132, s[56:57]
	s_waitcnt vmcnt(8)
	s_waitcnt lgkmcnt(0)
	s_setprio 1
	s_barrier
	v_mfma_f32_16x16x32_bf16 v[62:65], v[142:145], v[178:181], v[62:65]
	v_mfma_f32_16x16x32_bf16 v[58:61], v[150:153], v[178:181], v[58:61]
	v_mfma_f32_16x16x32_bf16 v[46:49], v[142:145], v[204:207], v[46:49]
	v_mfma_f32_16x16x32_bf16 v[42:45], v[150:153], v[204:207], v[42:45]
	v_mfma_f32_16x16x32_bf16 v[30:33], v[142:145], v[212:215], v[30:33]
	v_mfma_f32_16x16x32_bf16 v[26:29], v[150:153], v[212:215], v[26:29]
	v_mfma_f32_16x16x32_bf16 v[14:17], v[142:145], v[220:223], v[14:17]
	v_mfma_f32_16x16x32_bf16 v[10:13], v[150:153], v[220:223], v[10:13]
	v_mfma_f32_16x16x32_bf16 v[54:57], v[162:165], v[178:181], v[54:57]
	v_mfma_f32_16x16x32_bf16 v[50:53], v[170:173], v[178:181], v[50:53]
	v_mfma_f32_16x16x32_bf16 v[38:41], v[162:165], v[204:207], v[38:41]
	v_mfma_f32_16x16x32_bf16 v[34:37], v[170:173], v[204:207], v[34:37]
	v_mfma_f32_16x16x32_bf16 v[22:25], v[162:165], v[212:215], v[22:25]
	v_mfma_f32_16x16x32_bf16 v[18:21], v[170:173], v[212:215], v[18:21]
	v_mfma_f32_16x16x32_bf16 v[6:9], v[162:165], v[220:223], v[6:9]
	v_mfma_f32_16x16x32_bf16 v[2:5], v[170:173], v[220:223], v[2:5]
	v_mfma_f32_16x16x32_bf16 v[62:65], v[146:149], v[182:185], v[62:65]
	v_mfma_f32_16x16x32_bf16 v[58:61], v[154:157], v[182:185], v[58:61]
	v_mfma_f32_16x16x32_bf16 v[46:49], v[146:149], v[208:211], v[46:49]
	v_mfma_f32_16x16x32_bf16 v[42:45], v[154:157], v[208:211], v[42:45]
	v_mfma_f32_16x16x32_bf16 v[30:33], v[146:149], v[216:219], v[30:33]
	v_mfma_f32_16x16x32_bf16 v[26:29], v[154:157], v[216:219], v[26:29]
	v_mfma_f32_16x16x32_bf16 v[14:17], v[146:149], v[224:227], v[14:17]
	v_mfma_f32_16x16x32_bf16 v[10:13], v[154:157], v[224:227], v[10:13]
	v_mfma_f32_16x16x32_bf16 v[54:57], v[166:169], v[182:185], v[54:57]
	v_mfma_f32_16x16x32_bf16 v[50:53], v[174:177], v[182:185], v[50:53]
	v_mfma_f32_16x16x32_bf16 v[38:41], v[166:169], v[208:211], v[38:41]
	v_mfma_f32_16x16x32_bf16 v[34:37], v[174:177], v[208:211], v[34:37]
	v_mfma_f32_16x16x32_bf16 v[22:25], v[166:169], v[216:219], v[22:25]
	v_mfma_f32_16x16x32_bf16 v[18:21], v[174:177], v[216:219], v[18:21]
	v_mfma_f32_16x16x32_bf16 v[6:9], v[166:169], v[224:227], v[6:9]
	v_mfma_f32_16x16x32_bf16 v[2:5], v[174:177], v[224:227], v[2:5]
	s_barrier
	s_setprio 0
	s_add_i32 s60, s60, 2
	s_add_u32 s52, s52, 0x100
	s_addc_u32 s53, s53, 0
	s_add_u32 s58, s58, 0x100
	s_addc_u32 s59, s59, 0
	s_cmp_gt_u32 s60, 13
	s_cbranch_scc0 .LBB0_479
	s_and_b64 vcc, exec, s[38:39]
	s_cbranch_vccz .LBB0_482
	s_barrier

.Lrb4_skip:
	s_add_u32 s47, s52, 0xfffc0080
	s_addc_u32 s54, s53, -1
	s_add_i32 s68, 0, 0x10000
	s_cmp_eq_u32 s45, 12
	s_cselect_b32 s57, s1, s54
	s_cselect_b32 s56, s5, s47
	v_add_u32_e32 v0, s68, v221
	s_cselect_b32 s55, s6, s19
	s_cselect_b32 s54, s7, s18
	s_add_i32 s47, 0, 0x14000
	ds_read_b128 v[106:109], v0
	ds_read_b128 v[110:113], v0 offset:1024
	ds_read_b128 v[126:129], v0 offset:2048
	ds_read_b128 v[134:137], v0 offset:3072
	v_add_u32_e32 v0, s47, v221
	ds_read_b128 v[146:149], v0
	ds_read_b128 v[150:153], v0 offset:1024
	ds_read_b128 v[154:157], v0 offset:2048
	ds_read_b128 v[158:161], v0 offset:3072
	v_lshl_add_u64 v[216:217], s[52:53], 0, v[212:213]
	s_add_i32 m0, s59, 0xc000
	ds_read_b128 v[162:165], v222
	ds_read_b128 v[166:169], v222 offset:1024
	ds_read_b128 v[170:173], v222 offset:2048
	ds_read_b128 v[174:177], v222 offset:3072
	ds_read_b128 v[178:181], v222 offset:4096
	ds_read_b128 v[182:185], v222 offset:5120
	ds_read_b128 v[224:227], v222 offset:6144
	ds_read_b128 v[228:231], v222 offset:7168
	global_load_lds_dwordx4 v[216:217], off
	v_lshl_add_u64 v[216:217], s[52:53], 0, v[214:215]
	s_add_i32 m0, s59, 0xe000
	s_nop 0
	global_load_lds_dwordx4 v[216:217], off
	s_waitcnt vmcnt(8)
	s_waitcnt lgkmcnt(0)
	s_setprio 1
	s_barrier
	v_mfma_f32_16x16x32_bf16 v[142:145], v[106:109], v[162:165], 0
	v_mfma_f32_16x16x32_bf16 v[138:141], v[126:129], v[162:165], 0
	v_mfma_f32_16x16x32_bf16 v[118:121], v[106:109], v[170:173], 0
	v_mfma_f32_16x16x32_bf16 v[114:117], v[126:129], v[170:173], 0
	v_mfma_f32_16x16x32_bf16 v[94:97], v[106:109], v[178:181], 0
	v_mfma_f32_16x16x32_bf16 v[90:93], v[126:129], v[178:181], 0
	v_mfma_f32_16x16x32_bf16 v[78:81], v[106:109], v[224:227], 0
	v_mfma_f32_16x16x32_bf16 v[74:77], v[126:129], v[224:227], 0
	v_mfma_f32_16x16x32_bf16 v[130:133], v[146:149], v[162:165], 0
	v_mfma_f32_16x16x32_bf16 v[122:125], v[154:157], v[162:165], 0
	v_mfma_f32_16x16x32_bf16 v[102:105], v[146:149], v[170:173], 0
	v_mfma_f32_16x16x32_bf16 v[98:101], v[154:157], v[170:173], 0
	v_mfma_f32_16x16x32_bf16 v[86:89], v[146:149], v[178:181], 0
	v_mfma_f32_16x16x32_bf16 v[82:85], v[154:157], v[178:181], 0
	v_mfma_f32_16x16x32_bf16 v[70:73], v[146:149], v[224:227], 0
	v_mfma_f32_16x16x32_bf16 v[66:69], v[154:157], v[224:227], 0
	v_mfma_f32_16x16x32_bf16 v[142:145], v[110:113], v[166:169], v[142:145]
	v_mfma_f32_16x16x32_bf16 v[138:141], v[134:137], v[166:169], v[138:141]
	v_mfma_f32_16x16x32_bf16 v[118:121], v[110:113], v[174:177], v[118:121]
	v_mfma_f32_16x16x32_bf16 v[114:117], v[134:137], v[174:177], v[114:117]
	v_mfma_f32_16x16x32_bf16 v[94:97], v[110:113], v[182:185], v[94:97]
	v_mfma_f32_16x16x32_bf16 v[90:93], v[134:137], v[182:185], v[90:93]
	v_mfma_f32_16x16x32_bf16 v[78:81], v[110:113], v[228:231], v[78:81]
	v_mfma_f32_16x16x32_bf16 v[74:77], v[134:137], v[228:231], v[74:77]
	v_mfma_f32_16x16x32_bf16 v[130:133], v[150:153], v[166:169], v[130:133]
	v_mfma_f32_16x16x32_bf16 v[122:125], v[158:161], v[166:169], v[122:125]
	v_mfma_f32_16x16x32_bf16 v[102:105], v[150:153], v[174:177], v[102:105]
	v_mfma_f32_16x16x32_bf16 v[98:101], v[158:161], v[174:177], v[98:101]
	v_mfma_f32_16x16x32_bf16 v[86:89], v[150:153], v[182:185], v[86:89]
	v_mfma_f32_16x16x32_bf16 v[82:85], v[158:161], v[182:185], v[82:85]
	v_mfma_f32_16x16x32_bf16 v[70:73], v[150:153], v[228:231], v[70:73]
	v_mfma_f32_16x16x32_bf16 v[66:69], v[158:161], v[228:231], v[66:69]
	s_barrier
	s_setprio 0
	s_add_i32 s68, s68, s58
	v_lshl_add_u64 v[216:217], s[54:55], 0, v[208:209]
	s_mov_b32 m0, s68
	ds_read_b128 v[162:165], v222 offset:16384
	ds_read_b128 v[166:169], v222 offset:17408
	ds_read_b128 v[170:173], v222 offset:18432
	ds_read_b128 v[174:177], v222 offset:19456
	ds_read_b128 v[178:181], v222 offset:20480
	ds_read_b128 v[182:185], v222 offset:21504
	ds_read_b128 v[224:227], v222 offset:22528
	ds_read_b128 v[228:231], v222 offset:23552
	global_load_lds_dwordx4 v[216:217], off
	s_add_i32 m0, s68, 0x2000
	s_add_u32 s68, s54, 0x40000
	v_lshl_add_u64 v[240:241], s[54:55], 0, v[204:205]
	s_addc_u32 s69, s55, 0
	s_add_i32 s47, s47, s58
	global_load_lds_dwordx4 v[240:241], off
	v_lshl_add_u64 v[242:243], s[68:69], 0, v[208:209]
	s_mov_b32 m0, s47
	v_lshl_add_u64 v[244:245], s[56:57], 0, v[206:207]
	global_load_lds_dwordx4 v[242:243], off
	v_lshl_add_u64 v[242:243], s[68:69], 0, v[204:205]
	s_add_i32 m0, s47, 0x2000
	s_nop 0
	global_load_lds_dwordx4 v[242:243], off
	v_lshl_add_u64 v[242:243], s[56:57], 0, v[210:211]
	s_mov_b32 m0, s59
	s_nop 0
	global_load_lds_dwordx4 v[242:243], off
	s_mov_b32 m0, s60
	s_nop 0
	global_load_lds_dwordx4 v[244:245], off
	s_waitcnt vmcnt(8)
	s_waitcnt lgkmcnt(0)
	s_setprio 1
	s_barrier
	v_mfma_f32_16x16x32_bf16 v[62:65], v[106:109], v[162:165], 0
	v_mfma_f32_16x16x32_bf16 v[58:61], v[126:129], v[162:165], 0
	v_mfma_f32_16x16x32_bf16 v[46:49], v[106:109], v[170:173], 0
	v_mfma_f32_16x16x32_bf16 v[42:45], v[126:129], v[170:173], 0
	v_mfma_f32_16x16x32_bf16 v[30:33], v[106:109], v[178:181], 0
	v_mfma_f32_16x16x32_bf16 v[26:29], v[126:129], v[178:181], 0
	v_mfma_f32_16x16x32_bf16 v[14:17], v[106:109], v[224:227], 0
	v_mfma_f32_16x16x32_bf16 v[10:13], v[126:129], v[224:227], 0
	v_mfma_f32_16x16x32_bf16 v[54:57], v[146:149], v[162:165], 0
	v_mfma_f32_16x16x32_bf16 v[50:53], v[154:157], v[162:165], 0
	v_mfma_f32_16x16x32_bf16 v[38:41], v[146:149], v[170:173], 0
	v_mfma_f32_16x16x32_bf16 v[34:37], v[154:157], v[170:173], 0
	v_mfma_f32_16x16x32_bf16 v[22:25], v[146:149], v[178:181], 0
	v_mfma_f32_16x16x32_bf16 v[18:21], v[154:157], v[178:181], 0
	v_mfma_f32_16x16x32_bf16 v[6:9], v[146:149], v[224:227], 0
	v_mfma_f32_16x16x32_bf16 v[2:5], v[154:157], v[224:227], 0
	v_mfma_f32_16x16x32_bf16 v[62:65], v[110:113], v[166:169], v[62:65]
	v_mfma_f32_16x16x32_bf16 v[58:61], v[134:137], v[166:169], v[58:61]
	v_mfma_f32_16x16x32_bf16 v[46:49], v[110:113], v[174:177], v[46:49]
	v_mfma_f32_16x16x32_bf16 v[42:45], v[134:137], v[174:177], v[42:45]
	v_mfma_f32_16x16x32_bf16 v[30:33], v[110:113], v[182:185], v[30:33]
	v_mfma_f32_16x16x32_bf16 v[26:29], v[134:137], v[182:185], v[26:29]
	v_mfma_f32_16x16x32_bf16 v[14:17], v[110:113], v[228:231], v[14:17]
	v_mfma_f32_16x16x32_bf16 v[10:13], v[134:137], v[228:231], v[10:13]
	v_mfma_f32_16x16x32_bf16 v[54:57], v[150:153], v[166:169], v[54:57]
	v_mfma_f32_16x16x32_bf16 v[50:53], v[158:161], v[166:169], v[50:53]
	v_mfma_f32_16x16x32_bf16 v[38:41], v[150:153], v[174:177], v[38:41]
	v_mfma_f32_16x16x32_bf16 v[34:37], v[158:161], v[174:177], v[34:37]
	v_mfma_f32_16x16x32_bf16 v[22:25], v[150:153], v[182:185], v[22:25]
	v_mfma_f32_16x16x32_bf16 v[18:21], v[158:161], v[182:185], v[18:21]
	v_mfma_f32_16x16x32_bf16 v[6:9], v[150:153], v[228:231], v[6:9]
	v_mfma_f32_16x16x32_bf16 v[2:5], v[158:161], v[228:231], v[2:5]
	s_barrier
	s_setprio 0
	s_add_i32 s47, 0, 0x18000
	v_add_u32_e32 v0, s47, v221
	s_add_i32 s68, 0, 0x1c000
	ds_read_b128 v[106:109], v0
	ds_read_b128 v[110:113], v0 offset:1024
	ds_read_b128 v[126:129], v0 offset:2048
	ds_read_b128 v[134:137], v0 offset:3072
	v_add_u32_e32 v0, s68, v221
	ds_read_b128 v[146:149], v0
	ds_read_b128 v[150:153], v0 offset:1024
	ds_read_b128 v[154:157], v0 offset:2048
	ds_read_b128 v[158:161], v0 offset:3072
	s_add_u32 s56, s56, 0x40000
	s_addc_u32 s57, s57, 0
	s_mov_b32 m0, s61
	v_lshl_add_u64 v[246:247], s[56:57], 0, v[210:211]
	ds_read_b128 v[162:165], v222 offset:32768
	ds_read_b128 v[166:169], v222 offset:33792
	ds_read_b128 v[170:173], v222 offset:34816
	ds_read_b128 v[174:177], v222 offset:35840
	ds_read_b128 v[178:181], v222 offset:36864
	ds_read_b128 v[182:185], v222 offset:37888
	ds_read_b128 v[224:227], v222 offset:38912
	ds_read_b128 v[228:231], v222 offset:39936
	global_load_lds_dwordx4 v[246:247], off
	v_lshl_add_u64 v[246:247], s[56:57], 0, v[206:207]
	s_mov_b32 m0, s62
	s_nop 0
	global_load_lds_dwordx4 v[246:247], off
	s_waitcnt vmcnt(8)
	s_waitcnt lgkmcnt(0)
	s_setprio 1
	s_barrier
	v_mfma_f32_16x16x32_bf16 v[142:145], v[106:109], v[162:165], v[142:145]
	v_mfma_f32_16x16x32_bf16 v[138:141], v[126:129], v[162:165], v[138:141]
	v_mfma_f32_16x16x32_bf16 v[118:121], v[106:109], v[170:173], v[118:121]
	v_mfma_f32_16x16x32_bf16 v[114:117], v[126:129], v[170:173], v[114:117]
	v_mfma_f32_16x16x32_bf16 v[94:97], v[106:109], v[178:181], v[94:97]
	v_mfma_f32_16x16x32_bf16 v[90:93], v[126:129], v[178:181], v[90:93]
	v_mfma_f32_16x16x32_bf16 v[78:81], v[106:109], v[224:227], v[78:81]
	v_mfma_f32_16x16x32_bf16 v[74:77], v[126:129], v[224:227], v[74:77]
	v_mfma_f32_16x16x32_bf16 v[130:133], v[146:149], v[162:165], v[130:133]
	v_mfma_f32_16x16x32_bf16 v[122:125], v[154:157], v[162:165], v[122:125]
	v_mfma_f32_16x16x32_bf16 v[102:105], v[146:149], v[170:173], v[102:105]
	v_mfma_f32_16x16x32_bf16 v[98:101], v[154:157], v[170:173], v[98:101]
	v_mfma_f32_16x16x32_bf16 v[86:89], v[146:149], v[178:181], v[86:89]
	v_mfma_f32_16x16x32_bf16 v[82:85], v[154:157], v[178:181], v[82:85]
	v_mfma_f32_16x16x32_bf16 v[70:73], v[146:149], v[224:227], v[70:73]
	v_mfma_f32_16x16x32_bf16 v[66:69], v[154:157], v[224:227], v[66:69]
	v_mfma_f32_16x16x32_bf16 v[142:145], v[110:113], v[166:169], v[142:145]
	v_mfma_f32_16x16x32_bf16 v[138:141], v[134:137], v[166:169], v[138:141]
	v_mfma_f32_16x16x32_bf16 v[118:121], v[110:113], v[174:177], v[118:121]
	v_mfma_f32_16x16x32_bf16 v[114:117], v[134:137], v[174:177], v[114:117]
	v_mfma_f32_16x16x32_bf16 v[94:97], v[110:113], v[182:185], v[94:97]
	v_mfma_f32_16x16x32_bf16 v[90:93], v[134:137], v[182:185], v[90:93]
	v_mfma_f32_16x16x32_bf16 v[78:81], v[110:113], v[228:231], v[78:81]
	v_mfma_f32_16x16x32_bf16 v[74:77], v[134:137], v[228:231], v[74:77]
	v_mfma_f32_16x16x32_bf16 v[130:133], v[150:153], v[166:169], v[130:133]
	v_mfma_f32_16x16x32_bf16 v[122:125], v[158:161], v[166:169], v[122:125]
	v_mfma_f32_16x16x32_bf16 v[102:105], v[150:153], v[174:177], v[102:105]
	v_mfma_f32_16x16x32_bf16 v[98:101], v[158:161], v[174:177], v[98:101]
	v_mfma_f32_16x16x32_bf16 v[86:89], v[150:153], v[182:185], v[86:89]
	v_mfma_f32_16x16x32_bf16 v[82:85], v[158:161], v[182:185], v[82:85]
	v_mfma_f32_16x16x32_bf16 v[70:73], v[150:153], v[228:231], v[70:73]
	v_mfma_f32_16x16x32_bf16 v[66:69], v[158:161], v[228:231], v[66:69]
	s_barrier
	s_setprio 0
	s_add_i32 s47, s47, s58
	v_lshl_add_u64 v[216:217], v[216:217], 0, s[16:17]
	s_mov_b32 m0, s47
	ds_read_b128 v[162:165], v222 offset:49152
	ds_read_b128 v[166:169], v222 offset:50176
	ds_read_b128 v[170:173], v222 offset:51200
	ds_read_b128 v[174:177], v222 offset:52224
	ds_read_b128 v[178:181], v222 offset:53248
	ds_read_b128 v[182:185], v222 offset:54272
	ds_read_b128 v[224:227], v222 offset:55296
	ds_read_b128 v[228:231], v222 offset:56320
	global_load_lds_dwordx4 v[216:217], off
	s_add_i32 m0, s47, 0x2000
	s_add_u32 s54, s54, 0x40080
	v_lshl_add_u64 v[216:217], v[240:241], 0, s[16:17]
	s_addc_u32 s55, s55, 0
	s_add_i32 s47, s68, s58
	global_load_lds_dwordx4 v[216:217], off
	v_lshl_add_u64 v[216:217], s[54:55], 0, v[208:209]
	s_mov_b32 m0, s47
	s_nop 0
	global_load_lds_dwordx4 v[216:217], off
	v_lshl_add_u64 v[216:217], s[54:55], 0, v[204:205]
	s_add_i32 m0, s47, 0x2000
	s_nop 0
	global_load_lds_dwordx4 v[216:217], off
	v_lshl_add_u64 v[216:217], v[242:243], 0, s[16:17]
	s_mov_b32 m0, s65
	s_nop 0
	global_load_lds_dwordx4 v[216:217], off
	v_lshl_add_u64 v[216:217], v[244:245], 0, s[16:17]
	s_mov_b32 m0, s66
	s_nop 0
	global_load_lds_dwordx4 v[216:217], off
	s_waitcnt vmcnt(8)
	s_waitcnt lgkmcnt(0)
	s_setprio 1
	s_barrier
	v_mfma_f32_16x16x32_bf16 v[62:65], v[106:109], v[162:165], v[62:65]
	v_mfma_f32_16x16x32_bf16 v[58:61], v[126:129], v[162:165], v[58:61]
	v_mfma_f32_16x16x32_bf16 v[46:49], v[106:109], v[170:173], v[46:49]
	v_mfma_f32_16x16x32_bf16 v[42:45], v[126:129], v[170:173], v[42:45]
	v_mfma_f32_16x16x32_bf16 v[30:33], v[106:109], v[178:181], v[30:33]
	v_mfma_f32_16x16x32_bf16 v[26:29], v[126:129], v[178:181], v[26:29]
	v_mfma_f32_16x16x32_bf16 v[14:17], v[106:109], v[224:227], v[14:17]
	v_mfma_f32_16x16x32_bf16 v[10:13], v[126:129], v[224:227], v[10:13]
	v_mfma_f32_16x16x32_bf16 v[54:57], v[146:149], v[162:165], v[54:57]
	v_mfma_f32_16x16x32_bf16 v[50:53], v[154:157], v[162:165], v[50:53]
	v_mfma_f32_16x16x32_bf16 v[38:41], v[146:149], v[170:173], v[38:41]
	v_mfma_f32_16x16x32_bf16 v[34:37], v[154:157], v[170:173], v[34:37]
	v_mfma_f32_16x16x32_bf16 v[22:25], v[146:149], v[178:181], v[22:25]
	v_mfma_f32_16x16x32_bf16 v[18:21], v[154:157], v[178:181], v[18:21]
	v_mfma_f32_16x16x32_bf16 v[6:9], v[146:149], v[224:227], v[6:9]
	v_mfma_f32_16x16x32_bf16 v[2:5], v[154:157], v[224:227], v[2:5]
	v_mfma_f32_16x16x32_bf16 v[62:65], v[110:113], v[166:169], v[62:65]
	v_mfma_f32_16x16x32_bf16 v[58:61], v[134:137], v[166:169], v[58:61]
	v_mfma_f32_16x16x32_bf16 v[46:49], v[110:113], v[174:177], v[46:49]
	v_mfma_f32_16x16x32_bf16 v[42:45], v[134:137], v[174:177], v[42:45]
	v_mfma_f32_16x16x32_bf16 v[30:33], v[110:113], v[182:185], v[30:33]
	v_mfma_f32_16x16x32_bf16 v[26:29], v[134:137], v[182:185], v[26:29]
	v_mfma_f32_16x16x32_bf16 v[14:17], v[110:113], v[228:231], v[14:17]
	v_mfma_f32_16x16x32_bf16 v[10:13], v[134:137], v[228:231], v[10:13]
	v_mfma_f32_16x16x32_bf16 v[54:57], v[150:153], v[166:169], v[54:57]
	v_mfma_f32_16x16x32_bf16 v[50:53], v[158:161], v[166:169], v[50:53]
	v_mfma_f32_16x16x32_bf16 v[38:41], v[150:153], v[174:177], v[38:41]
	v_mfma_f32_16x16x32_bf16 v[34:37], v[158:161], v[174:177], v[34:37]
	v_mfma_f32_16x16x32_bf16 v[22:25], v[150:153], v[182:185], v[22:25]
	v_mfma_f32_16x16x32_bf16 v[18:21], v[158:161], v[182:185], v[18:21]
	v_mfma_f32_16x16x32_bf16 v[6:9], v[150:153], v[228:231], v[6:9]
	v_mfma_f32_16x16x32_bf16 v[2:5], v[158:161], v[228:231], v[2:5]
	s_barrier
	s_setprio 0
	s_add_i32 s45, s45, 2
	s_add_u32 s52, s52, 0x100
	s_addc_u32 s53, s53, 0
	s_add_u32 s18, s18, 0x100
	s_addc_u32 s19, s19, 0
	s_cmp_gt_u32 s45, 13
.LBB0_900:
	s_add_u32 s47, s52, 0xfffc0080
	s_addc_u32 s54, s53, -1
	s_add_i32 s68, 0, 0x10000
	s_cmp_eq_u32 s45, 12
	s_cselect_b32 s57, s1, s54
	s_cselect_b32 s56, s5, s47
	v_add_u32_e32 v0, s68, v221
	s_cselect_b32 s55, s6, s19
	s_cselect_b32 s54, s7, s18
	s_add_i32 s47, 0, 0x14000
	ds_read_b128 v[106:109], v0
	ds_read_b128 v[110:113], v0 offset:1024
	ds_read_b128 v[126:129], v0 offset:2048
	ds_read_b128 v[134:137], v0 offset:3072
	v_add_u32_e32 v0, s47, v221
	ds_read_b128 v[146:149], v0
	ds_read_b128 v[150:153], v0 offset:1024
	ds_read_b128 v[154:157], v0 offset:2048
	ds_read_b128 v[158:161], v0 offset:3072
	v_lshl_add_u64 v[216:217], s[52:53], 0, v[212:213]
	s_add_i32 m0, s59, 0xc000
	ds_read_b128 v[162:165], v222
	ds_read_b128 v[166:169], v222 offset:1024
	ds_read_b128 v[170:173], v222 offset:2048
	ds_read_b128 v[174:177], v222 offset:3072
	ds_read_b128 v[178:181], v222 offset:4096
	ds_read_b128 v[182:185], v222 offset:5120
	ds_read_b128 v[224:227], v222 offset:6144
	ds_read_b128 v[228:231], v222 offset:7168
	global_load_lds_dwordx4 v[216:217], off
	v_lshl_add_u64 v[216:217], s[52:53], 0, v[214:215]
	s_add_i32 m0, s59, 0xe000
	s_nop 0
	global_load_lds_dwordx4 v[216:217], off
	s_waitcnt vmcnt(8)
	s_waitcnt lgkmcnt(0)
	s_setprio 1
	s_barrier
	v_mfma_f32_16x16x32_bf16 v[142:145], v[106:109], v[162:165], v[142:145]
	v_mfma_f32_16x16x32_bf16 v[138:141], v[126:129], v[162:165], v[138:141]
	v_mfma_f32_16x16x32_bf16 v[118:121], v[106:109], v[170:173], v[118:121]
	v_mfma_f32_16x16x32_bf16 v[114:117], v[126:129], v[170:173], v[114:117]
	v_mfma_f32_16x16x32_bf16 v[94:97], v[106:109], v[178:181], v[94:97]
	v_mfma_f32_16x16x32_bf16 v[90:93], v[126:129], v[178:181], v[90:93]
	v_mfma_f32_16x16x32_bf16 v[78:81], v[106:109], v[224:227], v[78:81]
	v_mfma_f32_16x16x32_bf16 v[74:77], v[126:129], v[224:227], v[74:77]
	v_mfma_f32_16x16x32_bf16 v[130:133], v[146:149], v[162:165], v[130:133]
	v_mfma_f32_16x16x32_bf16 v[122:125], v[154:157], v[162:165], v[122:125]
	v_mfma_f32_16x16x32_bf16 v[102:105], v[146:149], v[170:173], v[102:105]
	v_mfma_f32_16x16x32_bf16 v[98:101], v[154:157], v[170:173], v[98:101]
	v_mfma_f32_16x16x32_bf16 v[86:89], v[146:149], v[178:181], v[86:89]
	v_mfma_f32_16x16x32_bf16 v[82:85], v[154:157], v[178:181], v[82:85]
	v_mfma_f32_16x16x32_bf16 v[70:73], v[146:149], v[224:227], v[70:73]
	v_mfma_f32_16x16x32_bf16 v[66:69], v[154:157], v[224:227], v[66:69]
	v_mfma_f32_16x16x32_bf16 v[142:145], v[110:113], v[166:169], v[142:145]
	v_mfma_f32_16x16x32_bf16 v[138:141], v[134:137], v[166:169], v[138:141]
	v_mfma_f32_16x16x32_bf16 v[118:121], v[110:113], v[174:177], v[118:121]
	v_mfma_f32_16x16x32_bf16 v[114:117], v[134:137], v[174:177], v[114:117]
	v_mfma_f32_16x16x32_bf16 v[94:97], v[110:113], v[182:185], v[94:97]
	v_mfma_f32_16x16x32_bf16 v[90:93], v[134:137], v[182:185], v[90:93]
	v_mfma_f32_16x16x32_bf16 v[78:81], v[110:113], v[228:231], v[78:81]
	v_mfma_f32_16x16x32_bf16 v[74:77], v[134:137], v[228:231], v[74:77]
	v_mfma_f32_16x16x32_bf16 v[130:133], v[150:153], v[166:169], v[130:133]
	v_mfma_f32_16x16x32_bf16 v[122:125], v[158:161], v[166:169], v[122:125]
	v_mfma_f32_16x16x32_bf16 v[102:105], v[150:153], v[174:177], v[102:105]
	v_mfma_f32_16x16x32_bf16 v[98:101], v[158:161], v[174:177], v[98:101]
	v_mfma_f32_16x16x32_bf16 v[86:89], v[150:153], v[182:185], v[86:89]
	v_mfma_f32_16x16x32_bf16 v[82:85], v[158:161], v[182:185], v[82:85]
	v_mfma_f32_16x16x32_bf16 v[70:73], v[150:153], v[228:231], v[70:73]
	v_mfma_f32_16x16x32_bf16 v[66:69], v[158:161], v[228:231], v[66:69]
	s_barrier
	s_setprio 0
	s_add_i32 s68, s68, s58
	v_lshl_add_u64 v[216:217], s[54:55], 0, v[208:209]
	s_mov_b32 m0, s68
	ds_read_b128 v[162:165], v222 offset:16384
	ds_read_b128 v[166:169], v222 offset:17408
	ds_read_b128 v[170:173], v222 offset:18432
	ds_read_b128 v[174:177], v222 offset:19456
	ds_read_b128 v[178:181], v222 offset:20480
	ds_read_b128 v[182:185], v222 offset:21504
	ds_read_b128 v[224:227], v222 offset:22528
	ds_read_b128 v[228:231], v222 offset:23552
	global_load_lds_dwordx4 v[216:217], off
	s_add_i32 m0, s68, 0x2000
	s_add_u32 s68, s54, 0x40000
	v_lshl_add_u64 v[240:241], s[54:55], 0, v[204:205]
	s_addc_u32 s69, s55, 0
	s_add_i32 s47, s47, s58
	global_load_lds_dwordx4 v[240:241], off
	v_lshl_add_u64 v[242:243], s[68:69], 0, v[208:209]
	s_mov_b32 m0, s47
	v_lshl_add_u64 v[244:245], s[56:57], 0, v[206:207]
	global_load_lds_dwordx4 v[242:243], off
	v_lshl_add_u64 v[242:243], s[68:69], 0, v[204:205]
	s_add_i32 m0, s47, 0x2000
	s_nop 0
	global_load_lds_dwordx4 v[242:243], off
	v_lshl_add_u64 v[242:243], s[56:57], 0, v[210:211]
	s_mov_b32 m0, s59
	s_nop 0
	global_load_lds_dwordx4 v[242:243], off
	s_mov_b32 m0, s60
	s_nop 0
	global_load_lds_dwordx4 v[244:245], off
	s_waitcnt vmcnt(8)
	s_waitcnt lgkmcnt(0)
	s_setprio 1
	s_barrier
	v_mfma_f32_16x16x32_bf16 v[62:65], v[106:109], v[162:165], v[62:65]
	v_mfma_f32_16x16x32_bf16 v[58:61], v[126:129], v[162:165], v[58:61]
	v_mfma_f32_16x16x32_bf16 v[46:49], v[106:109], v[170:173], v[46:49]
	v_mfma_f32_16x16x32_bf16 v[42:45], v[126:129], v[170:173], v[42:45]
	v_mfma_f32_16x16x32_bf16 v[30:33], v[106:109], v[178:181], v[30:33]
	v_mfma_f32_16x16x32_bf16 v[26:29], v[126:129], v[178:181], v[26:29]
	v_mfma_f32_16x16x32_bf16 v[14:17], v[106:109], v[224:227], v[14:17]
	v_mfma_f32_16x16x32_bf16 v[10:13], v[126:129], v[224:227], v[10:13]
	v_mfma_f32_16x16x32_bf16 v[54:57], v[146:149], v[162:165], v[54:57]
	v_mfma_f32_16x16x32_bf16 v[50:53], v[154:157], v[162:165], v[50:53]
	v_mfma_f32_16x16x32_bf16 v[38:41], v[146:149], v[170:173], v[38:41]
	v_mfma_f32_16x16x32_bf16 v[34:37], v[154:157], v[170:173], v[34:37]
	v_mfma_f32_16x16x32_bf16 v[22:25], v[146:149], v[178:181], v[22:25]
	v_mfma_f32_16x16x32_bf16 v[18:21], v[154:157], v[178:181], v[18:21]
	v_mfma_f32_16x16x32_bf16 v[6:9], v[146:149], v[224:227], v[6:9]
	v_mfma_f32_16x16x32_bf16 v[2:5], v[154:157], v[224:227], v[2:5]
	v_mfma_f32_16x16x32_bf16 v[62:65], v[110:113], v[166:169], v[62:65]
	v_mfma_f32_16x16x32_bf16 v[58:61], v[134:137], v[166:169], v[58:61]
	v_mfma_f32_16x16x32_bf16 v[46:49], v[110:113], v[174:177], v[46:49]
	v_mfma_f32_16x16x32_bf16 v[42:45], v[134:137], v[174:177], v[42:45]
	v_mfma_f32_16x16x32_bf16 v[30:33], v[110:113], v[182:185], v[30:33]
	v_mfma_f32_16x16x32_bf16 v[26:29], v[134:137], v[182:185], v[26:29]
	v_mfma_f32_16x16x32_bf16 v[14:17], v[110:113], v[228:231], v[14:17]
	v_mfma_f32_16x16x32_bf16 v[10:13], v[134:137], v[228:231], v[10:13]
	v_mfma_f32_16x16x32_bf16 v[54:57], v[150:153], v[166:169], v[54:57]
	v_mfma_f32_16x16x32_bf16 v[50:53], v[158:161], v[166:169], v[50:53]
	v_mfma_f32_16x16x32_bf16 v[38:41], v[150:153], v[174:177], v[38:41]
	v_mfma_f32_16x16x32_bf16 v[34:37], v[158:161], v[174:177], v[34:37]
	v_mfma_f32_16x16x32_bf16 v[22:25], v[150:153], v[182:185], v[22:25]
	v_mfma_f32_16x16x32_bf16 v[18:21], v[158:161], v[182:185], v[18:21]
	v_mfma_f32_16x16x32_bf16 v[6:9], v[150:153], v[228:231], v[6:9]
	v_mfma_f32_16x16x32_bf16 v[2:5], v[158:161], v[228:231], v[2:5]
	s_barrier
	s_setprio 0
	s_add_i32 s47, 0, 0x18000
	v_add_u32_e32 v0, s47, v221
	s_add_i32 s68, 0, 0x1c000
	ds_read_b128 v[106:109], v0
	ds_read_b128 v[110:113], v0 offset:1024
	ds_read_b128 v[126:129], v0 offset:2048
	ds_read_b128 v[134:137], v0 offset:3072
	v_add_u32_e32 v0, s68, v221
	ds_read_b128 v[146:149], v0
	ds_read_b128 v[150:153], v0 offset:1024
	ds_read_b128 v[154:157], v0 offset:2048
	ds_read_b128 v[158:161], v0 offset:3072
	s_add_u32 s56, s56, 0x40000
	s_addc_u32 s57, s57, 0
	s_mov_b32 m0, s61
	v_lshl_add_u64 v[246:247], s[56:57], 0, v[210:211]
	ds_read_b128 v[162:165], v222 offset:32768
	ds_read_b128 v[166:169], v222 offset:33792
	ds_read_b128 v[170:173], v222 offset:34816
	ds_read_b128 v[174:177], v222 offset:35840
	ds_read_b128 v[178:181], v222 offset:36864
	ds_read_b128 v[182:185], v222 offset:37888
	ds_read_b128 v[224:227], v222 offset:38912
	ds_read_b128 v[228:231], v222 offset:39936
	global_load_lds_dwordx4 v[246:247], off
	v_lshl_add_u64 v[246:247], s[56:57], 0, v[206:207]
	s_mov_b32 m0, s62
	s_nop 0
	global_load_lds_dwordx4 v[246:247], off
	s_waitcnt vmcnt(8)
	s_waitcnt lgkmcnt(0)
	s_setprio 1
	s_barrier
	v_mfma_f32_16x16x32_bf16 v[142:145], v[106:109], v[162:165], v[142:145]
	v_mfma_f32_16x16x32_bf16 v[138:141], v[126:129], v[162:165], v[138:141]
	v_mfma_f32_16x16x32_bf16 v[118:121], v[106:109], v[170:173], v[118:121]
	v_mfma_f32_16x16x32_bf16 v[114:117], v[126:129], v[170:173], v[114:117]
	v_mfma_f32_16x16x32_bf16 v[94:97], v[106:109], v[178:181], v[94:97]
	v_mfma_f32_16x16x32_bf16 v[90:93], v[126:129], v[178:181], v[90:93]
	v_mfma_f32_16x16x32_bf16 v[78:81], v[106:109], v[224:227], v[78:81]
	v_mfma_f32_16x16x32_bf16 v[74:77], v[126:129], v[224:227], v[74:77]
	v_mfma_f32_16x16x32_bf16 v[130:133], v[146:149], v[162:165], v[130:133]
	v_mfma_f32_16x16x32_bf16 v[122:125], v[154:157], v[162:165], v[122:125]
	v_mfma_f32_16x16x32_bf16 v[102:105], v[146:149], v[170:173], v[102:105]
	v_mfma_f32_16x16x32_bf16 v[98:101], v[154:157], v[170:173], v[98:101]
	v_mfma_f32_16x16x32_bf16 v[86:89], v[146:149], v[178:181], v[86:89]
	v_mfma_f32_16x16x32_bf16 v[82:85], v[154:157], v[178:181], v[82:85]
	v_mfma_f32_16x16x32_bf16 v[70:73], v[146:149], v[224:227], v[70:73]
	v_mfma_f32_16x16x32_bf16 v[66:69], v[154:157], v[224:227], v[66:69]
	v_mfma_f32_16x16x32_bf16 v[142:145], v[110:113], v[166:169], v[142:145]
	v_mfma_f32_16x16x32_bf16 v[138:141], v[134:137], v[166:169], v[138:141]
	v_mfma_f32_16x16x32_bf16 v[118:121], v[110:113], v[174:177], v[118:121]
	v_mfma_f32_16x16x32_bf16 v[114:117], v[134:137], v[174:177], v[114:117]
	v_mfma_f32_16x16x32_bf16 v[94:97], v[110:113], v[182:185], v[94:97]
	v_mfma_f32_16x16x32_bf16 v[90:93], v[134:137], v[182:185], v[90:93]
	v_mfma_f32_16x16x32_bf16 v[78:81], v[110:113], v[228:231], v[78:81]
	v_mfma_f32_16x16x32_bf16 v[74:77], v[134:137], v[228:231], v[74:77]
	v_mfma_f32_16x16x32_bf16 v[130:133], v[150:153], v[166:169], v[130:133]
	v_mfma_f32_16x16x32_bf16 v[122:125], v[158:161], v[166:169], v[122:125]
	v_mfma_f32_16x16x32_bf16 v[102:105], v[150:153], v[174:177], v[102:105]
	v_mfma_f32_16x16x32_bf16 v[98:101], v[158:161], v[174:177], v[98:101]
	v_mfma_f32_16x16x32_bf16 v[86:89], v[150:153], v[182:185], v[86:89]
	v_mfma_f32_16x16x32_bf16 v[82:85], v[158:161], v[182:185], v[82:85]
	v_mfma_f32_16x16x32_bf16 v[70:73], v[150:153], v[228:231], v[70:73]
	v_mfma_f32_16x16x32_bf16 v[66:69], v[158:161], v[228:231], v[66:69]
	s_barrier
	s_setprio 0
	s_add_i32 s47, s47, s58
	v_lshl_add_u64 v[216:217], v[216:217], 0, s[16:17]
	s_mov_b32 m0, s47
	ds_read_b128 v[162:165], v222 offset:49152
	ds_read_b128 v[166:169], v222 offset:50176
	ds_read_b128 v[170:173], v222 offset:51200
	ds_read_b128 v[174:177], v222 offset:52224
	ds_read_b128 v[178:181], v222 offset:53248
	ds_read_b128 v[182:185], v222 offset:54272
	ds_read_b128 v[224:227], v222 offset:55296
	ds_read_b128 v[228:231], v222 offset:56320
	global_load_lds_dwordx4 v[216:217], off
	s_add_i32 m0, s47, 0x2000
	s_add_u32 s54, s54, 0x40080
	v_lshl_add_u64 v[216:217], v[240:241], 0, s[16:17]
	s_addc_u32 s55, s55, 0
	s_add_i32 s47, s68, s58
	global_load_lds_dwordx4 v[216:217], off
	v_lshl_add_u64 v[216:217], s[54:55], 0, v[208:209]
	s_mov_b32 m0, s47
	s_nop 0
	global_load_lds_dwordx4 v[216:217], off
	v_lshl_add_u64 v[216:217], s[54:55], 0, v[204:205]
	s_add_i32 m0, s47, 0x2000
	s_nop 0
	global_load_lds_dwordx4 v[216:217], off
	v_lshl_add_u64 v[216:217], v[242:243], 0, s[16:17]
	s_mov_b32 m0, s65
	s_nop 0
	global_load_lds_dwordx4 v[216:217], off
	v_lshl_add_u64 v[216:217], v[244:245], 0, s[16:17]
	s_mov_b32 m0, s66
	s_nop 0
	global_load_lds_dwordx4 v[216:217], off
	s_waitcnt vmcnt(8)
	s_waitcnt lgkmcnt(0)
	s_setprio 1
	s_barrier
	v_mfma_f32_16x16x32_bf16 v[62:65], v[106:109], v[162:165], v[62:65]
	v_mfma_f32_16x16x32_bf16 v[58:61], v[126:129], v[162:165], v[58:61]
	v_mfma_f32_16x16x32_bf16 v[46:49], v[106:109], v[170:173], v[46:49]
	v_mfma_f32_16x16x32_bf16 v[42:45], v[126:129], v[170:173], v[42:45]
	v_mfma_f32_16x16x32_bf16 v[30:33], v[106:109], v[178:181], v[30:33]
	v_mfma_f32_16x16x32_bf16 v[26:29], v[126:129], v[178:181], v[26:29]
	v_mfma_f32_16x16x32_bf16 v[14:17], v[106:109], v[224:227], v[14:17]
	v_mfma_f32_16x16x32_bf16 v[10:13], v[126:129], v[224:227], v[10:13]
	v_mfma_f32_16x16x32_bf16 v[54:57], v[146:149], v[162:165], v[54:57]
	v_mfma_f32_16x16x32_bf16 v[50:53], v[154:157], v[162:165], v[50:53]
	v_mfma_f32_16x16x32_bf16 v[38:41], v[146:149], v[170:173], v[38:41]
	v_mfma_f32_16x16x32_bf16 v[34:37], v[154:157], v[170:173], v[34:37]
	v_mfma_f32_16x16x32_bf16 v[22:25], v[146:149], v[178:181], v[22:25]
	v_mfma_f32_16x16x32_bf16 v[18:21], v[154:157], v[178:181], v[18:21]
	v_mfma_f32_16x16x32_bf16 v[6:9], v[146:149], v[224:227], v[6:9]
	v_mfma_f32_16x16x32_bf16 v[2:5], v[154:157], v[224:227], v[2:5]
	v_mfma_f32_16x16x32_bf16 v[62:65], v[110:113], v[166:169], v[62:65]
	v_mfma_f32_16x16x32_bf16 v[58:61], v[134:137], v[166:169], v[58:61]
	v_mfma_f32_16x16x32_bf16 v[46:49], v[110:113], v[174:177], v[46:49]
	v_mfma_f32_16x16x32_bf16 v[42:45], v[134:137], v[174:177], v[42:45]
	v_mfma_f32_16x16x32_bf16 v[30:33], v[110:113], v[182:185], v[30:33]
	v_mfma_f32_16x16x32_bf16 v[26:29], v[134:137], v[182:185], v[26:29]
	v_mfma_f32_16x16x32_bf16 v[14:17], v[110:113], v[228:231], v[14:17]
	v_mfma_f32_16x16x32_bf16 v[10:13], v[134:137], v[228:231], v[10:13]
	v_mfma_f32_16x16x32_bf16 v[54:57], v[150:153], v[166:169], v[54:57]
	v_mfma_f32_16x16x32_bf16 v[50:53], v[158:161], v[166:169], v[50:53]
	v_mfma_f32_16x16x32_bf16 v[38:41], v[150:153], v[174:177], v[38:41]
	v_mfma_f32_16x16x32_bf16 v[34:37], v[158:161], v[174:177], v[34:37]
	v_mfma_f32_16x16x32_bf16 v[22:25], v[150:153], v[182:185], v[22:25]
	v_mfma_f32_16x16x32_bf16 v[18:21], v[158:161], v[182:185], v[18:21]
	v_mfma_f32_16x16x32_bf16 v[6:9], v[150:153], v[228:231], v[6:9]
	v_mfma_f32_16x16x32_bf16 v[2:5], v[158:161], v[228:231], v[2:5]
	s_barrier
	s_setprio 0
	s_add_i32 s45, s45, 2
	s_add_u32 s52, s52, 0x100
	s_addc_u32 s53, s53, 0
	s_add_u32 s18, s18, 0x100
	s_addc_u32 s19, s19, 0
	s_cmp_gt_u32 s45, 13
	s_cbranch_scc0 .LBB0_900
	s_and_b64 vcc, exec, s[40:41]
	s_cbranch_vccz .LBB0_903
	s_barrier

.Lrb5_skip:
	s_add_u32 s52, s50, 0xfffc0080
	s_addc_u32 s53, s51, -1
	s_add_i32 s67, 0, 0x10000
	s_cmp_eq_u32 s66, 12
	s_cselect_b32 s55, s45, s53
	s_cselect_b32 s54, s62, s52
	v_add_u32_e32 v0, s67, v144
	s_cselect_b32 s53, s43, s65
	s_cselect_b32 s52, s63, s64
	s_add_i32 s70, 0, 0x14000
	ds_read_b128 v[146:149], v0
	ds_read_b128 v[150:153], v0 offset:1024
	ds_read_b128 v[154:157], v0 offset:2048
	ds_read_b128 v[158:161], v0 offset:3072
	v_add_u32_e32 v0, s70, v144
	ds_read_b128 v[162:165], v0
	ds_read_b128 v[166:169], v0 offset:1024
	ds_read_b128 v[170:173], v0 offset:2048
	ds_read_b128 v[174:177], v0 offset:3072
	s_add_i32 m0, s5, 0xc000
	ds_read_b128 v[178:181], v145
	ds_read_b128 v[182:185], v145 offset:1024
	ds_read_b128 v[204:207], v145 offset:2048
	ds_read_b128 v[208:211], v145 offset:3072
	ds_read_b128 v[212:215], v145 offset:4096
	ds_read_b128 v[220:223], v145 offset:5120
	ds_read_b128 v[224:227], v145 offset:6144
	ds_read_b128 v[228:231], v145 offset:7168
	global_load_lds_dwordx4 v138, s[50:51]
	s_add_i32 m0, s5, 0xe000
	s_nop 0
	global_load_lds_dwordx4 v140, s[50:51]
	s_waitcnt vmcnt(8)
	s_waitcnt lgkmcnt(0)
	s_setprio 1
	s_barrier
	v_mfma_f32_16x16x32_bf16 v[118:121], v[146:149], v[178:181], 0
	v_mfma_f32_16x16x32_bf16 v[114:117], v[154:157], v[178:181], 0
	v_mfma_f32_16x16x32_bf16 v[110:113], v[146:149], v[204:207], 0
	v_mfma_f32_16x16x32_bf16 v[102:105], v[154:157], v[204:207], 0
	v_mfma_f32_16x16x32_bf16 v[94:97], v[146:149], v[212:215], 0
	v_mfma_f32_16x16x32_bf16 v[86:89], v[154:157], v[212:215], 0
	v_mfma_f32_16x16x32_bf16 v[78:81], v[146:149], v[224:227], 0
	v_mfma_f32_16x16x32_bf16 v[70:73], v[154:157], v[224:227], 0
	v_mfma_f32_16x16x32_bf16 v[126:129], v[162:165], v[178:181], 0
	v_mfma_f32_16x16x32_bf16 v[122:125], v[170:173], v[178:181], 0
	v_mfma_f32_16x16x32_bf16 v[106:109], v[162:165], v[204:207], 0
	v_mfma_f32_16x16x32_bf16 v[98:101], v[170:173], v[204:207], 0
	v_mfma_f32_16x16x32_bf16 v[90:93], v[162:165], v[212:215], 0
	v_mfma_f32_16x16x32_bf16 v[82:85], v[170:173], v[212:215], 0
	v_mfma_f32_16x16x32_bf16 v[74:77], v[162:165], v[224:227], 0
	v_mfma_f32_16x16x32_bf16 v[66:69], v[170:173], v[224:227], 0
	v_mfma_f32_16x16x32_bf16 v[118:121], v[150:153], v[182:185], v[118:121]
	v_mfma_f32_16x16x32_bf16 v[114:117], v[158:161], v[182:185], v[114:117]
	v_mfma_f32_16x16x32_bf16 v[110:113], v[150:153], v[208:211], v[110:113]
	v_mfma_f32_16x16x32_bf16 v[102:105], v[158:161], v[208:211], v[102:105]
	v_mfma_f32_16x16x32_bf16 v[94:97], v[150:153], v[220:223], v[94:97]
	v_mfma_f32_16x16x32_bf16 v[86:89], v[158:161], v[220:223], v[86:89]
	v_mfma_f32_16x16x32_bf16 v[78:81], v[150:153], v[228:231], v[78:81]
	v_mfma_f32_16x16x32_bf16 v[70:73], v[158:161], v[228:231], v[70:73]
	v_mfma_f32_16x16x32_bf16 v[126:129], v[166:169], v[182:185], v[126:129]
	v_mfma_f32_16x16x32_bf16 v[122:125], v[174:177], v[182:185], v[122:125]
	v_mfma_f32_16x16x32_bf16 v[106:109], v[166:169], v[208:211], v[106:109]
	v_mfma_f32_16x16x32_bf16 v[98:101], v[174:177], v[208:211], v[98:101]
	v_mfma_f32_16x16x32_bf16 v[90:93], v[166:169], v[220:223], v[90:93]
	v_mfma_f32_16x16x32_bf16 v[82:85], v[174:177], v[220:223], v[82:85]
	v_mfma_f32_16x16x32_bf16 v[74:77], v[166:169], v[228:231], v[74:77]
	v_mfma_f32_16x16x32_bf16 v[66:69], v[174:177], v[228:231], v[66:69]
	s_barrier
	s_setprio 0
	s_add_i32 s67, s67, s4
	s_mov_b32 m0, s67
	ds_read_b128 v[178:181], v145 offset:16384
	ds_read_b128 v[182:185], v145 offset:17408
	ds_read_b128 v[204:207], v145 offset:18432
	ds_read_b128 v[208:211], v145 offset:19456
	ds_read_b128 v[212:215], v145 offset:20480
	ds_read_b128 v[220:223], v145 offset:21504
	ds_read_b128 v[224:227], v145 offset:22528
	ds_read_b128 v[228:231], v145 offset:23552
	global_load_lds_dwordx4 v134, s[52:53]
	s_add_i32 m0, s67, 0x2000
	s_add_u32 s68, s52, 0x40000
	s_addc_u32 s69, s53, 0
	s_add_i32 s67, s70, s4
	global_load_lds_dwordx4 v130, s[52:53]
	s_mov_b32 m0, s67
	s_nop 0
	global_load_lds_dwordx4 v134, s[68:69]
	s_add_i32 m0, s67, 0x2000
	s_nop 0
	global_load_lds_dwordx4 v130, s[68:69]
	s_mov_b32 m0, s5
	s_nop 0
	global_load_lds_dwordx4 v136, s[54:55]
	s_mov_b32 m0, s6
	s_nop 0
	global_load_lds_dwordx4 v132, s[54:55]
	s_waitcnt vmcnt(8)
	s_waitcnt lgkmcnt(0)
	s_setprio 1
	s_barrier
	v_mfma_f32_16x16x32_bf16 v[62:65], v[146:149], v[178:181], 0
	v_mfma_f32_16x16x32_bf16 v[54:57], v[154:157], v[178:181], 0
	v_mfma_f32_16x16x32_bf16 v[46:49], v[146:149], v[204:207], 0
	v_mfma_f32_16x16x32_bf16 v[38:41], v[154:157], v[204:207], 0
	v_mfma_f32_16x16x32_bf16 v[30:33], v[146:149], v[212:215], 0
	v_mfma_f32_16x16x32_bf16 v[22:25], v[154:157], v[212:215], 0
	v_mfma_f32_16x16x32_bf16 v[14:17], v[146:149], v[224:227], 0
	v_mfma_f32_16x16x32_bf16 v[6:9], v[154:157], v[224:227], 0
	v_mfma_f32_16x16x32_bf16 v[58:61], v[162:165], v[178:181], 0
	v_mfma_f32_16x16x32_bf16 v[50:53], v[170:173], v[178:181], 0
	v_mfma_f32_16x16x32_bf16 v[42:45], v[162:165], v[204:207], 0
	v_mfma_f32_16x16x32_bf16 v[34:37], v[170:173], v[204:207], 0
	v_mfma_f32_16x16x32_bf16 v[26:29], v[162:165], v[212:215], 0
	v_mfma_f32_16x16x32_bf16 v[18:21], v[170:173], v[212:215], 0
	v_mfma_f32_16x16x32_bf16 v[10:13], v[162:165], v[224:227], 0
	v_mfma_f32_16x16x32_bf16 v[2:5], v[170:173], v[224:227], 0
	v_mfma_f32_16x16x32_bf16 v[62:65], v[150:153], v[182:185], v[62:65]
	v_mfma_f32_16x16x32_bf16 v[54:57], v[158:161], v[182:185], v[54:57]
	v_mfma_f32_16x16x32_bf16 v[46:49], v[150:153], v[208:211], v[46:49]
	v_mfma_f32_16x16x32_bf16 v[38:41], v[158:161], v[208:211], v[38:41]
	v_mfma_f32_16x16x32_bf16 v[30:33], v[150:153], v[220:223], v[30:33]
	v_mfma_f32_16x16x32_bf16 v[22:25], v[158:161], v[220:223], v[22:25]
	v_mfma_f32_16x16x32_bf16 v[14:17], v[150:153], v[228:231], v[14:17]
	v_mfma_f32_16x16x32_bf16 v[6:9], v[158:161], v[228:231], v[6:9]
	v_mfma_f32_16x16x32_bf16 v[58:61], v[166:169], v[182:185], v[58:61]
	v_mfma_f32_16x16x32_bf16 v[50:53], v[174:177], v[182:185], v[50:53]
	v_mfma_f32_16x16x32_bf16 v[42:45], v[166:169], v[208:211], v[42:45]
	v_mfma_f32_16x16x32_bf16 v[34:37], v[174:177], v[208:211], v[34:37]
	v_mfma_f32_16x16x32_bf16 v[26:29], v[166:169], v[220:223], v[26:29]
	v_mfma_f32_16x16x32_bf16 v[18:21], v[174:177], v[220:223], v[18:21]
	v_mfma_f32_16x16x32_bf16 v[10:13], v[166:169], v[228:231], v[10:13]
	v_mfma_f32_16x16x32_bf16 v[2:5], v[174:177], v[228:231], v[2:5]
	s_barrier
	s_setprio 0
	s_add_i32 s67, 0, 0x18000
	v_add_u32_e32 v0, s67, v144
	s_add_i32 s68, 0, 0x1c000
	ds_read_b128 v[146:149], v0
	ds_read_b128 v[150:153], v0 offset:1024
	ds_read_b128 v[154:157], v0 offset:2048
	ds_read_b128 v[158:161], v0 offset:3072
	v_add_u32_e32 v0, s68, v144
	ds_read_b128 v[162:165], v0
	ds_read_b128 v[166:169], v0 offset:1024
	ds_read_b128 v[170:173], v0 offset:2048
	ds_read_b128 v[174:177], v0 offset:3072
	s_add_u32 s54, s54, 0x40000
	s_addc_u32 s55, s55, 0
	s_mov_b32 m0, s7
	ds_read_b128 v[178:181], v145 offset:32768
	ds_read_b128 v[182:185], v145 offset:33792
	ds_read_b128 v[204:207], v145 offset:34816
	ds_read_b128 v[208:211], v145 offset:35840
	ds_read_b128 v[212:215], v145 offset:36864
	ds_read_b128 v[220:223], v145 offset:37888
	ds_read_b128 v[224:227], v145 offset:38912
	ds_read_b128 v[228:231], v145 offset:39936
	global_load_lds_dwordx4 v136, s[54:55]
	s_mov_b32 m0, s56
	s_nop 0
	global_load_lds_dwordx4 v132, s[54:55]
	s_waitcnt vmcnt(8)
	s_waitcnt lgkmcnt(0)
	s_setprio 1
	s_barrier
	v_mfma_f32_16x16x32_bf16 v[118:121], v[146:149], v[178:181], v[118:121]
	v_mfma_f32_16x16x32_bf16 v[114:117], v[154:157], v[178:181], v[114:117]
	v_mfma_f32_16x16x32_bf16 v[110:113], v[146:149], v[204:207], v[110:113]
	v_mfma_f32_16x16x32_bf16 v[102:105], v[154:157], v[204:207], v[102:105]
	v_mfma_f32_16x16x32_bf16 v[94:97], v[146:149], v[212:215], v[94:97]
	v_mfma_f32_16x16x32_bf16 v[86:89], v[154:157], v[212:215], v[86:89]
	v_mfma_f32_16x16x32_bf16 v[78:81], v[146:149], v[224:227], v[78:81]
	v_mfma_f32_16x16x32_bf16 v[70:73], v[154:157], v[224:227], v[70:73]
	v_mfma_f32_16x16x32_bf16 v[126:129], v[162:165], v[178:181], v[126:129]
	v_mfma_f32_16x16x32_bf16 v[122:125], v[170:173], v[178:181], v[122:125]
	v_mfma_f32_16x16x32_bf16 v[106:109], v[162:165], v[204:207], v[106:109]
	v_mfma_f32_16x16x32_bf16 v[98:101], v[170:173], v[204:207], v[98:101]
	v_mfma_f32_16x16x32_bf16 v[90:93], v[162:165], v[212:215], v[90:93]
	v_mfma_f32_16x16x32_bf16 v[82:85], v[170:173], v[212:215], v[82:85]
	v_mfma_f32_16x16x32_bf16 v[74:77], v[162:165], v[224:227], v[74:77]
	v_mfma_f32_16x16x32_bf16 v[66:69], v[170:173], v[224:227], v[66:69]
	v_mfma_f32_16x16x32_bf16 v[118:121], v[150:153], v[182:185], v[118:121]
	v_mfma_f32_16x16x32_bf16 v[114:117], v[158:161], v[182:185], v[114:117]
	v_mfma_f32_16x16x32_bf16 v[110:113], v[150:153], v[208:211], v[110:113]
	v_mfma_f32_16x16x32_bf16 v[102:105], v[158:161], v[208:211], v[102:105]
	v_mfma_f32_16x16x32_bf16 v[94:97], v[150:153], v[220:223], v[94:97]
	v_mfma_f32_16x16x32_bf16 v[86:89], v[158:161], v[220:223], v[86:89]
	v_mfma_f32_16x16x32_bf16 v[78:81], v[150:153], v[228:231], v[78:81]
	v_mfma_f32_16x16x32_bf16 v[70:73], v[158:161], v[228:231], v[70:73]
	v_mfma_f32_16x16x32_bf16 v[126:129], v[166:169], v[182:185], v[126:129]
	v_mfma_f32_16x16x32_bf16 v[122:125], v[174:177], v[182:185], v[122:125]
	v_mfma_f32_16x16x32_bf16 v[106:109], v[166:169], v[208:211], v[106:109]
	v_mfma_f32_16x16x32_bf16 v[98:101], v[174:177], v[208:211], v[98:101]
	v_mfma_f32_16x16x32_bf16 v[90:93], v[166:169], v[220:223], v[90:93]
	v_mfma_f32_16x16x32_bf16 v[82:85], v[174:177], v[220:223], v[82:85]
	v_mfma_f32_16x16x32_bf16 v[74:77], v[166:169], v[228:231], v[74:77]
	v_mfma_f32_16x16x32_bf16 v[66:69], v[174:177], v[228:231], v[66:69]
	s_barrier
	s_setprio 0
	s_add_i32 s69, s67, s4
	s_add_u32 s52, s52, 0x80
	s_addc_u32 s53, s53, 0
	s_mov_b32 m0, s69
	ds_read_b128 v[178:181], v145 offset:49152
	ds_read_b128 v[182:185], v145 offset:50176
	ds_read_b128 v[204:207], v145 offset:51200
	ds_read_b128 v[208:211], v145 offset:52224
	ds_read_b128 v[212:215], v145 offset:53248
	ds_read_b128 v[220:223], v145 offset:54272
	ds_read_b128 v[224:227], v145 offset:55296
	ds_read_b128 v[228:231], v145 offset:56320
	global_load_lds_dwordx4 v134, s[52:53]
	s_add_i32 m0, s69, 0x2000
	s_add_i32 s69, s68, s4
	global_load_lds_dwordx4 v130, s[52:53]
	s_add_u32 s52, s52, 0x40000
	s_addc_u32 s53, s53, 0
	s_mov_b32 m0, s69
	s_sub_u32 s54, s54, 0x3ff80
	global_load_lds_dwordx4 v134, s[52:53]
	s_subb_u32 s55, s55, 0
	s_add_i32 m0, s69, 0x2000
	s_nop 0
	global_load_lds_dwordx4 v130, s[52:53]
	s_mov_b32 m0, s59
	s_nop 0
	global_load_lds_dwordx4 v136, s[54:55]
	s_mov_b32 m0, s60
	s_nop 0
	global_load_lds_dwordx4 v132, s[54:55]
	s_waitcnt vmcnt(8)
	s_waitcnt lgkmcnt(0)
	s_setprio 1
	s_barrier
	v_mfma_f32_16x16x32_bf16 v[62:65], v[146:149], v[178:181], v[62:65]
	v_mfma_f32_16x16x32_bf16 v[54:57], v[154:157], v[178:181], v[54:57]
	v_mfma_f32_16x16x32_bf16 v[46:49], v[146:149], v[204:207], v[46:49]
	v_mfma_f32_16x16x32_bf16 v[38:41], v[154:157], v[204:207], v[38:41]
	v_mfma_f32_16x16x32_bf16 v[30:33], v[146:149], v[212:215], v[30:33]
	v_mfma_f32_16x16x32_bf16 v[22:25], v[154:157], v[212:215], v[22:25]
	v_mfma_f32_16x16x32_bf16 v[14:17], v[146:149], v[224:227], v[14:17]
	v_mfma_f32_16x16x32_bf16 v[6:9], v[154:157], v[224:227], v[6:9]
	v_mfma_f32_16x16x32_bf16 v[58:61], v[162:165], v[178:181], v[58:61]
	v_mfma_f32_16x16x32_bf16 v[50:53], v[170:173], v[178:181], v[50:53]
	v_mfma_f32_16x16x32_bf16 v[42:45], v[162:165], v[204:207], v[42:45]
	v_mfma_f32_16x16x32_bf16 v[34:37], v[170:173], v[204:207], v[34:37]
	v_mfma_f32_16x16x32_bf16 v[26:29], v[162:165], v[212:215], v[26:29]
	v_mfma_f32_16x16x32_bf16 v[18:21], v[170:173], v[212:215], v[18:21]
	v_mfma_f32_16x16x32_bf16 v[10:13], v[162:165], v[224:227], v[10:13]
	v_mfma_f32_16x16x32_bf16 v[2:5], v[170:173], v[224:227], v[2:5]
	v_mfma_f32_16x16x32_bf16 v[62:65], v[150:153], v[182:185], v[62:65]
	v_mfma_f32_16x16x32_bf16 v[54:57], v[158:161], v[182:185], v[54:57]
	v_mfma_f32_16x16x32_bf16 v[46:49], v[150:153], v[208:211], v[46:49]
	v_mfma_f32_16x16x32_bf16 v[38:41], v[158:161], v[208:211], v[38:41]
	v_mfma_f32_16x16x32_bf16 v[30:33], v[150:153], v[220:223], v[30:33]
	v_mfma_f32_16x16x32_bf16 v[22:25], v[158:161], v[220:223], v[22:25]
	v_mfma_f32_16x16x32_bf16 v[14:17], v[150:153], v[228:231], v[14:17]
	v_mfma_f32_16x16x32_bf16 v[6:9], v[158:161], v[228:231], v[6:9]
	v_mfma_f32_16x16x32_bf16 v[58:61], v[166:169], v[182:185], v[58:61]
	v_mfma_f32_16x16x32_bf16 v[50:53], v[174:177], v[182:185], v[50:53]
	v_mfma_f32_16x16x32_bf16 v[42:45], v[166:169], v[208:211], v[42:45]
	v_mfma_f32_16x16x32_bf16 v[34:37], v[174:177], v[208:211], v[34:37]
	v_mfma_f32_16x16x32_bf16 v[26:29], v[166:169], v[220:223], v[26:29]
	v_mfma_f32_16x16x32_bf16 v[18:21], v[174:177], v[220:223], v[18:21]
	v_mfma_f32_16x16x32_bf16 v[10:13], v[166:169], v[228:231], v[10:13]
	v_mfma_f32_16x16x32_bf16 v[2:5], v[174:177], v[228:231], v[2:5]
	s_barrier
	s_setprio 0
	s_add_i32 s66, s66, 2
	s_add_u32 s50, s50, 0x100
	s_addc_u32 s51, s51, 0
	s_add_u32 s64, s64, 0x100
	s_addc_u32 s65, s65, 0
	s_cmp_gt_u32 s66, 13
.LBB0_997:
	s_add_u32 s52, s50, 0xfffc0080
	s_addc_u32 s53, s51, -1
	s_add_i32 s67, 0, 0x10000
	s_cmp_eq_u32 s66, 12
	s_cselect_b32 s55, s45, s53
	s_cselect_b32 s54, s62, s52
	v_add_u32_e32 v0, s67, v144
	s_cselect_b32 s53, s43, s65
	s_cselect_b32 s52, s63, s64
	s_add_i32 s70, 0, 0x14000
	ds_read_b128 v[146:149], v0
	ds_read_b128 v[150:153], v0 offset:1024
	ds_read_b128 v[154:157], v0 offset:2048
	ds_read_b128 v[158:161], v0 offset:3072
	v_add_u32_e32 v0, s70, v144
	ds_read_b128 v[162:165], v0
	ds_read_b128 v[166:169], v0 offset:1024
	ds_read_b128 v[170:173], v0 offset:2048
	ds_read_b128 v[174:177], v0 offset:3072
	s_add_i32 m0, s5, 0xc000
	ds_read_b128 v[178:181], v145
	ds_read_b128 v[182:185], v145 offset:1024
	ds_read_b128 v[204:207], v145 offset:2048
	ds_read_b128 v[208:211], v145 offset:3072
	ds_read_b128 v[212:215], v145 offset:4096
	ds_read_b128 v[220:223], v145 offset:5120
	ds_read_b128 v[224:227], v145 offset:6144
	ds_read_b128 v[228:231], v145 offset:7168
	global_load_lds_dwordx4 v138, s[50:51]
	s_add_i32 m0, s5, 0xe000
	s_nop 0
	global_load_lds_dwordx4 v140, s[50:51]
	s_waitcnt vmcnt(8)
	s_waitcnt lgkmcnt(0)
	s_setprio 1
	s_barrier
	v_mfma_f32_16x16x32_bf16 v[118:121], v[146:149], v[178:181], v[118:121]
	v_mfma_f32_16x16x32_bf16 v[114:117], v[154:157], v[178:181], v[114:117]
	v_mfma_f32_16x16x32_bf16 v[110:113], v[146:149], v[204:207], v[110:113]
	v_mfma_f32_16x16x32_bf16 v[102:105], v[154:157], v[204:207], v[102:105]
	v_mfma_f32_16x16x32_bf16 v[94:97], v[146:149], v[212:215], v[94:97]
	v_mfma_f32_16x16x32_bf16 v[86:89], v[154:157], v[212:215], v[86:89]
	v_mfma_f32_16x16x32_bf16 v[78:81], v[146:149], v[224:227], v[78:81]
	v_mfma_f32_16x16x32_bf16 v[70:73], v[154:157], v[224:227], v[70:73]
	v_mfma_f32_16x16x32_bf16 v[126:129], v[162:165], v[178:181], v[126:129]
	v_mfma_f32_16x16x32_bf16 v[122:125], v[170:173], v[178:181], v[122:125]
	v_mfma_f32_16x16x32_bf16 v[106:109], v[162:165], v[204:207], v[106:109]
	v_mfma_f32_16x16x32_bf16 v[98:101], v[170:173], v[204:207], v[98:101]
	v_mfma_f32_16x16x32_bf16 v[90:93], v[162:165], v[212:215], v[90:93]
	v_mfma_f32_16x16x32_bf16 v[82:85], v[170:173], v[212:215], v[82:85]
	v_mfma_f32_16x16x32_bf16 v[74:77], v[162:165], v[224:227], v[74:77]
	v_mfma_f32_16x16x32_bf16 v[66:69], v[170:173], v[224:227], v[66:69]
	v_mfma_f32_16x16x32_bf16 v[118:121], v[150:153], v[182:185], v[118:121]
	v_mfma_f32_16x16x32_bf16 v[114:117], v[158:161], v[182:185], v[114:117]
	v_mfma_f32_16x16x32_bf16 v[110:113], v[150:153], v[208:211], v[110:113]
	v_mfma_f32_16x16x32_bf16 v[102:105], v[158:161], v[208:211], v[102:105]
	v_mfma_f32_16x16x32_bf16 v[94:97], v[150:153], v[220:223], v[94:97]
	v_mfma_f32_16x16x32_bf16 v[86:89], v[158:161], v[220:223], v[86:89]
	v_mfma_f32_16x16x32_bf16 v[78:81], v[150:153], v[228:231], v[78:81]
	v_mfma_f32_16x16x32_bf16 v[70:73], v[158:161], v[228:231], v[70:73]
	v_mfma_f32_16x16x32_bf16 v[126:129], v[166:169], v[182:185], v[126:129]
	v_mfma_f32_16x16x32_bf16 v[122:125], v[174:177], v[182:185], v[122:125]
	v_mfma_f32_16x16x32_bf16 v[106:109], v[166:169], v[208:211], v[106:109]
	v_mfma_f32_16x16x32_bf16 v[98:101], v[174:177], v[208:211], v[98:101]
	v_mfma_f32_16x16x32_bf16 v[90:93], v[166:169], v[220:223], v[90:93]
	v_mfma_f32_16x16x32_bf16 v[82:85], v[174:177], v[220:223], v[82:85]
	v_mfma_f32_16x16x32_bf16 v[74:77], v[166:169], v[228:231], v[74:77]
	v_mfma_f32_16x16x32_bf16 v[66:69], v[174:177], v[228:231], v[66:69]
	s_barrier
	s_setprio 0
	s_add_i32 s67, s67, s4
	s_mov_b32 m0, s67
	ds_read_b128 v[178:181], v145 offset:16384
	ds_read_b128 v[182:185], v145 offset:17408
	ds_read_b128 v[204:207], v145 offset:18432
	ds_read_b128 v[208:211], v145 offset:19456
	ds_read_b128 v[212:215], v145 offset:20480
	ds_read_b128 v[220:223], v145 offset:21504
	ds_read_b128 v[224:227], v145 offset:22528
	ds_read_b128 v[228:231], v145 offset:23552
	global_load_lds_dwordx4 v134, s[52:53]
	s_add_i32 m0, s67, 0x2000
	s_add_u32 s68, s52, 0x40000
	s_addc_u32 s69, s53, 0
	s_add_i32 s67, s70, s4
	global_load_lds_dwordx4 v130, s[52:53]
	s_mov_b32 m0, s67
	s_nop 0
	global_load_lds_dwordx4 v134, s[68:69]
	s_add_i32 m0, s67, 0x2000
	s_nop 0
	global_load_lds_dwordx4 v130, s[68:69]
	s_mov_b32 m0, s5
	s_nop 0
	global_load_lds_dwordx4 v136, s[54:55]
	s_mov_b32 m0, s6
	s_nop 0
	global_load_lds_dwordx4 v132, s[54:55]
	s_waitcnt vmcnt(8)
	s_waitcnt lgkmcnt(0)
	s_setprio 1
	s_barrier
	v_mfma_f32_16x16x32_bf16 v[62:65], v[146:149], v[178:181], v[62:65]
	v_mfma_f32_16x16x32_bf16 v[54:57], v[154:157], v[178:181], v[54:57]
	v_mfma_f32_16x16x32_bf16 v[46:49], v[146:149], v[204:207], v[46:49]
	v_mfma_f32_16x16x32_bf16 v[38:41], v[154:157], v[204:207], v[38:41]
	v_mfma_f32_16x16x32_bf16 v[30:33], v[146:149], v[212:215], v[30:33]
	v_mfma_f32_16x16x32_bf16 v[22:25], v[154:157], v[212:215], v[22:25]
	v_mfma_f32_16x16x32_bf16 v[14:17], v[146:149], v[224:227], v[14:17]
	v_mfma_f32_16x16x32_bf16 v[6:9], v[154:157], v[224:227], v[6:9]
	v_mfma_f32_16x16x32_bf16 v[58:61], v[162:165], v[178:181], v[58:61]
	v_mfma_f32_16x16x32_bf16 v[50:53], v[170:173], v[178:181], v[50:53]
	v_mfma_f32_16x16x32_bf16 v[42:45], v[162:165], v[204:207], v[42:45]
	v_mfma_f32_16x16x32_bf16 v[34:37], v[170:173], v[204:207], v[34:37]
	v_mfma_f32_16x16x32_bf16 v[26:29], v[162:165], v[212:215], v[26:29]
	v_mfma_f32_16x16x32_bf16 v[18:21], v[170:173], v[212:215], v[18:21]
	v_mfma_f32_16x16x32_bf16 v[10:13], v[162:165], v[224:227], v[10:13]
	v_mfma_f32_16x16x32_bf16 v[2:5], v[170:173], v[224:227], v[2:5]
	v_mfma_f32_16x16x32_bf16 v[62:65], v[150:153], v[182:185], v[62:65]
	v_mfma_f32_16x16x32_bf16 v[54:57], v[158:161], v[182:185], v[54:57]
	v_mfma_f32_16x16x32_bf16 v[46:49], v[150:153], v[208:211], v[46:49]
	v_mfma_f32_16x16x32_bf16 v[38:41], v[158:161], v[208:211], v[38:41]
	v_mfma_f32_16x16x32_bf16 v[30:33], v[150:153], v[220:223], v[30:33]
	v_mfma_f32_16x16x32_bf16 v[22:25], v[158:161], v[220:223], v[22:25]
	v_mfma_f32_16x16x32_bf16 v[14:17], v[150:153], v[228:231], v[14:17]
	v_mfma_f32_16x16x32_bf16 v[6:9], v[158:161], v[228:231], v[6:9]
	v_mfma_f32_16x16x32_bf16 v[58:61], v[166:169], v[182:185], v[58:61]
	v_mfma_f32_16x16x32_bf16 v[50:53], v[174:177], v[182:185], v[50:53]
	v_mfma_f32_16x16x32_bf16 v[42:45], v[166:169], v[208:211], v[42:45]
	v_mfma_f32_16x16x32_bf16 v[34:37], v[174:177], v[208:211], v[34:37]
	v_mfma_f32_16x16x32_bf16 v[26:29], v[166:169], v[220:223], v[26:29]
	v_mfma_f32_16x16x32_bf16 v[18:21], v[174:177], v[220:223], v[18:21]
	v_mfma_f32_16x16x32_bf16 v[10:13], v[166:169], v[228:231], v[10:13]
	v_mfma_f32_16x16x32_bf16 v[2:5], v[174:177], v[228:231], v[2:5]
	s_barrier
	s_setprio 0
	s_add_i32 s67, 0, 0x18000
	v_add_u32_e32 v0, s67, v144
	s_add_i32 s68, 0, 0x1c000
	ds_read_b128 v[146:149], v0
	ds_read_b128 v[150:153], v0 offset:1024
	ds_read_b128 v[154:157], v0 offset:2048
	ds_read_b128 v[158:161], v0 offset:3072
	v_add_u32_e32 v0, s68, v144
	ds_read_b128 v[162:165], v0
	ds_read_b128 v[166:169], v0 offset:1024
	ds_read_b128 v[170:173], v0 offset:2048
	ds_read_b128 v[174:177], v0 offset:3072
	s_add_u32 s54, s54, 0x40000
	s_addc_u32 s55, s55, 0
	s_mov_b32 m0, s7
	ds_read_b128 v[178:181], v145 offset:32768
	ds_read_b128 v[182:185], v145 offset:33792
	ds_read_b128 v[204:207], v145 offset:34816
	ds_read_b128 v[208:211], v145 offset:35840
	ds_read_b128 v[212:215], v145 offset:36864
	ds_read_b128 v[220:223], v145 offset:37888
	ds_read_b128 v[224:227], v145 offset:38912
	ds_read_b128 v[228:231], v145 offset:39936
	global_load_lds_dwordx4 v136, s[54:55]
	s_mov_b32 m0, s56
	s_nop 0
	global_load_lds_dwordx4 v132, s[54:55]
	s_waitcnt vmcnt(8)
	s_waitcnt lgkmcnt(0)
	s_setprio 1
	s_barrier
	v_mfma_f32_16x16x32_bf16 v[118:121], v[146:149], v[178:181], v[118:121]
	v_mfma_f32_16x16x32_bf16 v[114:117], v[154:157], v[178:181], v[114:117]
	v_mfma_f32_16x16x32_bf16 v[110:113], v[146:149], v[204:207], v[110:113]
	v_mfma_f32_16x16x32_bf16 v[102:105], v[154:157], v[204:207], v[102:105]
	v_mfma_f32_16x16x32_bf16 v[94:97], v[146:149], v[212:215], v[94:97]
	v_mfma_f32_16x16x32_bf16 v[86:89], v[154:157], v[212:215], v[86:89]
	v_mfma_f32_16x16x32_bf16 v[78:81], v[146:149], v[224:227], v[78:81]
	v_mfma_f32_16x16x32_bf16 v[70:73], v[154:157], v[224:227], v[70:73]
	v_mfma_f32_16x16x32_bf16 v[126:129], v[162:165], v[178:181], v[126:129]
	v_mfma_f32_16x16x32_bf16 v[122:125], v[170:173], v[178:181], v[122:125]
	v_mfma_f32_16x16x32_bf16 v[106:109], v[162:165], v[204:207], v[106:109]
	v_mfma_f32_16x16x32_bf16 v[98:101], v[170:173], v[204:207], v[98:101]
	v_mfma_f32_16x16x32_bf16 v[90:93], v[162:165], v[212:215], v[90:93]
	v_mfma_f32_16x16x32_bf16 v[82:85], v[170:173], v[212:215], v[82:85]
	v_mfma_f32_16x16x32_bf16 v[74:77], v[162:165], v[224:227], v[74:77]
	v_mfma_f32_16x16x32_bf16 v[66:69], v[170:173], v[224:227], v[66:69]
	v_mfma_f32_16x16x32_bf16 v[118:121], v[150:153], v[182:185], v[118:121]
	v_mfma_f32_16x16x32_bf16 v[114:117], v[158:161], v[182:185], v[114:117]
	v_mfma_f32_16x16x32_bf16 v[110:113], v[150:153], v[208:211], v[110:113]
	v_mfma_f32_16x16x32_bf16 v[102:105], v[158:161], v[208:211], v[102:105]
	v_mfma_f32_16x16x32_bf16 v[94:97], v[150:153], v[220:223], v[94:97]
	v_mfma_f32_16x16x32_bf16 v[86:89], v[158:161], v[220:223], v[86:89]
	v_mfma_f32_16x16x32_bf16 v[78:81], v[150:153], v[228:231], v[78:81]
	v_mfma_f32_16x16x32_bf16 v[70:73], v[158:161], v[228:231], v[70:73]
	v_mfma_f32_16x16x32_bf16 v[126:129], v[166:169], v[182:185], v[126:129]
	v_mfma_f32_16x16x32_bf16 v[122:125], v[174:177], v[182:185], v[122:125]
	v_mfma_f32_16x16x32_bf16 v[106:109], v[166:169], v[208:211], v[106:109]
	v_mfma_f32_16x16x32_bf16 v[98:101], v[174:177], v[208:211], v[98:101]
	v_mfma_f32_16x16x32_bf16 v[90:93], v[166:169], v[220:223], v[90:93]
	v_mfma_f32_16x16x32_bf16 v[82:85], v[174:177], v[220:223], v[82:85]
	v_mfma_f32_16x16x32_bf16 v[74:77], v[166:169], v[228:231], v[74:77]
	v_mfma_f32_16x16x32_bf16 v[66:69], v[174:177], v[228:231], v[66:69]
	s_barrier
	s_setprio 0
	s_add_i32 s69, s67, s4
	s_add_u32 s52, s52, 0x80
	s_addc_u32 s53, s53, 0
	s_mov_b32 m0, s69
	ds_read_b128 v[178:181], v145 offset:49152
	ds_read_b128 v[182:185], v145 offset:50176
	ds_read_b128 v[204:207], v145 offset:51200
	ds_read_b128 v[208:211], v145 offset:52224
	ds_read_b128 v[212:215], v145 offset:53248
	ds_read_b128 v[220:223], v145 offset:54272
	ds_read_b128 v[224:227], v145 offset:55296
	ds_read_b128 v[228:231], v145 offset:56320
	global_load_lds_dwordx4 v134, s[52:53]
	s_add_i32 m0, s69, 0x2000
	s_add_i32 s69, s68, s4
	global_load_lds_dwordx4 v130, s[52:53]
	s_add_u32 s52, s52, 0x40000
	s_addc_u32 s53, s53, 0
	s_mov_b32 m0, s69
	s_sub_u32 s54, s54, 0x3ff80
	global_load_lds_dwordx4 v134, s[52:53]
	s_subb_u32 s55, s55, 0
	s_add_i32 m0, s69, 0x2000
	s_nop 0
	global_load_lds_dwordx4 v130, s[52:53]
	s_mov_b32 m0, s59
	s_nop 0
	global_load_lds_dwordx4 v136, s[54:55]
	s_mov_b32 m0, s60
	s_nop 0
	global_load_lds_dwordx4 v132, s[54:55]
	s_waitcnt vmcnt(8)
	s_waitcnt lgkmcnt(0)
	s_setprio 1
	s_barrier
	v_mfma_f32_16x16x32_bf16 v[62:65], v[146:149], v[178:181], v[62:65]
	v_mfma_f32_16x16x32_bf16 v[54:57], v[154:157], v[178:181], v[54:57]
	v_mfma_f32_16x16x32_bf16 v[46:49], v[146:149], v[204:207], v[46:49]
	v_mfma_f32_16x16x32_bf16 v[38:41], v[154:157], v[204:207], v[38:41]
	v_mfma_f32_16x16x32_bf16 v[30:33], v[146:149], v[212:215], v[30:33]
	v_mfma_f32_16x16x32_bf16 v[22:25], v[154:157], v[212:215], v[22:25]
	v_mfma_f32_16x16x32_bf16 v[14:17], v[146:149], v[224:227], v[14:17]
	v_mfma_f32_16x16x32_bf16 v[6:9], v[154:157], v[224:227], v[6:9]
	v_mfma_f32_16x16x32_bf16 v[58:61], v[162:165], v[178:181], v[58:61]
	v_mfma_f32_16x16x32_bf16 v[50:53], v[170:173], v[178:181], v[50:53]
	v_mfma_f32_16x16x32_bf16 v[42:45], v[162:165], v[204:207], v[42:45]
	v_mfma_f32_16x16x32_bf16 v[34:37], v[170:173], v[204:207], v[34:37]
	v_mfma_f32_16x16x32_bf16 v[26:29], v[162:165], v[212:215], v[26:29]
	v_mfma_f32_16x16x32_bf16 v[18:21], v[170:173], v[212:215], v[18:21]
	v_mfma_f32_16x16x32_bf16 v[10:13], v[162:165], v[224:227], v[10:13]
	v_mfma_f32_16x16x32_bf16 v[2:5], v[170:173], v[224:227], v[2:5]
	v_mfma_f32_16x16x32_bf16 v[62:65], v[150:153], v[182:185], v[62:65]
	v_mfma_f32_16x16x32_bf16 v[54:57], v[158:161], v[182:185], v[54:57]
	v_mfma_f32_16x16x32_bf16 v[46:49], v[150:153], v[208:211], v[46:49]
	v_mfma_f32_16x16x32_bf16 v[38:41], v[158:161], v[208:211], v[38:41]
	v_mfma_f32_16x16x32_bf16 v[30:33], v[150:153], v[220:223], v[30:33]
	v_mfma_f32_16x16x32_bf16 v[22:25], v[158:161], v[220:223], v[22:25]
	v_mfma_f32_16x16x32_bf16 v[14:17], v[150:153], v[228:231], v[14:17]
	v_mfma_f32_16x16x32_bf16 v[6:9], v[158:161], v[228:231], v[6:9]
	v_mfma_f32_16x16x32_bf16 v[58:61], v[166:169], v[182:185], v[58:61]
	v_mfma_f32_16x16x32_bf16 v[50:53], v[174:177], v[182:185], v[50:53]
	v_mfma_f32_16x16x32_bf16 v[42:45], v[166:169], v[208:211], v[42:45]
	v_mfma_f32_16x16x32_bf16 v[34:37], v[174:177], v[208:211], v[34:37]
	v_mfma_f32_16x16x32_bf16 v[26:29], v[166:169], v[220:223], v[26:29]
	v_mfma_f32_16x16x32_bf16 v[18:21], v[174:177], v[220:223], v[18:21]
	v_mfma_f32_16x16x32_bf16 v[10:13], v[166:169], v[228:231], v[10:13]
	v_mfma_f32_16x16x32_bf16 v[2:5], v[174:177], v[228:231], v[2:5]
	s_barrier
	s_setprio 0
	s_add_i32 s66, s66, 2
	s_add_u32 s50, s50, 0x100
	s_addc_u32 s51, s51, 0
	s_add_u32 s64, s64, 0x100
	s_addc_u32 s65, s65, 0
	s_cmp_gt_u32 s66, 13
	s_cbranch_scc0 .LBB0_997
	s_and_b64 vcc, exec, s[40:41]
	s_cbranch_vccz .LBB0_1000
	s_barrier

.Lrb6_skip:
	s_add_u32 s0, s44, 0x100
	s_addc_u32 s1, s45, 0
	s_add_i32 s63, 0, 0x10000
	s_cmp_eq_u32 s62, 40
	s_cselect_b32 s51, s41, s1
	s_cselect_b32 s50, s40, s0
	v_add_u32_e32 v0, s63, v221
	s_cselect_b32 s49, s43, s47
	s_cselect_b32 s48, s42, s7
	s_add_i32 s64, 0, 0x14000
	ds_read_b128 v[106:109], v0
	ds_read_b128 v[110:113], v0 offset:1024
	ds_read_b128 v[126:129], v0 offset:2048
	ds_read_b128 v[134:137], v0 offset:3072
	v_add_u32_e32 v0, s64, v221
	ds_read_b128 v[146:149], v0
	ds_read_b128 v[150:153], v0 offset:1024
	ds_read_b128 v[154:157], v0 offset:2048
	ds_read_b128 v[158:161], v0 offset:3072
	v_lshl_add_u64 v[216:217], s[44:45], 0, v[212:213]
	s_add_i32 m0, s53, 0xc000
	ds_read_b128 v[162:165], v222
	ds_read_b128 v[166:169], v222 offset:1024
	ds_read_b128 v[170:173], v222 offset:2048
	ds_read_b128 v[174:177], v222 offset:3072
	ds_read_b128 v[178:181], v222 offset:4096
	ds_read_b128 v[182:185], v222 offset:5120
	ds_read_b128 v[224:227], v222 offset:6144
	ds_read_b128 v[228:231], v222 offset:7168
	global_load_lds_dwordx4 v[216:217], off
	v_lshl_add_u64 v[216:217], s[44:45], 0, v[214:215]
	s_add_i32 m0, s53, 0xe000
	s_nop 0
	global_load_lds_dwordx4 v[216:217], off
	s_waitcnt vmcnt(8)
	s_waitcnt lgkmcnt(0)
	s_setprio 1
	s_barrier
	v_mfma_f32_16x16x32_bf16 v[142:145], v[106:109], v[162:165], 0
	v_mfma_f32_16x16x32_bf16 v[138:141], v[126:129], v[162:165], 0
	v_mfma_f32_16x16x32_bf16 v[118:121], v[106:109], v[170:173], 0
	v_mfma_f32_16x16x32_bf16 v[114:117], v[126:129], v[170:173], 0
	v_mfma_f32_16x16x32_bf16 v[94:97], v[106:109], v[178:181], 0
	v_mfma_f32_16x16x32_bf16 v[90:93], v[126:129], v[178:181], 0
	v_mfma_f32_16x16x32_bf16 v[78:81], v[106:109], v[224:227], 0
	v_mfma_f32_16x16x32_bf16 v[74:77], v[126:129], v[224:227], 0
	v_mfma_f32_16x16x32_bf16 v[130:133], v[146:149], v[162:165], 0
	v_mfma_f32_16x16x32_bf16 v[122:125], v[154:157], v[162:165], 0
	v_mfma_f32_16x16x32_bf16 v[102:105], v[146:149], v[170:173], 0
	v_mfma_f32_16x16x32_bf16 v[98:101], v[154:157], v[170:173], 0
	v_mfma_f32_16x16x32_bf16 v[86:89], v[146:149], v[178:181], 0
	v_mfma_f32_16x16x32_bf16 v[82:85], v[154:157], v[178:181], 0
	v_mfma_f32_16x16x32_bf16 v[70:73], v[146:149], v[224:227], 0
	v_mfma_f32_16x16x32_bf16 v[66:69], v[154:157], v[224:227], 0
	v_mfma_f32_16x16x32_bf16 v[142:145], v[110:113], v[166:169], v[142:145]
	v_mfma_f32_16x16x32_bf16 v[138:141], v[134:137], v[166:169], v[138:141]
	v_mfma_f32_16x16x32_bf16 v[118:121], v[110:113], v[174:177], v[118:121]
	v_mfma_f32_16x16x32_bf16 v[114:117], v[134:137], v[174:177], v[114:117]
	v_mfma_f32_16x16x32_bf16 v[94:97], v[110:113], v[182:185], v[94:97]
	v_mfma_f32_16x16x32_bf16 v[90:93], v[134:137], v[182:185], v[90:93]
	v_mfma_f32_16x16x32_bf16 v[78:81], v[110:113], v[228:231], v[78:81]
	v_mfma_f32_16x16x32_bf16 v[74:77], v[134:137], v[228:231], v[74:77]
	v_mfma_f32_16x16x32_bf16 v[130:133], v[150:153], v[166:169], v[130:133]
	v_mfma_f32_16x16x32_bf16 v[122:125], v[158:161], v[166:169], v[122:125]
	v_mfma_f32_16x16x32_bf16 v[102:105], v[150:153], v[174:177], v[102:105]
	v_mfma_f32_16x16x32_bf16 v[98:101], v[158:161], v[174:177], v[98:101]
	v_mfma_f32_16x16x32_bf16 v[86:89], v[150:153], v[182:185], v[86:89]
	v_mfma_f32_16x16x32_bf16 v[82:85], v[158:161], v[182:185], v[82:85]
	v_mfma_f32_16x16x32_bf16 v[70:73], v[150:153], v[228:231], v[70:73]
	v_mfma_f32_16x16x32_bf16 v[66:69], v[158:161], v[228:231], v[66:69]
	s_barrier
	s_setprio 0
	s_add_i32 s44, s63, s52
	v_lshl_add_u64 v[216:217], s[48:49], 0, v[208:209]
	s_mov_b32 m0, s44
	ds_read_b128 v[162:165], v222 offset:16384
	ds_read_b128 v[166:169], v222 offset:17408
	ds_read_b128 v[170:173], v222 offset:18432
	ds_read_b128 v[174:177], v222 offset:19456
	ds_read_b128 v[178:181], v222 offset:20480
	ds_read_b128 v[182:185], v222 offset:21504
	ds_read_b128 v[224:227], v222 offset:22528
	ds_read_b128 v[228:231], v222 offset:23552
	global_load_lds_dwordx4 v[216:217], off
	s_add_i32 m0, s44, 0x2000
	s_add_u32 s44, s48, 0xb0000
	v_lshl_add_u64 v[240:241], s[48:49], 0, v[204:205]
	s_addc_u32 s45, s49, 0
	s_add_i32 s63, s64, s52
	global_load_lds_dwordx4 v[240:241], off
	v_lshl_add_u64 v[242:243], s[44:45], 0, v[208:209]
	s_mov_b32 m0, s63
	v_lshl_add_u64 v[244:245], s[50:51], 0, v[206:207]
	global_load_lds_dwordx4 v[242:243], off
	v_lshl_add_u64 v[242:243], s[44:45], 0, v[204:205]
	s_add_i32 m0, s63, 0x2000
	s_nop 0
	global_load_lds_dwordx4 v[242:243], off
	v_lshl_add_u64 v[242:243], s[50:51], 0, v[210:211]
	s_mov_b32 m0, s53
	s_nop 0
	global_load_lds_dwordx4 v[242:243], off
	s_mov_b32 m0, s54
	s_nop 0
	global_load_lds_dwordx4 v[244:245], off
	s_waitcnt vmcnt(8)
	s_waitcnt lgkmcnt(0)
	s_setprio 1
	s_barrier
	v_mfma_f32_16x16x32_bf16 v[62:65], v[106:109], v[162:165], 0
	v_mfma_f32_16x16x32_bf16 v[58:61], v[126:129], v[162:165], 0
	v_mfma_f32_16x16x32_bf16 v[46:49], v[106:109], v[170:173], 0
	v_mfma_f32_16x16x32_bf16 v[42:45], v[126:129], v[170:173], 0
	v_mfma_f32_16x16x32_bf16 v[30:33], v[106:109], v[178:181], 0
	v_mfma_f32_16x16x32_bf16 v[26:29], v[126:129], v[178:181], 0
	v_mfma_f32_16x16x32_bf16 v[14:17], v[106:109], v[224:227], 0
	v_mfma_f32_16x16x32_bf16 v[10:13], v[126:129], v[224:227], 0
	v_mfma_f32_16x16x32_bf16 v[54:57], v[146:149], v[162:165], 0
	v_mfma_f32_16x16x32_bf16 v[50:53], v[154:157], v[162:165], 0
	v_mfma_f32_16x16x32_bf16 v[38:41], v[146:149], v[170:173], 0
	v_mfma_f32_16x16x32_bf16 v[34:37], v[154:157], v[170:173], 0
	v_mfma_f32_16x16x32_bf16 v[22:25], v[146:149], v[178:181], 0
	v_mfma_f32_16x16x32_bf16 v[18:21], v[154:157], v[178:181], 0
	v_mfma_f32_16x16x32_bf16 v[6:9], v[146:149], v[224:227], 0
	v_mfma_f32_16x16x32_bf16 v[2:5], v[154:157], v[224:227], 0
	v_mfma_f32_16x16x32_bf16 v[62:65], v[110:113], v[166:169], v[62:65]
	v_mfma_f32_16x16x32_bf16 v[58:61], v[134:137], v[166:169], v[58:61]
	v_mfma_f32_16x16x32_bf16 v[46:49], v[110:113], v[174:177], v[46:49]
	v_mfma_f32_16x16x32_bf16 v[42:45], v[134:137], v[174:177], v[42:45]
	v_mfma_f32_16x16x32_bf16 v[30:33], v[110:113], v[182:185], v[30:33]
	v_mfma_f32_16x16x32_bf16 v[26:29], v[134:137], v[182:185], v[26:29]
	v_mfma_f32_16x16x32_bf16 v[14:17], v[110:113], v[228:231], v[14:17]
	v_mfma_f32_16x16x32_bf16 v[10:13], v[134:137], v[228:231], v[10:13]
	v_mfma_f32_16x16x32_bf16 v[54:57], v[150:153], v[166:169], v[54:57]
	v_mfma_f32_16x16x32_bf16 v[50:53], v[158:161], v[166:169], v[50:53]
	v_mfma_f32_16x16x32_bf16 v[38:41], v[150:153], v[174:177], v[38:41]
	v_mfma_f32_16x16x32_bf16 v[34:37], v[158:161], v[174:177], v[34:37]
	v_mfma_f32_16x16x32_bf16 v[22:25], v[150:153], v[182:185], v[22:25]
	v_mfma_f32_16x16x32_bf16 v[18:21], v[158:161], v[182:185], v[18:21]
	v_mfma_f32_16x16x32_bf16 v[6:9], v[150:153], v[228:231], v[6:9]
	v_mfma_f32_16x16x32_bf16 v[2:5], v[158:161], v[228:231], v[2:5]
	s_barrier
	s_setprio 0
	s_add_i32 s63, 0, 0x18000
	v_add_u32_e32 v0, s63, v221
	s_add_i32 s64, 0, 0x1c000
	ds_read_b128 v[106:109], v0
	ds_read_b128 v[110:113], v0 offset:1024
	ds_read_b128 v[126:129], v0 offset:2048
	ds_read_b128 v[134:137], v0 offset:3072
	v_add_u32_e32 v0, s64, v221
	ds_read_b128 v[146:149], v0
	ds_read_b128 v[150:153], v0 offset:1024
	ds_read_b128 v[154:157], v0 offset:2048
	ds_read_b128 v[158:161], v0 offset:3072
	s_add_u32 s44, s50, 0xb0000
	s_addc_u32 s45, s51, 0
	s_mov_b32 m0, s55
	v_lshl_add_u64 v[246:247], s[44:45], 0, v[210:211]
	ds_read_b128 v[162:165], v222 offset:32768
	ds_read_b128 v[166:169], v222 offset:33792
	ds_read_b128 v[170:173], v222 offset:34816
	ds_read_b128 v[174:177], v222 offset:35840
	ds_read_b128 v[178:181], v222 offset:36864
	ds_read_b128 v[182:185], v222 offset:37888
	ds_read_b128 v[224:227], v222 offset:38912
	ds_read_b128 v[228:231], v222 offset:39936
	global_load_lds_dwordx4 v[246:247], off
	v_lshl_add_u64 v[246:247], s[44:45], 0, v[206:207]
	s_mov_b32 m0, s56
	s_nop 0
	global_load_lds_dwordx4 v[246:247], off
	s_waitcnt vmcnt(8)
	s_waitcnt lgkmcnt(0)
	s_setprio 1
	s_barrier
	v_mfma_f32_16x16x32_bf16 v[142:145], v[106:109], v[162:165], v[142:145]
	v_mfma_f32_16x16x32_bf16 v[138:141], v[126:129], v[162:165], v[138:141]
	v_mfma_f32_16x16x32_bf16 v[118:121], v[106:109], v[170:173], v[118:121]
	v_mfma_f32_16x16x32_bf16 v[114:117], v[126:129], v[170:173], v[114:117]
	v_mfma_f32_16x16x32_bf16 v[94:97], v[106:109], v[178:181], v[94:97]
	v_mfma_f32_16x16x32_bf16 v[90:93], v[126:129], v[178:181], v[90:93]
	v_mfma_f32_16x16x32_bf16 v[78:81], v[106:109], v[224:227], v[78:81]
	v_mfma_f32_16x16x32_bf16 v[74:77], v[126:129], v[224:227], v[74:77]
	v_mfma_f32_16x16x32_bf16 v[130:133], v[146:149], v[162:165], v[130:133]
	v_mfma_f32_16x16x32_bf16 v[122:125], v[154:157], v[162:165], v[122:125]
	v_mfma_f32_16x16x32_bf16 v[102:105], v[146:149], v[170:173], v[102:105]
	v_mfma_f32_16x16x32_bf16 v[98:101], v[154:157], v[170:173], v[98:101]
	v_mfma_f32_16x16x32_bf16 v[86:89], v[146:149], v[178:181], v[86:89]
	v_mfma_f32_16x16x32_bf16 v[82:85], v[154:157], v[178:181], v[82:85]
	v_mfma_f32_16x16x32_bf16 v[70:73], v[146:149], v[224:227], v[70:73]
	v_mfma_f32_16x16x32_bf16 v[66:69], v[154:157], v[224:227], v[66:69]
	v_mfma_f32_16x16x32_bf16 v[142:145], v[110:113], v[166:169], v[142:145]
	v_mfma_f32_16x16x32_bf16 v[138:141], v[134:137], v[166:169], v[138:141]
	v_mfma_f32_16x16x32_bf16 v[118:121], v[110:113], v[174:177], v[118:121]
	v_mfma_f32_16x16x32_bf16 v[114:117], v[134:137], v[174:177], v[114:117]
	v_mfma_f32_16x16x32_bf16 v[94:97], v[110:113], v[182:185], v[94:97]
	v_mfma_f32_16x16x32_bf16 v[90:93], v[134:137], v[182:185], v[90:93]
	v_mfma_f32_16x16x32_bf16 v[78:81], v[110:113], v[228:231], v[78:81]
	v_mfma_f32_16x16x32_bf16 v[74:77], v[134:137], v[228:231], v[74:77]
	v_mfma_f32_16x16x32_bf16 v[130:133], v[150:153], v[166:169], v[130:133]
	v_mfma_f32_16x16x32_bf16 v[122:125], v[158:161], v[166:169], v[122:125]
	v_mfma_f32_16x16x32_bf16 v[102:105], v[150:153], v[174:177], v[102:105]
	v_mfma_f32_16x16x32_bf16 v[98:101], v[158:161], v[174:177], v[98:101]
	v_mfma_f32_16x16x32_bf16 v[86:89], v[150:153], v[182:185], v[86:89]
	v_mfma_f32_16x16x32_bf16 v[82:85], v[158:161], v[182:185], v[82:85]
	v_mfma_f32_16x16x32_bf16 v[70:73], v[150:153], v[228:231], v[70:73]
	v_mfma_f32_16x16x32_bf16 v[66:69], v[158:161], v[228:231], v[66:69]
	s_barrier
	s_setprio 0
	s_add_i32 s44, s63, s52
	v_lshl_add_u64 v[216:217], v[216:217], 0, s[16:17]
	s_mov_b32 m0, s44
	ds_read_b128 v[162:165], v222 offset:49152
	ds_read_b128 v[166:169], v222 offset:50176
	ds_read_b128 v[170:173], v222 offset:51200
	ds_read_b128 v[174:177], v222 offset:52224
	ds_read_b128 v[178:181], v222 offset:53248
	ds_read_b128 v[182:185], v222 offset:54272
	ds_read_b128 v[224:227], v222 offset:55296
	ds_read_b128 v[228:231], v222 offset:56320
	global_load_lds_dwordx4 v[216:217], off
	s_add_i32 m0, s44, 0x2000
	s_add_u32 s44, s48, 0xb0080
	v_lshl_add_u64 v[216:217], v[240:241], 0, s[16:17]
	s_addc_u32 s45, s49, 0
	s_add_i32 s48, s64, s52
	global_load_lds_dwordx4 v[216:217], off
	v_lshl_add_u64 v[216:217], s[44:45], 0, v[208:209]
	s_mov_b32 m0, s48
	s_nop 0
	global_load_lds_dwordx4 v[216:217], off
	v_lshl_add_u64 v[216:217], s[44:45], 0, v[204:205]
	s_add_i32 m0, s48, 0x2000
	s_nop 0
	global_load_lds_dwordx4 v[216:217], off
	v_lshl_add_u64 v[216:217], v[242:243], 0, s[16:17]
	s_mov_b32 m0, s59
	s_nop 0
	global_load_lds_dwordx4 v[216:217], off
	v_lshl_add_u64 v[216:217], v[244:245], 0, s[16:17]
	s_mov_b32 m0, s60
	s_nop 0
	global_load_lds_dwordx4 v[216:217], off
	s_waitcnt vmcnt(8)
	s_waitcnt lgkmcnt(0)
	s_setprio 1
	s_barrier
	v_mfma_f32_16x16x32_bf16 v[62:65], v[106:109], v[162:165], v[62:65]
	v_mfma_f32_16x16x32_bf16 v[58:61], v[126:129], v[162:165], v[58:61]
	v_mfma_f32_16x16x32_bf16 v[46:49], v[106:109], v[170:173], v[46:49]
	v_mfma_f32_16x16x32_bf16 v[42:45], v[126:129], v[170:173], v[42:45]
	v_mfma_f32_16x16x32_bf16 v[30:33], v[106:109], v[178:181], v[30:33]
	v_mfma_f32_16x16x32_bf16 v[26:29], v[126:129], v[178:181], v[26:29]
	v_mfma_f32_16x16x32_bf16 v[14:17], v[106:109], v[224:227], v[14:17]
	v_mfma_f32_16x16x32_bf16 v[10:13], v[126:129], v[224:227], v[10:13]
	v_mfma_f32_16x16x32_bf16 v[54:57], v[146:149], v[162:165], v[54:57]
	v_mfma_f32_16x16x32_bf16 v[50:53], v[154:157], v[162:165], v[50:53]
	v_mfma_f32_16x16x32_bf16 v[38:41], v[146:149], v[170:173], v[38:41]
	v_mfma_f32_16x16x32_bf16 v[34:37], v[154:157], v[170:173], v[34:37]
	v_mfma_f32_16x16x32_bf16 v[22:25], v[146:149], v[178:181], v[22:25]
	v_mfma_f32_16x16x32_bf16 v[18:21], v[154:157], v[178:181], v[18:21]
	v_mfma_f32_16x16x32_bf16 v[6:9], v[146:149], v[224:227], v[6:9]
	v_mfma_f32_16x16x32_bf16 v[2:5], v[154:157], v[224:227], v[2:5]
	v_mfma_f32_16x16x32_bf16 v[62:65], v[110:113], v[166:169], v[62:65]
	v_mfma_f32_16x16x32_bf16 v[58:61], v[134:137], v[166:169], v[58:61]
	v_mfma_f32_16x16x32_bf16 v[46:49], v[110:113], v[174:177], v[46:49]
	v_mfma_f32_16x16x32_bf16 v[42:45], v[134:137], v[174:177], v[42:45]
	v_mfma_f32_16x16x32_bf16 v[30:33], v[110:113], v[182:185], v[30:33]
	v_mfma_f32_16x16x32_bf16 v[26:29], v[134:137], v[182:185], v[26:29]
	v_mfma_f32_16x16x32_bf16 v[14:17], v[110:113], v[228:231], v[14:17]
	v_mfma_f32_16x16x32_bf16 v[10:13], v[134:137], v[228:231], v[10:13]
	v_mfma_f32_16x16x32_bf16 v[54:57], v[150:153], v[166:169], v[54:57]
	v_mfma_f32_16x16x32_bf16 v[50:53], v[158:161], v[166:169], v[50:53]
	v_mfma_f32_16x16x32_bf16 v[38:41], v[150:153], v[174:177], v[38:41]
	v_mfma_f32_16x16x32_bf16 v[34:37], v[158:161], v[174:177], v[34:37]
	v_mfma_f32_16x16x32_bf16 v[22:25], v[150:153], v[182:185], v[22:25]
	v_mfma_f32_16x16x32_bf16 v[18:21], v[158:161], v[182:185], v[18:21]
	v_mfma_f32_16x16x32_bf16 v[6:9], v[150:153], v[228:231], v[6:9]
	v_mfma_f32_16x16x32_bf16 v[2:5], v[158:161], v[228:231], v[2:5]
	s_barrier
	s_setprio 0
	s_add_i32 s62, s62, 2
	s_add_u32 s7, s7, 0x100
	s_addc_u32 s47, s47, 0
	s_cmp_gt_u32 s62, 41
	s_mov_b64 s[44:45], s[0:1]
.LBB0_1088:
	s_add_u32 s0, s44, 0x100
	s_addc_u32 s1, s45, 0
	s_add_i32 s63, 0, 0x10000
	s_cmp_eq_u32 s62, 40
	s_cselect_b32 s51, s41, s1
	s_cselect_b32 s50, s40, s0
	v_add_u32_e32 v0, s63, v221
	s_cselect_b32 s49, s43, s47
	s_cselect_b32 s48, s42, s7
	s_add_i32 s64, 0, 0x14000
	ds_read_b128 v[106:109], v0
	ds_read_b128 v[110:113], v0 offset:1024
	ds_read_b128 v[126:129], v0 offset:2048
	ds_read_b128 v[134:137], v0 offset:3072
	v_add_u32_e32 v0, s64, v221
	ds_read_b128 v[146:149], v0
	ds_read_b128 v[150:153], v0 offset:1024
	ds_read_b128 v[154:157], v0 offset:2048
	ds_read_b128 v[158:161], v0 offset:3072
	v_lshl_add_u64 v[216:217], s[44:45], 0, v[212:213]
	s_add_i32 m0, s53, 0xc000
	ds_read_b128 v[162:165], v222
	ds_read_b128 v[166:169], v222 offset:1024
	ds_read_b128 v[170:173], v222 offset:2048
	ds_read_b128 v[174:177], v222 offset:3072
	ds_read_b128 v[178:181], v222 offset:4096
	ds_read_b128 v[182:185], v222 offset:5120
	ds_read_b128 v[224:227], v222 offset:6144
	ds_read_b128 v[228:231], v222 offset:7168
	global_load_lds_dwordx4 v[216:217], off
	v_lshl_add_u64 v[216:217], s[44:45], 0, v[214:215]
	s_add_i32 m0, s53, 0xe000
	s_nop 0
	global_load_lds_dwordx4 v[216:217], off
	s_waitcnt vmcnt(8)
	s_waitcnt lgkmcnt(0)
	s_setprio 1
	s_barrier
	v_mfma_f32_16x16x32_bf16 v[142:145], v[106:109], v[162:165], v[142:145]
	v_mfma_f32_16x16x32_bf16 v[138:141], v[126:129], v[162:165], v[138:141]
	v_mfma_f32_16x16x32_bf16 v[118:121], v[106:109], v[170:173], v[118:121]
	v_mfma_f32_16x16x32_bf16 v[114:117], v[126:129], v[170:173], v[114:117]
	v_mfma_f32_16x16x32_bf16 v[94:97], v[106:109], v[178:181], v[94:97]
	v_mfma_f32_16x16x32_bf16 v[90:93], v[126:129], v[178:181], v[90:93]
	v_mfma_f32_16x16x32_bf16 v[78:81], v[106:109], v[224:227], v[78:81]
	v_mfma_f32_16x16x32_bf16 v[74:77], v[126:129], v[224:227], v[74:77]
	v_mfma_f32_16x16x32_bf16 v[130:133], v[146:149], v[162:165], v[130:133]
	v_mfma_f32_16x16x32_bf16 v[122:125], v[154:157], v[162:165], v[122:125]
	v_mfma_f32_16x16x32_bf16 v[102:105], v[146:149], v[170:173], v[102:105]
	v_mfma_f32_16x16x32_bf16 v[98:101], v[154:157], v[170:173], v[98:101]
	v_mfma_f32_16x16x32_bf16 v[86:89], v[146:149], v[178:181], v[86:89]
	v_mfma_f32_16x16x32_bf16 v[82:85], v[154:157], v[178:181], v[82:85]
	v_mfma_f32_16x16x32_bf16 v[70:73], v[146:149], v[224:227], v[70:73]
	v_mfma_f32_16x16x32_bf16 v[66:69], v[154:157], v[224:227], v[66:69]
	v_mfma_f32_16x16x32_bf16 v[142:145], v[110:113], v[166:169], v[142:145]
	v_mfma_f32_16x16x32_bf16 v[138:141], v[134:137], v[166:169], v[138:141]
	v_mfma_f32_16x16x32_bf16 v[118:121], v[110:113], v[174:177], v[118:121]
	v_mfma_f32_16x16x32_bf16 v[114:117], v[134:137], v[174:177], v[114:117]
	v_mfma_f32_16x16x32_bf16 v[94:97], v[110:113], v[182:185], v[94:97]
	v_mfma_f32_16x16x32_bf16 v[90:93], v[134:137], v[182:185], v[90:93]
	v_mfma_f32_16x16x32_bf16 v[78:81], v[110:113], v[228:231], v[78:81]
	v_mfma_f32_16x16x32_bf16 v[74:77], v[134:137], v[228:231], v[74:77]
	v_mfma_f32_16x16x32_bf16 v[130:133], v[150:153], v[166:169], v[130:133]
	v_mfma_f32_16x16x32_bf16 v[122:125], v[158:161], v[166:169], v[122:125]
	v_mfma_f32_16x16x32_bf16 v[102:105], v[150:153], v[174:177], v[102:105]
	v_mfma_f32_16x16x32_bf16 v[98:101], v[158:161], v[174:177], v[98:101]
	v_mfma_f32_16x16x32_bf16 v[86:89], v[150:153], v[182:185], v[86:89]
	v_mfma_f32_16x16x32_bf16 v[82:85], v[158:161], v[182:185], v[82:85]
	v_mfma_f32_16x16x32_bf16 v[70:73], v[150:153], v[228:231], v[70:73]
	v_mfma_f32_16x16x32_bf16 v[66:69], v[158:161], v[228:231], v[66:69]
	s_barrier
	s_setprio 0
	s_add_i32 s44, s63, s52
	v_lshl_add_u64 v[216:217], s[48:49], 0, v[208:209]
	s_mov_b32 m0, s44
	ds_read_b128 v[162:165], v222 offset:16384
	ds_read_b128 v[166:169], v222 offset:17408
	ds_read_b128 v[170:173], v222 offset:18432
	ds_read_b128 v[174:177], v222 offset:19456
	ds_read_b128 v[178:181], v222 offset:20480
	ds_read_b128 v[182:185], v222 offset:21504
	ds_read_b128 v[224:227], v222 offset:22528
	ds_read_b128 v[228:231], v222 offset:23552
	global_load_lds_dwordx4 v[216:217], off
	s_add_i32 m0, s44, 0x2000
	s_add_u32 s44, s48, 0xb0000
	v_lshl_add_u64 v[240:241], s[48:49], 0, v[204:205]
	s_addc_u32 s45, s49, 0
	s_add_i32 s63, s64, s52
	global_load_lds_dwordx4 v[240:241], off
	v_lshl_add_u64 v[242:243], s[44:45], 0, v[208:209]
	s_mov_b32 m0, s63
	v_lshl_add_u64 v[244:245], s[50:51], 0, v[206:207]
	global_load_lds_dwordx4 v[242:243], off
	v_lshl_add_u64 v[242:243], s[44:45], 0, v[204:205]
	s_add_i32 m0, s63, 0x2000
	s_nop 0
	global_load_lds_dwordx4 v[242:243], off
	v_lshl_add_u64 v[242:243], s[50:51], 0, v[210:211]
	s_mov_b32 m0, s53
	s_nop 0
	global_load_lds_dwordx4 v[242:243], off
	s_mov_b32 m0, s54
	s_nop 0
	global_load_lds_dwordx4 v[244:245], off
	s_waitcnt vmcnt(8)
	s_waitcnt lgkmcnt(0)
	s_setprio 1
	s_barrier
	v_mfma_f32_16x16x32_bf16 v[62:65], v[106:109], v[162:165], v[62:65]
	v_mfma_f32_16x16x32_bf16 v[58:61], v[126:129], v[162:165], v[58:61]
	v_mfma_f32_16x16x32_bf16 v[46:49], v[106:109], v[170:173], v[46:49]
	v_mfma_f32_16x16x32_bf16 v[42:45], v[126:129], v[170:173], v[42:45]
	v_mfma_f32_16x16x32_bf16 v[30:33], v[106:109], v[178:181], v[30:33]
	v_mfma_f32_16x16x32_bf16 v[26:29], v[126:129], v[178:181], v[26:29]
	v_mfma_f32_16x16x32_bf16 v[14:17], v[106:109], v[224:227], v[14:17]
	v_mfma_f32_16x16x32_bf16 v[10:13], v[126:129], v[224:227], v[10:13]
	v_mfma_f32_16x16x32_bf16 v[54:57], v[146:149], v[162:165], v[54:57]
	v_mfma_f32_16x16x32_bf16 v[50:53], v[154:157], v[162:165], v[50:53]
	v_mfma_f32_16x16x32_bf16 v[38:41], v[146:149], v[170:173], v[38:41]
	v_mfma_f32_16x16x32_bf16 v[34:37], v[154:157], v[170:173], v[34:37]
	v_mfma_f32_16x16x32_bf16 v[22:25], v[146:149], v[178:181], v[22:25]
	v_mfma_f32_16x16x32_bf16 v[18:21], v[154:157], v[178:181], v[18:21]
	v_mfma_f32_16x16x32_bf16 v[6:9], v[146:149], v[224:227], v[6:9]
	v_mfma_f32_16x16x32_bf16 v[2:5], v[154:157], v[224:227], v[2:5]
	v_mfma_f32_16x16x32_bf16 v[62:65], v[110:113], v[166:169], v[62:65]
	v_mfma_f32_16x16x32_bf16 v[58:61], v[134:137], v[166:169], v[58:61]
	v_mfma_f32_16x16x32_bf16 v[46:49], v[110:113], v[174:177], v[46:49]
	v_mfma_f32_16x16x32_bf16 v[42:45], v[134:137], v[174:177], v[42:45]
	v_mfma_f32_16x16x32_bf16 v[30:33], v[110:113], v[182:185], v[30:33]
	v_mfma_f32_16x16x32_bf16 v[26:29], v[134:137], v[182:185], v[26:29]
	v_mfma_f32_16x16x32_bf16 v[14:17], v[110:113], v[228:231], v[14:17]
	v_mfma_f32_16x16x32_bf16 v[10:13], v[134:137], v[228:231], v[10:13]
	v_mfma_f32_16x16x32_bf16 v[54:57], v[150:153], v[166:169], v[54:57]
	v_mfma_f32_16x16x32_bf16 v[50:53], v[158:161], v[166:169], v[50:53]
	v_mfma_f32_16x16x32_bf16 v[38:41], v[150:153], v[174:177], v[38:41]
	v_mfma_f32_16x16x32_bf16 v[34:37], v[158:161], v[174:177], v[34:37]
	v_mfma_f32_16x16x32_bf16 v[22:25], v[150:153], v[182:185], v[22:25]
	v_mfma_f32_16x16x32_bf16 v[18:21], v[158:161], v[182:185], v[18:21]
	v_mfma_f32_16x16x32_bf16 v[6:9], v[150:153], v[228:231], v[6:9]
	v_mfma_f32_16x16x32_bf16 v[2:5], v[158:161], v[228:231], v[2:5]
	s_barrier
	s_setprio 0
	s_add_i32 s63, 0, 0x18000
	v_add_u32_e32 v0, s63, v221
	s_add_i32 s64, 0, 0x1c000
	ds_read_b128 v[106:109], v0
	ds_read_b128 v[110:113], v0 offset:1024
	ds_read_b128 v[126:129], v0 offset:2048
	ds_read_b128 v[134:137], v0 offset:3072
	v_add_u32_e32 v0, s64, v221
	ds_read_b128 v[146:149], v0
	ds_read_b128 v[150:153], v0 offset:1024
	ds_read_b128 v[154:157], v0 offset:2048
	ds_read_b128 v[158:161], v0 offset:3072
	s_add_u32 s44, s50, 0xb0000
	s_addc_u32 s45, s51, 0
	s_mov_b32 m0, s55
	v_lshl_add_u64 v[246:247], s[44:45], 0, v[210:211]
	ds_read_b128 v[162:165], v222 offset:32768
	ds_read_b128 v[166:169], v222 offset:33792
	ds_read_b128 v[170:173], v222 offset:34816
	ds_read_b128 v[174:177], v222 offset:35840
	ds_read_b128 v[178:181], v222 offset:36864
	ds_read_b128 v[182:185], v222 offset:37888
	ds_read_b128 v[224:227], v222 offset:38912
	ds_read_b128 v[228:231], v222 offset:39936
	global_load_lds_dwordx4 v[246:247], off
	v_lshl_add_u64 v[246:247], s[44:45], 0, v[206:207]
	s_mov_b32 m0, s56
	s_nop 0
	global_load_lds_dwordx4 v[246:247], off
	s_waitcnt vmcnt(8)
	s_waitcnt lgkmcnt(0)
	s_setprio 1
	s_barrier
	v_mfma_f32_16x16x32_bf16 v[142:145], v[106:109], v[162:165], v[142:145]
	v_mfma_f32_16x16x32_bf16 v[138:141], v[126:129], v[162:165], v[138:141]
	v_mfma_f32_16x16x32_bf16 v[118:121], v[106:109], v[170:173], v[118:121]
	v_mfma_f32_16x16x32_bf16 v[114:117], v[126:129], v[170:173], v[114:117]
	v_mfma_f32_16x16x32_bf16 v[94:97], v[106:109], v[178:181], v[94:97]
	v_mfma_f32_16x16x32_bf16 v[90:93], v[126:129], v[178:181], v[90:93]
	v_mfma_f32_16x16x32_bf16 v[78:81], v[106:109], v[224:227], v[78:81]
	v_mfma_f32_16x16x32_bf16 v[74:77], v[126:129], v[224:227], v[74:77]
	v_mfma_f32_16x16x32_bf16 v[130:133], v[146:149], v[162:165], v[130:133]
	v_mfma_f32_16x16x32_bf16 v[122:125], v[154:157], v[162:165], v[122:125]
	v_mfma_f32_16x16x32_bf16 v[102:105], v[146:149], v[170:173], v[102:105]
	v_mfma_f32_16x16x32_bf16 v[98:101], v[154:157], v[170:173], v[98:101]
	v_mfma_f32_16x16x32_bf16 v[86:89], v[146:149], v[178:181], v[86:89]
	v_mfma_f32_16x16x32_bf16 v[82:85], v[154:157], v[178:181], v[82:85]
	v_mfma_f32_16x16x32_bf16 v[70:73], v[146:149], v[224:227], v[70:73]
	v_mfma_f32_16x16x32_bf16 v[66:69], v[154:157], v[224:227], v[66:69]
	v_mfma_f32_16x16x32_bf16 v[142:145], v[110:113], v[166:169], v[142:145]
	v_mfma_f32_16x16x32_bf16 v[138:141], v[134:137], v[166:169], v[138:141]
	v_mfma_f32_16x16x32_bf16 v[118:121], v[110:113], v[174:177], v[118:121]
	v_mfma_f32_16x16x32_bf16 v[114:117], v[134:137], v[174:177], v[114:117]
	v_mfma_f32_16x16x32_bf16 v[94:97], v[110:113], v[182:185], v[94:97]
	v_mfma_f32_16x16x32_bf16 v[90:93], v[134:137], v[182:185], v[90:93]
	v_mfma_f32_16x16x32_bf16 v[78:81], v[110:113], v[228:231], v[78:81]
	v_mfma_f32_16x16x32_bf16 v[74:77], v[134:137], v[228:231], v[74:77]
	v_mfma_f32_16x16x32_bf16 v[130:133], v[150:153], v[166:169], v[130:133]
	v_mfma_f32_16x16x32_bf16 v[122:125], v[158:161], v[166:169], v[122:125]
	v_mfma_f32_16x16x32_bf16 v[102:105], v[150:153], v[174:177], v[102:105]
	v_mfma_f32_16x16x32_bf16 v[98:101], v[158:161], v[174:177], v[98:101]
	v_mfma_f32_16x16x32_bf16 v[86:89], v[150:153], v[182:185], v[86:89]
	v_mfma_f32_16x16x32_bf16 v[82:85], v[158:161], v[182:185], v[82:85]
	v_mfma_f32_16x16x32_bf16 v[70:73], v[150:153], v[228:231], v[70:73]
	v_mfma_f32_16x16x32_bf16 v[66:69], v[158:161], v[228:231], v[66:69]
	s_barrier
	s_setprio 0
	s_add_i32 s44, s63, s52
	v_lshl_add_u64 v[216:217], v[216:217], 0, s[16:17]
	s_mov_b32 m0, s44
	ds_read_b128 v[162:165], v222 offset:49152
	ds_read_b128 v[166:169], v222 offset:50176
	ds_read_b128 v[170:173], v222 offset:51200
	ds_read_b128 v[174:177], v222 offset:52224
	ds_read_b128 v[178:181], v222 offset:53248
	ds_read_b128 v[182:185], v222 offset:54272
	ds_read_b128 v[224:227], v222 offset:55296
	ds_read_b128 v[228:231], v222 offset:56320
	global_load_lds_dwordx4 v[216:217], off
	s_add_i32 m0, s44, 0x2000
	s_add_u32 s44, s48, 0xb0080
	v_lshl_add_u64 v[216:217], v[240:241], 0, s[16:17]
	s_addc_u32 s45, s49, 0
	s_add_i32 s48, s64, s52
	global_load_lds_dwordx4 v[216:217], off
	v_lshl_add_u64 v[216:217], s[44:45], 0, v[208:209]
	s_mov_b32 m0, s48
	s_nop 0
	global_load_lds_dwordx4 v[216:217], off
	v_lshl_add_u64 v[216:217], s[44:45], 0, v[204:205]
	s_add_i32 m0, s48, 0x2000
	s_nop 0
	global_load_lds_dwordx4 v[216:217], off
	v_lshl_add_u64 v[216:217], v[242:243], 0, s[16:17]
	s_mov_b32 m0, s59
	s_nop 0
	global_load_lds_dwordx4 v[216:217], off
	v_lshl_add_u64 v[216:217], v[244:245], 0, s[16:17]
	s_mov_b32 m0, s60
	s_nop 0
	global_load_lds_dwordx4 v[216:217], off
	s_waitcnt vmcnt(8)
	s_waitcnt lgkmcnt(0)
	s_setprio 1
	s_barrier
	v_mfma_f32_16x16x32_bf16 v[62:65], v[106:109], v[162:165], v[62:65]
	v_mfma_f32_16x16x32_bf16 v[58:61], v[126:129], v[162:165], v[58:61]
	v_mfma_f32_16x16x32_bf16 v[46:49], v[106:109], v[170:173], v[46:49]
	v_mfma_f32_16x16x32_bf16 v[42:45], v[126:129], v[170:173], v[42:45]
	v_mfma_f32_16x16x32_bf16 v[30:33], v[106:109], v[178:181], v[30:33]
	v_mfma_f32_16x16x32_bf16 v[26:29], v[126:129], v[178:181], v[26:29]
	v_mfma_f32_16x16x32_bf16 v[14:17], v[106:109], v[224:227], v[14:17]
	v_mfma_f32_16x16x32_bf16 v[10:13], v[126:129], v[224:227], v[10:13]
	v_mfma_f32_16x16x32_bf16 v[54:57], v[146:149], v[162:165], v[54:57]
	v_mfma_f32_16x16x32_bf16 v[50:53], v[154:157], v[162:165], v[50:53]
	v_mfma_f32_16x16x32_bf16 v[38:41], v[146:149], v[170:173], v[38:41]
	v_mfma_f32_16x16x32_bf16 v[34:37], v[154:157], v[170:173], v[34:37]
	v_mfma_f32_16x16x32_bf16 v[22:25], v[146:149], v[178:181], v[22:25]
	v_mfma_f32_16x16x32_bf16 v[18:21], v[154:157], v[178:181], v[18:21]
	v_mfma_f32_16x16x32_bf16 v[6:9], v[146:149], v[224:227], v[6:9]
	v_mfma_f32_16x16x32_bf16 v[2:5], v[154:157], v[224:227], v[2:5]
	v_mfma_f32_16x16x32_bf16 v[62:65], v[110:113], v[166:169], v[62:65]
	v_mfma_f32_16x16x32_bf16 v[58:61], v[134:137], v[166:169], v[58:61]
	v_mfma_f32_16x16x32_bf16 v[46:49], v[110:113], v[174:177], v[46:49]
	v_mfma_f32_16x16x32_bf16 v[42:45], v[134:137], v[174:177], v[42:45]
	v_mfma_f32_16x16x32_bf16 v[30:33], v[110:113], v[182:185], v[30:33]
	v_mfma_f32_16x16x32_bf16 v[26:29], v[134:137], v[182:185], v[26:29]
	v_mfma_f32_16x16x32_bf16 v[14:17], v[110:113], v[228:231], v[14:17]
	v_mfma_f32_16x16x32_bf16 v[10:13], v[134:137], v[228:231], v[10:13]
	v_mfma_f32_16x16x32_bf16 v[54:57], v[150:153], v[166:169], v[54:57]
	v_mfma_f32_16x16x32_bf16 v[50:53], v[158:161], v[166:169], v[50:53]
	v_mfma_f32_16x16x32_bf16 v[38:41], v[150:153], v[174:177], v[38:41]
	v_mfma_f32_16x16x32_bf16 v[34:37], v[158:161], v[174:177], v[34:37]
	v_mfma_f32_16x16x32_bf16 v[22:25], v[150:153], v[182:185], v[22:25]
	v_mfma_f32_16x16x32_bf16 v[18:21], v[158:161], v[182:185], v[18:21]
	v_mfma_f32_16x16x32_bf16 v[6:9], v[150:153], v[228:231], v[6:9]
	v_mfma_f32_16x16x32_bf16 v[2:5], v[158:161], v[228:231], v[2:5]
	s_barrier
	s_setprio 0
	s_add_i32 s62, s62, 2
	s_add_u32 s7, s7, 0x100
	s_addc_u32 s47, s47, 0
	s_cmp_gt_u32 s62, 41
	s_mov_b64 s[44:45], s[0:1]
	s_cbranch_scc0 .LBB0_1088
	s_and_b64 vcc, exec, s[22:23]
	s_cbranch_vccz .LBB0_1091
	s_barrier

.Lrb7_skip:
	s_add_u32 s42, s40, 0xfffc0080
	s_addc_u32 s43, s41, -1
	s_add_i32 s54, 0, 0x10000
	s_cmp_eq_u32 s53, 12
	s_cselect_b32 s49, s7, s43
	s_cselect_b32 s48, s23, s42
	v_add_u32_e32 v0, s54, v160
	s_cselect_b32 s43, s21, s52
	s_cselect_b32 s42, s50, s51
	s_add_i32 s65, 0, 0x14000
	ds_read_b128 v[142:145], v0
	ds_read_b128 v[146:149], v0 offset:1024
	ds_read_b128 v[150:153], v0 offset:2048
	ds_read_b128 v[154:157], v0 offset:3072
	v_add_u32_e32 v0, s65, v160
	ds_read_b128 v[162:165], v0
	ds_read_b128 v[166:169], v0 offset:1024
	ds_read_b128 v[170:173], v0 offset:2048
	ds_read_b128 v[174:177], v0 offset:3072
	v_lshl_add_u64 v[228:229], s[40:41], 0, v[138:139]
	s_add_i32 m0, s57, 0xc000
	ds_read_b128 v[178:181], v161
	ds_read_b128 v[182:185], v161 offset:1024
	ds_read_b128 v[204:207], v161 offset:2048
	ds_read_b128 v[208:211], v161 offset:3072
	ds_read_b128 v[212:215], v161 offset:4096
	ds_read_b128 v[216:219], v161 offset:5120
	ds_read_b128 v[220:223], v161 offset:6144
	ds_read_b128 v[224:227], v161 offset:7168
	global_load_lds_dwordx4 v[228:229], off
	v_lshl_add_u64 v[228:229], s[40:41], 0, v[140:141]
	s_add_i32 m0, s57, 0xe000
	s_nop 0
	global_load_lds_dwordx4 v[228:229], off
	s_waitcnt vmcnt(8)
	s_waitcnt lgkmcnt(0)
	s_setprio 1
	s_barrier
	v_mfma_f32_16x16x32_bf16 v[126:129], v[142:145], v[178:181], 0
	v_mfma_f32_16x16x32_bf16 v[122:125], v[150:153], v[178:181], 0
	v_mfma_f32_16x16x32_bf16 v[110:113], v[142:145], v[204:207], 0
	v_mfma_f32_16x16x32_bf16 v[106:109], v[150:153], v[204:207], 0
	v_mfma_f32_16x16x32_bf16 v[94:97], v[142:145], v[212:215], 0
	v_mfma_f32_16x16x32_bf16 v[90:93], v[150:153], v[212:215], 0
	v_mfma_f32_16x16x32_bf16 v[78:81], v[142:145], v[220:223], 0
	v_mfma_f32_16x16x32_bf16 v[74:77], v[150:153], v[220:223], 0
	v_mfma_f32_16x16x32_bf16 v[118:121], v[162:165], v[178:181], 0
	v_mfma_f32_16x16x32_bf16 v[114:117], v[170:173], v[178:181], 0
	v_mfma_f32_16x16x32_bf16 v[102:105], v[162:165], v[204:207], 0
	v_mfma_f32_16x16x32_bf16 v[98:101], v[170:173], v[204:207], 0
	v_mfma_f32_16x16x32_bf16 v[86:89], v[162:165], v[212:215], 0
	v_mfma_f32_16x16x32_bf16 v[82:85], v[170:173], v[212:215], 0
	v_mfma_f32_16x16x32_bf16 v[70:73], v[162:165], v[220:223], 0
	v_mfma_f32_16x16x32_bf16 v[66:69], v[170:173], v[220:223], 0
	v_mfma_f32_16x16x32_bf16 v[126:129], v[146:149], v[182:185], v[126:129]
	v_mfma_f32_16x16x32_bf16 v[122:125], v[154:157], v[182:185], v[122:125]
	v_mfma_f32_16x16x32_bf16 v[110:113], v[146:149], v[208:211], v[110:113]
	v_mfma_f32_16x16x32_bf16 v[106:109], v[154:157], v[208:211], v[106:109]
	v_mfma_f32_16x16x32_bf16 v[94:97], v[146:149], v[216:219], v[94:97]
	v_mfma_f32_16x16x32_bf16 v[90:93], v[154:157], v[216:219], v[90:93]
	v_mfma_f32_16x16x32_bf16 v[78:81], v[146:149], v[224:227], v[78:81]
	v_mfma_f32_16x16x32_bf16 v[74:77], v[154:157], v[224:227], v[74:77]
	v_mfma_f32_16x16x32_bf16 v[118:121], v[166:169], v[182:185], v[118:121]
	v_mfma_f32_16x16x32_bf16 v[114:117], v[174:177], v[182:185], v[114:117]
	v_mfma_f32_16x16x32_bf16 v[102:105], v[166:169], v[208:211], v[102:105]
	v_mfma_f32_16x16x32_bf16 v[98:101], v[174:177], v[208:211], v[98:101]
	v_mfma_f32_16x16x32_bf16 v[86:89], v[166:169], v[216:219], v[86:89]
	v_mfma_f32_16x16x32_bf16 v[82:85], v[174:177], v[216:219], v[82:85]
	v_mfma_f32_16x16x32_bf16 v[70:73], v[166:169], v[224:227], v[70:73]
	v_mfma_f32_16x16x32_bf16 v[66:69], v[174:177], v[224:227], v[66:69]
	s_barrier
	s_setprio 0
	s_add_i32 s54, s54, s56
	v_lshl_add_u64 v[228:229], s[42:43], 0, v[134:135]
	s_mov_b32 m0, s54
	ds_read_b128 v[178:181], v161 offset:16384
	ds_read_b128 v[182:185], v161 offset:17408
	ds_read_b128 v[204:207], v161 offset:18432
	ds_read_b128 v[208:211], v161 offset:19456
	ds_read_b128 v[212:215], v161 offset:20480
	ds_read_b128 v[216:219], v161 offset:21504
	ds_read_b128 v[220:223], v161 offset:22528
	ds_read_b128 v[224:227], v161 offset:23552
	global_load_lds_dwordx4 v[228:229], off
	s_add_i32 m0, s54, 0x2000
	s_add_u32 s54, s42, 0x40000
	v_lshl_add_u64 v[230:231], s[42:43], 0, v[130:131]
	s_addc_u32 s55, s43, 0
	s_add_i32 s65, s65, s56
	global_load_lds_dwordx4 v[230:231], off
	v_lshl_add_u64 v[240:241], s[54:55], 0, v[134:135]
	s_mov_b32 m0, s65
	v_lshl_add_u64 v[242:243], s[48:49], 0, v[132:133]
	global_load_lds_dwordx4 v[240:241], off
	v_lshl_add_u64 v[240:241], s[54:55], 0, v[130:131]
	s_add_i32 m0, s65, 0x2000
	s_nop 0
	global_load_lds_dwordx4 v[240:241], off
	v_lshl_add_u64 v[240:241], s[48:49], 0, v[136:137]
	s_mov_b32 m0, s57
	s_nop 0
	global_load_lds_dwordx4 v[240:241], off
	s_mov_b32 m0, s58
	s_nop 0
	global_load_lds_dwordx4 v[242:243], off
	s_waitcnt vmcnt(8)
	s_waitcnt lgkmcnt(0)
	s_setprio 1
	s_barrier
	v_mfma_f32_16x16x32_bf16 v[62:65], v[142:145], v[178:181], 0
	v_mfma_f32_16x16x32_bf16 v[58:61], v[150:153], v[178:181], 0
	v_mfma_f32_16x16x32_bf16 v[46:49], v[142:145], v[204:207], 0
	v_mfma_f32_16x16x32_bf16 v[42:45], v[150:153], v[204:207], 0
	v_mfma_f32_16x16x32_bf16 v[30:33], v[142:145], v[212:215], 0
	v_mfma_f32_16x16x32_bf16 v[26:29], v[150:153], v[212:215], 0
	v_mfma_f32_16x16x32_bf16 v[14:17], v[142:145], v[220:223], 0
	v_mfma_f32_16x16x32_bf16 v[10:13], v[150:153], v[220:223], 0
	v_mfma_f32_16x16x32_bf16 v[54:57], v[162:165], v[178:181], 0
	v_mfma_f32_16x16x32_bf16 v[50:53], v[170:173], v[178:181], 0
	v_mfma_f32_16x16x32_bf16 v[38:41], v[162:165], v[204:207], 0
	v_mfma_f32_16x16x32_bf16 v[34:37], v[170:173], v[204:207], 0
	v_mfma_f32_16x16x32_bf16 v[22:25], v[162:165], v[212:215], 0
	v_mfma_f32_16x16x32_bf16 v[18:21], v[170:173], v[212:215], 0
	v_mfma_f32_16x16x32_bf16 v[6:9], v[162:165], v[220:223], 0
	v_mfma_f32_16x16x32_bf16 v[2:5], v[170:173], v[220:223], 0
	v_mfma_f32_16x16x32_bf16 v[62:65], v[146:149], v[182:185], v[62:65]
	v_mfma_f32_16x16x32_bf16 v[58:61], v[154:157], v[182:185], v[58:61]
	v_mfma_f32_16x16x32_bf16 v[46:49], v[146:149], v[208:211], v[46:49]
	v_mfma_f32_16x16x32_bf16 v[42:45], v[154:157], v[208:211], v[42:45]
	v_mfma_f32_16x16x32_bf16 v[30:33], v[146:149], v[216:219], v[30:33]
	v_mfma_f32_16x16x32_bf16 v[26:29], v[154:157], v[216:219], v[26:29]
	v_mfma_f32_16x16x32_bf16 v[14:17], v[146:149], v[224:227], v[14:17]
	v_mfma_f32_16x16x32_bf16 v[10:13], v[154:157], v[224:227], v[10:13]
	v_mfma_f32_16x16x32_bf16 v[54:57], v[166:169], v[182:185], v[54:57]
	v_mfma_f32_16x16x32_bf16 v[50:53], v[174:177], v[182:185], v[50:53]
	v_mfma_f32_16x16x32_bf16 v[38:41], v[166:169], v[208:211], v[38:41]
	v_mfma_f32_16x16x32_bf16 v[34:37], v[174:177], v[208:211], v[34:37]
	v_mfma_f32_16x16x32_bf16 v[22:25], v[166:169], v[216:219], v[22:25]
	v_mfma_f32_16x16x32_bf16 v[18:21], v[174:177], v[216:219], v[18:21]
	v_mfma_f32_16x16x32_bf16 v[6:9], v[166:169], v[224:227], v[6:9]
	v_mfma_f32_16x16x32_bf16 v[2:5], v[174:177], v[224:227], v[2:5]
	s_barrier
	s_setprio 0
	s_add_i32 s54, 0, 0x18000
	v_add_u32_e32 v0, s54, v160
	s_add_i32 s55, 0, 0x1c000
	ds_read_b128 v[142:145], v0
	ds_read_b128 v[146:149], v0 offset:1024
	ds_read_b128 v[150:153], v0 offset:2048
	ds_read_b128 v[154:157], v0 offset:3072
	v_add_u32_e32 v0, s55, v160
	ds_read_b128 v[162:165], v0
	ds_read_b128 v[166:169], v0 offset:1024
	ds_read_b128 v[170:173], v0 offset:2048
	ds_read_b128 v[174:177], v0 offset:3072
	s_add_u32 s48, s48, 0x40000
	s_addc_u32 s49, s49, 0
	s_mov_b32 m0, s59
	v_lshl_add_u64 v[244:245], s[48:49], 0, v[136:137]
	ds_read_b128 v[178:181], v161 offset:32768
	ds_read_b128 v[182:185], v161 offset:33792
	ds_read_b128 v[204:207], v161 offset:34816
	ds_read_b128 v[208:211], v161 offset:35840
	ds_read_b128 v[212:215], v161 offset:36864
	ds_read_b128 v[216:219], v161 offset:37888
	ds_read_b128 v[220:223], v161 offset:38912
	ds_read_b128 v[224:227], v161 offset:39936
	global_load_lds_dwordx4 v[244:245], off
	v_lshl_add_u64 v[244:245], s[48:49], 0, v[132:133]
	s_mov_b32 m0, s60
	s_nop 0
	global_load_lds_dwordx4 v[244:245], off
	s_waitcnt vmcnt(8)
	s_waitcnt lgkmcnt(0)
	s_setprio 1
	s_barrier
	v_mfma_f32_16x16x32_bf16 v[126:129], v[142:145], v[178:181], v[126:129]
	v_mfma_f32_16x16x32_bf16 v[122:125], v[150:153], v[178:181], v[122:125]
	v_mfma_f32_16x16x32_bf16 v[110:113], v[142:145], v[204:207], v[110:113]
	v_mfma_f32_16x16x32_bf16 v[106:109], v[150:153], v[204:207], v[106:109]
	v_mfma_f32_16x16x32_bf16 v[94:97], v[142:145], v[212:215], v[94:97]
	v_mfma_f32_16x16x32_bf16 v[90:93], v[150:153], v[212:215], v[90:93]
	v_mfma_f32_16x16x32_bf16 v[78:81], v[142:145], v[220:223], v[78:81]
	v_mfma_f32_16x16x32_bf16 v[74:77], v[150:153], v[220:223], v[74:77]
	v_mfma_f32_16x16x32_bf16 v[118:121], v[162:165], v[178:181], v[118:121]
	v_mfma_f32_16x16x32_bf16 v[114:117], v[170:173], v[178:181], v[114:117]
	v_mfma_f32_16x16x32_bf16 v[102:105], v[162:165], v[204:207], v[102:105]
	v_mfma_f32_16x16x32_bf16 v[98:101], v[170:173], v[204:207], v[98:101]
	v_mfma_f32_16x16x32_bf16 v[86:89], v[162:165], v[212:215], v[86:89]
	v_mfma_f32_16x16x32_bf16 v[82:85], v[170:173], v[212:215], v[82:85]
	v_mfma_f32_16x16x32_bf16 v[70:73], v[162:165], v[220:223], v[70:73]
	v_mfma_f32_16x16x32_bf16 v[66:69], v[170:173], v[220:223], v[66:69]
	v_mfma_f32_16x16x32_bf16 v[126:129], v[146:149], v[182:185], v[126:129]
	v_mfma_f32_16x16x32_bf16 v[122:125], v[154:157], v[182:185], v[122:125]
	v_mfma_f32_16x16x32_bf16 v[110:113], v[146:149], v[208:211], v[110:113]
	v_mfma_f32_16x16x32_bf16 v[106:109], v[154:157], v[208:211], v[106:109]
	v_mfma_f32_16x16x32_bf16 v[94:97], v[146:149], v[216:219], v[94:97]
	v_mfma_f32_16x16x32_bf16 v[90:93], v[154:157], v[216:219], v[90:93]
	v_mfma_f32_16x16x32_bf16 v[78:81], v[146:149], v[224:227], v[78:81]
	v_mfma_f32_16x16x32_bf16 v[74:77], v[154:157], v[224:227], v[74:77]
	v_mfma_f32_16x16x32_bf16 v[118:121], v[166:169], v[182:185], v[118:121]
	v_mfma_f32_16x16x32_bf16 v[114:117], v[174:177], v[182:185], v[114:117]
	v_mfma_f32_16x16x32_bf16 v[102:105], v[166:169], v[208:211], v[102:105]
	v_mfma_f32_16x16x32_bf16 v[98:101], v[174:177], v[208:211], v[98:101]
	v_mfma_f32_16x16x32_bf16 v[86:89], v[166:169], v[216:219], v[86:89]
	v_mfma_f32_16x16x32_bf16 v[82:85], v[174:177], v[216:219], v[82:85]
	v_mfma_f32_16x16x32_bf16 v[70:73], v[166:169], v[224:227], v[70:73]
	v_mfma_f32_16x16x32_bf16 v[66:69], v[174:177], v[224:227], v[66:69]
	s_barrier
	s_setprio 0
	s_add_i32 s48, s54, s56
	v_lshl_add_u64 v[228:229], v[228:229], 0, s[16:17]
	s_mov_b32 m0, s48
	ds_read_b128 v[178:181], v161 offset:49152
	ds_read_b128 v[182:185], v161 offset:50176
	ds_read_b128 v[204:207], v161 offset:51200
	ds_read_b128 v[208:211], v161 offset:52224
	ds_read_b128 v[212:215], v161 offset:53248
	ds_read_b128 v[216:219], v161 offset:54272
	ds_read_b128 v[220:223], v161 offset:55296
	ds_read_b128 v[224:227], v161 offset:56320
	global_load_lds_dwordx4 v[228:229], off
	s_add_i32 m0, s48, 0x2000
	s_add_u32 s42, s42, 0x40080
	v_lshl_add_u64 v[228:229], v[230:231], 0, s[16:17]
	s_addc_u32 s43, s43, 0
	s_add_i32 s48, s55, s56
	global_load_lds_dwordx4 v[228:229], off
	v_lshl_add_u64 v[228:229], s[42:43], 0, v[134:135]
	s_mov_b32 m0, s48
	s_nop 0
	global_load_lds_dwordx4 v[228:229], off
	v_lshl_add_u64 v[228:229], s[42:43], 0, v[130:131]
	s_add_i32 m0, s48, 0x2000
	s_nop 0
	global_load_lds_dwordx4 v[228:229], off
	v_lshl_add_u64 v[228:229], v[240:241], 0, s[16:17]
	s_mov_b32 m0, s63
	s_nop 0
	global_load_lds_dwordx4 v[228:229], off
	v_lshl_add_u64 v[228:229], v[242:243], 0, s[16:17]
	s_mov_b32 m0, s64
	s_nop 0
	global_load_lds_dwordx4 v[228:229], off
	s_waitcnt vmcnt(8)
	s_waitcnt lgkmcnt(0)
	s_setprio 1
	s_barrier
	v_mfma_f32_16x16x32_bf16 v[62:65], v[142:145], v[178:181], v[62:65]
	v_mfma_f32_16x16x32_bf16 v[58:61], v[150:153], v[178:181], v[58:61]
	v_mfma_f32_16x16x32_bf16 v[46:49], v[142:145], v[204:207], v[46:49]
	v_mfma_f32_16x16x32_bf16 v[42:45], v[150:153], v[204:207], v[42:45]
	v_mfma_f32_16x16x32_bf16 v[30:33], v[142:145], v[212:215], v[30:33]
	v_mfma_f32_16x16x32_bf16 v[26:29], v[150:153], v[212:215], v[26:29]
	v_mfma_f32_16x16x32_bf16 v[14:17], v[142:145], v[220:223], v[14:17]
	v_mfma_f32_16x16x32_bf16 v[10:13], v[150:153], v[220:223], v[10:13]
	v_mfma_f32_16x16x32_bf16 v[54:57], v[162:165], v[178:181], v[54:57]
	v_mfma_f32_16x16x32_bf16 v[50:53], v[170:173], v[178:181], v[50:53]
	v_mfma_f32_16x16x32_bf16 v[38:41], v[162:165], v[204:207], v[38:41]
	v_mfma_f32_16x16x32_bf16 v[34:37], v[170:173], v[204:207], v[34:37]
	v_mfma_f32_16x16x32_bf16 v[22:25], v[162:165], v[212:215], v[22:25]
	v_mfma_f32_16x16x32_bf16 v[18:21], v[170:173], v[212:215], v[18:21]
	v_mfma_f32_16x16x32_bf16 v[6:9], v[162:165], v[220:223], v[6:9]
	v_mfma_f32_16x16x32_bf16 v[2:5], v[170:173], v[220:223], v[2:5]
	v_mfma_f32_16x16x32_bf16 v[62:65], v[146:149], v[182:185], v[62:65]
	v_mfma_f32_16x16x32_bf16 v[58:61], v[154:157], v[182:185], v[58:61]
	v_mfma_f32_16x16x32_bf16 v[46:49], v[146:149], v[208:211], v[46:49]
	v_mfma_f32_16x16x32_bf16 v[42:45], v[154:157], v[208:211], v[42:45]
	v_mfma_f32_16x16x32_bf16 v[30:33], v[146:149], v[216:219], v[30:33]
	v_mfma_f32_16x16x32_bf16 v[26:29], v[154:157], v[216:219], v[26:29]
	v_mfma_f32_16x16x32_bf16 v[14:17], v[146:149], v[224:227], v[14:17]
	v_mfma_f32_16x16x32_bf16 v[10:13], v[154:157], v[224:227], v[10:13]
	v_mfma_f32_16x16x32_bf16 v[54:57], v[166:169], v[182:185], v[54:57]
	v_mfma_f32_16x16x32_bf16 v[50:53], v[174:177], v[182:185], v[50:53]
	v_mfma_f32_16x16x32_bf16 v[38:41], v[166:169], v[208:211], v[38:41]
	v_mfma_f32_16x16x32_bf16 v[34:37], v[174:177], v[208:211], v[34:37]
	v_mfma_f32_16x16x32_bf16 v[22:25], v[166:169], v[216:219], v[22:25]
	v_mfma_f32_16x16x32_bf16 v[18:21], v[174:177], v[216:219], v[18:21]
	v_mfma_f32_16x16x32_bf16 v[6:9], v[166:169], v[224:227], v[6:9]
	v_mfma_f32_16x16x32_bf16 v[2:5], v[174:177], v[224:227], v[2:5]
	s_barrier
	s_setprio 0
	s_add_i32 s53, s53, 2
	s_add_u32 s40, s40, 0x100
	s_addc_u32 s41, s41, 0
	s_add_u32 s51, s51, 0x100
	s_addc_u32 s52, s52, 0
	s_cmp_gt_u32 s53, 13
.LBB0_1186:
	s_add_u32 s42, s40, 0xfffc0080
	s_addc_u32 s43, s41, -1
	s_add_i32 s54, 0, 0x10000
	s_cmp_eq_u32 s53, 12
	s_cselect_b32 s49, s7, s43
	s_cselect_b32 s48, s23, s42
	v_add_u32_e32 v0, s54, v160
	s_cselect_b32 s43, s21, s52
	s_cselect_b32 s42, s50, s51
	s_add_i32 s65, 0, 0x14000
	ds_read_b128 v[142:145], v0
	ds_read_b128 v[146:149], v0 offset:1024
	ds_read_b128 v[150:153], v0 offset:2048
	ds_read_b128 v[154:157], v0 offset:3072
	v_add_u32_e32 v0, s65, v160
	ds_read_b128 v[162:165], v0
	ds_read_b128 v[166:169], v0 offset:1024
	ds_read_b128 v[170:173], v0 offset:2048
	ds_read_b128 v[174:177], v0 offset:3072
	v_lshl_add_u64 v[228:229], s[40:41], 0, v[138:139]
	s_add_i32 m0, s57, 0xc000
	ds_read_b128 v[178:181], v161
	ds_read_b128 v[182:185], v161 offset:1024
	ds_read_b128 v[204:207], v161 offset:2048
	ds_read_b128 v[208:211], v161 offset:3072
	ds_read_b128 v[212:215], v161 offset:4096
	ds_read_b128 v[216:219], v161 offset:5120
	ds_read_b128 v[220:223], v161 offset:6144
	ds_read_b128 v[224:227], v161 offset:7168
	global_load_lds_dwordx4 v[228:229], off
	v_lshl_add_u64 v[228:229], s[40:41], 0, v[140:141]
	s_add_i32 m0, s57, 0xe000
	s_nop 0
	global_load_lds_dwordx4 v[228:229], off
	s_waitcnt vmcnt(8)
	s_waitcnt lgkmcnt(0)
	s_setprio 1
	s_barrier
	v_mfma_f32_16x16x32_bf16 v[126:129], v[142:145], v[178:181], v[126:129]
	v_mfma_f32_16x16x32_bf16 v[122:125], v[150:153], v[178:181], v[122:125]
	v_mfma_f32_16x16x32_bf16 v[110:113], v[142:145], v[204:207], v[110:113]
	v_mfma_f32_16x16x32_bf16 v[106:109], v[150:153], v[204:207], v[106:109]
	v_mfma_f32_16x16x32_bf16 v[94:97], v[142:145], v[212:215], v[94:97]
	v_mfma_f32_16x16x32_bf16 v[90:93], v[150:153], v[212:215], v[90:93]
	v_mfma_f32_16x16x32_bf16 v[78:81], v[142:145], v[220:223], v[78:81]
	v_mfma_f32_16x16x32_bf16 v[74:77], v[150:153], v[220:223], v[74:77]
	v_mfma_f32_16x16x32_bf16 v[118:121], v[162:165], v[178:181], v[118:121]
	v_mfma_f32_16x16x32_bf16 v[114:117], v[170:173], v[178:181], v[114:117]
	v_mfma_f32_16x16x32_bf16 v[102:105], v[162:165], v[204:207], v[102:105]
	v_mfma_f32_16x16x32_bf16 v[98:101], v[170:173], v[204:207], v[98:101]
	v_mfma_f32_16x16x32_bf16 v[86:89], v[162:165], v[212:215], v[86:89]
	v_mfma_f32_16x16x32_bf16 v[82:85], v[170:173], v[212:215], v[82:85]
	v_mfma_f32_16x16x32_bf16 v[70:73], v[162:165], v[220:223], v[70:73]
	v_mfma_f32_16x16x32_bf16 v[66:69], v[170:173], v[220:223], v[66:69]
	v_mfma_f32_16x16x32_bf16 v[126:129], v[146:149], v[182:185], v[126:129]
	v_mfma_f32_16x16x32_bf16 v[122:125], v[154:157], v[182:185], v[122:125]
	v_mfma_f32_16x16x32_bf16 v[110:113], v[146:149], v[208:211], v[110:113]
	v_mfma_f32_16x16x32_bf16 v[106:109], v[154:157], v[208:211], v[106:109]
	v_mfma_f32_16x16x32_bf16 v[94:97], v[146:149], v[216:219], v[94:97]
	v_mfma_f32_16x16x32_bf16 v[90:93], v[154:157], v[216:219], v[90:93]
	v_mfma_f32_16x16x32_bf16 v[78:81], v[146:149], v[224:227], v[78:81]
	v_mfma_f32_16x16x32_bf16 v[74:77], v[154:157], v[224:227], v[74:77]
	v_mfma_f32_16x16x32_bf16 v[118:121], v[166:169], v[182:185], v[118:121]
	v_mfma_f32_16x16x32_bf16 v[114:117], v[174:177], v[182:185], v[114:117]
	v_mfma_f32_16x16x32_bf16 v[102:105], v[166:169], v[208:211], v[102:105]
	v_mfma_f32_16x16x32_bf16 v[98:101], v[174:177], v[208:211], v[98:101]
	v_mfma_f32_16x16x32_bf16 v[86:89], v[166:169], v[216:219], v[86:89]
	v_mfma_f32_16x16x32_bf16 v[82:85], v[174:177], v[216:219], v[82:85]
	v_mfma_f32_16x16x32_bf16 v[70:73], v[166:169], v[224:227], v[70:73]
	v_mfma_f32_16x16x32_bf16 v[66:69], v[174:177], v[224:227], v[66:69]
	s_barrier
	s_setprio 0
	s_add_i32 s54, s54, s56
	v_lshl_add_u64 v[228:229], s[42:43], 0, v[134:135]
	s_mov_b32 m0, s54
	ds_read_b128 v[178:181], v161 offset:16384
	ds_read_b128 v[182:185], v161 offset:17408
	ds_read_b128 v[204:207], v161 offset:18432
	ds_read_b128 v[208:211], v161 offset:19456
	ds_read_b128 v[212:215], v161 offset:20480
	ds_read_b128 v[216:219], v161 offset:21504
	ds_read_b128 v[220:223], v161 offset:22528
	ds_read_b128 v[224:227], v161 offset:23552
	global_load_lds_dwordx4 v[228:229], off
	s_add_i32 m0, s54, 0x2000
	s_add_u32 s54, s42, 0x40000
	v_lshl_add_u64 v[230:231], s[42:43], 0, v[130:131]
	s_addc_u32 s55, s43, 0
	s_add_i32 s65, s65, s56
	global_load_lds_dwordx4 v[230:231], off
	v_lshl_add_u64 v[240:241], s[54:55], 0, v[134:135]
	s_mov_b32 m0, s65
	v_lshl_add_u64 v[242:243], s[48:49], 0, v[132:133]
	global_load_lds_dwordx4 v[240:241], off
	v_lshl_add_u64 v[240:241], s[54:55], 0, v[130:131]
	s_add_i32 m0, s65, 0x2000
	s_nop 0
	global_load_lds_dwordx4 v[240:241], off
	v_lshl_add_u64 v[240:241], s[48:49], 0, v[136:137]
	s_mov_b32 m0, s57
	s_nop 0
	global_load_lds_dwordx4 v[240:241], off
	s_mov_b32 m0, s58
	s_nop 0
	global_load_lds_dwordx4 v[242:243], off
	s_waitcnt vmcnt(8)
	s_waitcnt lgkmcnt(0)
	s_setprio 1
	s_barrier
	v_mfma_f32_16x16x32_bf16 v[62:65], v[142:145], v[178:181], v[62:65]
	v_mfma_f32_16x16x32_bf16 v[58:61], v[150:153], v[178:181], v[58:61]
	v_mfma_f32_16x16x32_bf16 v[46:49], v[142:145], v[204:207], v[46:49]
	v_mfma_f32_16x16x32_bf16 v[42:45], v[150:153], v[204:207], v[42:45]
	v_mfma_f32_16x16x32_bf16 v[30:33], v[142:145], v[212:215], v[30:33]
	v_mfma_f32_16x16x32_bf16 v[26:29], v[150:153], v[212:215], v[26:29]
	v_mfma_f32_16x16x32_bf16 v[14:17], v[142:145], v[220:223], v[14:17]
	v_mfma_f32_16x16x32_bf16 v[10:13], v[150:153], v[220:223], v[10:13]
	v_mfma_f32_16x16x32_bf16 v[54:57], v[162:165], v[178:181], v[54:57]
	v_mfma_f32_16x16x32_bf16 v[50:53], v[170:173], v[178:181], v[50:53]
	v_mfma_f32_16x16x32_bf16 v[38:41], v[162:165], v[204:207], v[38:41]
	v_mfma_f32_16x16x32_bf16 v[34:37], v[170:173], v[204:207], v[34:37]
	v_mfma_f32_16x16x32_bf16 v[22:25], v[162:165], v[212:215], v[22:25]
	v_mfma_f32_16x16x32_bf16 v[18:21], v[170:173], v[212:215], v[18:21]
	v_mfma_f32_16x16x32_bf16 v[6:9], v[162:165], v[220:223], v[6:9]
	v_mfma_f32_16x16x32_bf16 v[2:5], v[170:173], v[220:223], v[2:5]
	v_mfma_f32_16x16x32_bf16 v[62:65], v[146:149], v[182:185], v[62:65]
	v_mfma_f32_16x16x32_bf16 v[58:61], v[154:157], v[182:185], v[58:61]
	v_mfma_f32_16x16x32_bf16 v[46:49], v[146:149], v[208:211], v[46:49]
	v_mfma_f32_16x16x32_bf16 v[42:45], v[154:157], v[208:211], v[42:45]
	v_mfma_f32_16x16x32_bf16 v[30:33], v[146:149], v[216:219], v[30:33]
	v_mfma_f32_16x16x32_bf16 v[26:29], v[154:157], v[216:219], v[26:29]
	v_mfma_f32_16x16x32_bf16 v[14:17], v[146:149], v[224:227], v[14:17]
	v_mfma_f32_16x16x32_bf16 v[10:13], v[154:157], v[224:227], v[10:13]
	v_mfma_f32_16x16x32_bf16 v[54:57], v[166:169], v[182:185], v[54:57]
	v_mfma_f32_16x16x32_bf16 v[50:53], v[174:177], v[182:185], v[50:53]
	v_mfma_f32_16x16x32_bf16 v[38:41], v[166:169], v[208:211], v[38:41]
	v_mfma_f32_16x16x32_bf16 v[34:37], v[174:177], v[208:211], v[34:37]
	v_mfma_f32_16x16x32_bf16 v[22:25], v[166:169], v[216:219], v[22:25]
	v_mfma_f32_16x16x32_bf16 v[18:21], v[174:177], v[216:219], v[18:21]
	v_mfma_f32_16x16x32_bf16 v[6:9], v[166:169], v[224:227], v[6:9]
	v_mfma_f32_16x16x32_bf16 v[2:5], v[174:177], v[224:227], v[2:5]
	s_barrier
	s_setprio 0
	s_add_i32 s54, 0, 0x18000
	v_add_u32_e32 v0, s54, v160
	s_add_i32 s55, 0, 0x1c000
	ds_read_b128 v[142:145], v0
	ds_read_b128 v[146:149], v0 offset:1024
	ds_read_b128 v[150:153], v0 offset:2048
	ds_read_b128 v[154:157], v0 offset:3072
	v_add_u32_e32 v0, s55, v160
	ds_read_b128 v[162:165], v0
	ds_read_b128 v[166:169], v0 offset:1024
	ds_read_b128 v[170:173], v0 offset:2048
	ds_read_b128 v[174:177], v0 offset:3072
	s_add_u32 s48, s48, 0x40000
	s_addc_u32 s49, s49, 0
	s_mov_b32 m0, s59
	v_lshl_add_u64 v[244:245], s[48:49], 0, v[136:137]
	ds_read_b128 v[178:181], v161 offset:32768
	ds_read_b128 v[182:185], v161 offset:33792
	ds_read_b128 v[204:207], v161 offset:34816
	ds_read_b128 v[208:211], v161 offset:35840
	ds_read_b128 v[212:215], v161 offset:36864
	ds_read_b128 v[216:219], v161 offset:37888
	ds_read_b128 v[220:223], v161 offset:38912
	ds_read_b128 v[224:227], v161 offset:39936
	global_load_lds_dwordx4 v[244:245], off
	v_lshl_add_u64 v[244:245], s[48:49], 0, v[132:133]
	s_mov_b32 m0, s60
	s_nop 0
	global_load_lds_dwordx4 v[244:245], off
	s_waitcnt vmcnt(8)
	s_waitcnt lgkmcnt(0)
	s_setprio 1
	s_barrier
	v_mfma_f32_16x16x32_bf16 v[126:129], v[142:145], v[178:181], v[126:129]
	v_mfma_f32_16x16x32_bf16 v[122:125], v[150:153], v[178:181], v[122:125]
	v_mfma_f32_16x16x32_bf16 v[110:113], v[142:145], v[204:207], v[110:113]
	v_mfma_f32_16x16x32_bf16 v[106:109], v[150:153], v[204:207], v[106:109]
	v_mfma_f32_16x16x32_bf16 v[94:97], v[142:145], v[212:215], v[94:97]
	v_mfma_f32_16x16x32_bf16 v[90:93], v[150:153], v[212:215], v[90:93]
	v_mfma_f32_16x16x32_bf16 v[78:81], v[142:145], v[220:223], v[78:81]
	v_mfma_f32_16x16x32_bf16 v[74:77], v[150:153], v[220:223], v[74:77]
	v_mfma_f32_16x16x32_bf16 v[118:121], v[162:165], v[178:181], v[118:121]
	v_mfma_f32_16x16x32_bf16 v[114:117], v[170:173], v[178:181], v[114:117]
	v_mfma_f32_16x16x32_bf16 v[102:105], v[162:165], v[204:207], v[102:105]
	v_mfma_f32_16x16x32_bf16 v[98:101], v[170:173], v[204:207], v[98:101]
	v_mfma_f32_16x16x32_bf16 v[86:89], v[162:165], v[212:215], v[86:89]
	v_mfma_f32_16x16x32_bf16 v[82:85], v[170:173], v[212:215], v[82:85]
	v_mfma_f32_16x16x32_bf16 v[70:73], v[162:165], v[220:223], v[70:73]
	v_mfma_f32_16x16x32_bf16 v[66:69], v[170:173], v[220:223], v[66:69]
	v_mfma_f32_16x16x32_bf16 v[126:129], v[146:149], v[182:185], v[126:129]
	v_mfma_f32_16x16x32_bf16 v[122:125], v[154:157], v[182:185], v[122:125]
	v_mfma_f32_16x16x32_bf16 v[110:113], v[146:149], v[208:211], v[110:113]
	v_mfma_f32_16x16x32_bf16 v[106:109], v[154:157], v[208:211], v[106:109]
	v_mfma_f32_16x16x32_bf16 v[94:97], v[146:149], v[216:219], v[94:97]
	v_mfma_f32_16x16x32_bf16 v[90:93], v[154:157], v[216:219], v[90:93]
	v_mfma_f32_16x16x32_bf16 v[78:81], v[146:149], v[224:227], v[78:81]
	v_mfma_f32_16x16x32_bf16 v[74:77], v[154:157], v[224:227], v[74:77]
	v_mfma_f32_16x16x32_bf16 v[118:121], v[166:169], v[182:185], v[118:121]
	v_mfma_f32_16x16x32_bf16 v[114:117], v[174:177], v[182:185], v[114:117]
	v_mfma_f32_16x16x32_bf16 v[102:105], v[166:169], v[208:211], v[102:105]
	v_mfma_f32_16x16x32_bf16 v[98:101], v[174:177], v[208:211], v[98:101]
	v_mfma_f32_16x16x32_bf16 v[86:89], v[166:169], v[216:219], v[86:89]
	v_mfma_f32_16x16x32_bf16 v[82:85], v[174:177], v[216:219], v[82:85]
	v_mfma_f32_16x16x32_bf16 v[70:73], v[166:169], v[224:227], v[70:73]
	v_mfma_f32_16x16x32_bf16 v[66:69], v[174:177], v[224:227], v[66:69]
	s_barrier
	s_setprio 0
	s_add_i32 s48, s54, s56
	v_lshl_add_u64 v[228:229], v[228:229], 0, s[16:17]
	s_mov_b32 m0, s48
	ds_read_b128 v[178:181], v161 offset:49152
	ds_read_b128 v[182:185], v161 offset:50176
	ds_read_b128 v[204:207], v161 offset:51200
	ds_read_b128 v[208:211], v161 offset:52224
	ds_read_b128 v[212:215], v161 offset:53248
	ds_read_b128 v[216:219], v161 offset:54272
	ds_read_b128 v[220:223], v161 offset:55296
	ds_read_b128 v[224:227], v161 offset:56320
	global_load_lds_dwordx4 v[228:229], off
	s_add_i32 m0, s48, 0x2000
	s_add_u32 s42, s42, 0x40080
	v_lshl_add_u64 v[228:229], v[230:231], 0, s[16:17]
	s_addc_u32 s43, s43, 0
	s_add_i32 s48, s55, s56
	global_load_lds_dwordx4 v[228:229], off
	v_lshl_add_u64 v[228:229], s[42:43], 0, v[134:135]
	s_mov_b32 m0, s48
	s_nop 0
	global_load_lds_dwordx4 v[228:229], off
	v_lshl_add_u64 v[228:229], s[42:43], 0, v[130:131]
	s_add_i32 m0, s48, 0x2000
	s_nop 0
	global_load_lds_dwordx4 v[228:229], off
	v_lshl_add_u64 v[228:229], v[240:241], 0, s[16:17]
	s_mov_b32 m0, s63
	s_nop 0
	global_load_lds_dwordx4 v[228:229], off
	v_lshl_add_u64 v[228:229], v[242:243], 0, s[16:17]
	s_mov_b32 m0, s64
	s_nop 0
	global_load_lds_dwordx4 v[228:229], off
	s_waitcnt vmcnt(8)
	s_waitcnt lgkmcnt(0)
	s_setprio 1
	s_barrier
	v_mfma_f32_16x16x32_bf16 v[62:65], v[142:145], v[178:181], v[62:65]
	v_mfma_f32_16x16x32_bf16 v[58:61], v[150:153], v[178:181], v[58:61]
	v_mfma_f32_16x16x32_bf16 v[46:49], v[142:145], v[204:207], v[46:49]
	v_mfma_f32_16x16x32_bf16 v[42:45], v[150:153], v[204:207], v[42:45]
	v_mfma_f32_16x16x32_bf16 v[30:33], v[142:145], v[212:215], v[30:33]
	v_mfma_f32_16x16x32_bf16 v[26:29], v[150:153], v[212:215], v[26:29]
	v_mfma_f32_16x16x32_bf16 v[14:17], v[142:145], v[220:223], v[14:17]
	v_mfma_f32_16x16x32_bf16 v[10:13], v[150:153], v[220:223], v[10:13]
	v_mfma_f32_16x16x32_bf16 v[54:57], v[162:165], v[178:181], v[54:57]
	v_mfma_f32_16x16x32_bf16 v[50:53], v[170:173], v[178:181], v[50:53]
	v_mfma_f32_16x16x32_bf16 v[38:41], v[162:165], v[204:207], v[38:41]
	v_mfma_f32_16x16x32_bf16 v[34:37], v[170:173], v[204:207], v[34:37]
	v_mfma_f32_16x16x32_bf16 v[22:25], v[162:165], v[212:215], v[22:25]
	v_mfma_f32_16x16x32_bf16 v[18:21], v[170:173], v[212:215], v[18:21]
	v_mfma_f32_16x16x32_bf16 v[6:9], v[162:165], v[220:223], v[6:9]
	v_mfma_f32_16x16x32_bf16 v[2:5], v[170:173], v[220:223], v[2:5]
	v_mfma_f32_16x16x32_bf16 v[62:65], v[146:149], v[182:185], v[62:65]
	v_mfma_f32_16x16x32_bf16 v[58:61], v[154:157], v[182:185], v[58:61]
	v_mfma_f32_16x16x32_bf16 v[46:49], v[146:149], v[208:211], v[46:49]
	v_mfma_f32_16x16x32_bf16 v[42:45], v[154:157], v[208:211], v[42:45]
	v_mfma_f32_16x16x32_bf16 v[30:33], v[146:149], v[216:219], v[30:33]
	v_mfma_f32_16x16x32_bf16 v[26:29], v[154:157], v[216:219], v[26:29]
	v_mfma_f32_16x16x32_bf16 v[14:17], v[146:149], v[224:227], v[14:17]
	v_mfma_f32_16x16x32_bf16 v[10:13], v[154:157], v[224:227], v[10:13]
	v_mfma_f32_16x16x32_bf16 v[54:57], v[166:169], v[182:185], v[54:57]
	v_mfma_f32_16x16x32_bf16 v[50:53], v[174:177], v[182:185], v[50:53]
	v_mfma_f32_16x16x32_bf16 v[38:41], v[166:169], v[208:211], v[38:41]
	v_mfma_f32_16x16x32_bf16 v[34:37], v[174:177], v[208:211], v[34:37]
	v_mfma_f32_16x16x32_bf16 v[22:25], v[166:169], v[216:219], v[22:25]
	v_mfma_f32_16x16x32_bf16 v[18:21], v[174:177], v[216:219], v[18:21]
	v_mfma_f32_16x16x32_bf16 v[6:9], v[166:169], v[224:227], v[6:9]
	v_mfma_f32_16x16x32_bf16 v[2:5], v[174:177], v[224:227], v[2:5]
	s_barrier
	s_setprio 0
	s_add_i32 s53, s53, 2
	s_add_u32 s40, s40, 0x100
	s_addc_u32 s41, s41, 0
	s_add_u32 s51, s51, 0x100
	s_addc_u32 s52, s52, 0
	s_cmp_gt_u32 s53, 13
	s_cbranch_scc0 .LBB0_1186
	s_and_b64 vcc, exec, s[18:19]
	s_cbranch_vccz .LBB0_1189
	s_barrier
